# GEMM main loops: SP2 load segments also start with their A-fragment LDS reads
# baseline (speedup 1.0000x reference)
; #define PG8_STAGE(bufoff, gbase, voff) do { _Pragma("unroll") for (int _i = 0; _i < 2; ++_i) \
;         __builtin_amdgcn_global_load_lds((const unsigned*)((const char*)(gbase) + (voff)[_i]), (LAS unsigned*)(lds + (bufoff) + ldsw + _i * 8192), 16, 0, 0); } while (0)
; #define PG8_LDA(dst, b, h) do { _Pragma("unroll") for (int m = 0; m < 4; ++m) _Pragma("unroll") for (int k = 0; k < 2; ++k) dst[m][k] = *(const LAS bf16x8*)(lds + PG8_SA(b, h) + aoff + m * 2048 + k * 1024); } while (0)
; #define PG8_LDB(dst, b, h) do { _Pragma("unroll") for (int n = 0; n < 2; ++n) _Pragma("unroll") for (int k = 0; k < 2; ++k) dst[n][k] = *(const LAS bf16x8*)(lds + PG8_SB(b, h) + boff + n * 2048 + k * 1024); } while (0)
; #define PG8_MMA(ai, bj, At, Bt) do { __builtin_amdgcn_s_setprio(1); _Pragma("unroll") for (int m = 0; m < 4; ++m) _Pragma("unroll") for (int n = 0; n < 2; ++n) _Pragma("unroll") for (int k = 0; k < 2; ++k) \
;         acc[ai][bj][m][n] = __builtin_amdgcn_mfma_f32_16x16x32_bf16(Bt[n][k], At[m][k], acc[ai][bj][m][n], 0, 0, 0); __builtin_amdgcn_s_setprio(0); } while (0)
; #define PG8_WAIT_V(n) asm volatile("s_waitcnt vmcnt(" #n ")" ::: "memory")
; #define PG8_WAIT_L(n) asm volatile("s_waitcnt lgkmcnt(" #n ")" ::: "memory")
; #define PG8_BAR __builtin_amdgcn_s_barrier()
; #define PG8_SCHED __builtin_amdgcn_sched_barrier(0)
; template <class Epi, class Sched, int LDA, int LDB, bool ALIGN_EPI = true>
; __device__ __forceinline__ void gemm_phase(LAS unsigned char* lds, const Gemm g, const Sched& S, const Epi& E, int wave) {
;     ...
;             const bool last = (t == nt - 2);
;             const char* a1 = cA + (size_t)(t + 1) * kstep;
;             const char* a2 = last ? nA : cA + (size_t)(t + 2) * kstep; const char* b2 = last ? nB : cB + (size_t)(t + 2) * kstep;
;             const char* a3 = a2 + kstep; const char* b3 = b2 + kstep;
;             PG8_LDB(B0, 0, 0); PG8_LDB(B1, 0, 1); PG8_SCHED; PG8_LDA(At, 0, 0); PG8_STAGE(PG8_SA(1, 1), a1 + hstepA, voffA);
;             PG8_WAIT_V(8); PG8_WAIT_L(0); PG8_BAR; PG8_MMA(0, 0, At, B0); PG8_MMA(0, 1, At, B1); PG8_BAR; PG8_SCHED;
;             PG8_LDA(At, 0, 1); PG8_STAGE(PG8_SB(0, 0), b2, voffB); PG8_STAGE(PG8_SB(0, 1), b2 + hstepB, voffB); PG8_STAGE(PG8_SA(0, 0), a2, voffA);
.LBB0_485:
	ds_read_b128 v[184:187], v145
	ds_read_b128 v[188:191], v145 offset:1024
	ds_read_b128 v[192:195], v145 offset:2048
	ds_read_b128 v[196:199], v145 offset:3072
	ds_read_b128 v[200:203], v145 offset:4096
	ds_read_b128 v[204:207], v145 offset:5120
	ds_read_b128 v[208:211], v145 offset:6144
	ds_read_b128 v[212:215], v145 offset:7168
	s_add_u32 s24, s18, 0x100
	s_addc_u32 s25, s19, 0
	s_add_i32 s54, 0, 0x10000
	s_cmp_eq_u32 s53, 28
	s_cselect_b32 s35, s3, s25
	s_cselect_b32 s34, s2, s24
	v_add_u32_e32 v140, s54, v143
	s_cselect_b32 s29, s1, s45
	s_cselect_b32 s28, s17, s44
	s_add_i32 s55, 0, 0x14000
	ds_read_b128 v[146:149], v140
	ds_read_b128 v[150:153], v140 offset:1024
	ds_read_b128 v[154:157], v140 offset:2048
	ds_read_b128 v[158:161], v140 offset:3072
	v_add_u32_e32 v140, s55, v143
	ds_read_b128 v[162:165], v140
	ds_read_b128 v[166:169], v140 offset:1024
	ds_read_b128 v[170:173], v140 offset:2048
	ds_read_b128 v[180:183], v140 offset:3072
	v_lshl_add_u64 v[140:141], s[18:19], 0, v[136:137]
	s_add_i32 m0, s38, 0xc000
	s_nop 0
	global_load_lds_dwordx4 v[140:141], off
	v_lshl_add_u64 v[140:141], s[18:19], 0, v[138:139]
	s_add_i32 m0, s38, 0xe000
	s_nop 0
	global_load_lds_dwordx4 v[140:141], off
	s_waitcnt vmcnt(8)
	s_waitcnt lgkmcnt(0)
	s_setprio 1
	s_barrier
	v_mfma_f32_16x16x32_bf16 v[126:129], v[146:149], v[184:187], v[126:129]
	v_mfma_f32_16x16x32_bf16 v[118:121], v[154:157], v[184:187], v[118:121]
	v_mfma_f32_16x16x32_bf16 v[110:113], v[146:149], v[192:195], v[110:113]
	v_mfma_f32_16x16x32_bf16 v[102:105], v[154:157], v[192:195], v[102:105]
	v_mfma_f32_16x16x32_bf16 v[94:97], v[146:149], v[200:203], v[94:97]
	v_mfma_f32_16x16x32_bf16 v[86:89], v[154:157], v[200:203], v[86:89]
	v_mfma_f32_16x16x32_bf16 v[78:81], v[146:149], v[208:211], v[78:81]
	v_mfma_f32_16x16x32_bf16 v[70:73], v[154:157], v[208:211], v[70:73]
	v_mfma_f32_16x16x32_bf16 v[126:129], v[150:153], v[188:191], v[126:129]
	v_mfma_f32_16x16x32_bf16 v[118:121], v[158:161], v[188:191], v[118:121]
	v_mfma_f32_16x16x32_bf16 v[110:113], v[150:153], v[196:199], v[110:113]
	v_mfma_f32_16x16x32_bf16 v[102:105], v[158:161], v[196:199], v[102:105]
	v_mfma_f32_16x16x32_bf16 v[94:97], v[150:153], v[204:207], v[94:97]
	v_mfma_f32_16x16x32_bf16 v[86:89], v[158:161], v[204:207], v[86:89]
	v_mfma_f32_16x16x32_bf16 v[78:81], v[150:153], v[212:215], v[78:81]
	v_mfma_f32_16x16x32_bf16 v[70:73], v[158:161], v[212:215], v[70:73]
	v_mfma_f32_16x16x32_bf16 v[122:125], v[162:165], v[184:187], v[122:125]
	v_mfma_f32_16x16x32_bf16 v[114:117], v[170:173], v[184:187], v[114:117]
	v_mfma_f32_16x16x32_bf16 v[106:109], v[162:165], v[192:195], v[106:109]
	v_mfma_f32_16x16x32_bf16 v[98:101], v[170:173], v[192:195], v[98:101]
	v_mfma_f32_16x16x32_bf16 v[90:93], v[162:165], v[200:203], v[90:93]
	v_mfma_f32_16x16x32_bf16 v[82:85], v[170:173], v[200:203], v[82:85]
	v_mfma_f32_16x16x32_bf16 v[74:77], v[162:165], v[208:211], v[74:77]
	v_mfma_f32_16x16x32_bf16 v[66:69], v[170:173], v[208:211], v[66:69]
	v_mfma_f32_16x16x32_bf16 v[122:125], v[166:169], v[188:191], v[122:125]
	v_mfma_f32_16x16x32_bf16 v[114:117], v[180:183], v[188:191], v[114:117]
	v_mfma_f32_16x16x32_bf16 v[106:109], v[166:169], v[196:199], v[106:109]
	v_mfma_f32_16x16x32_bf16 v[98:101], v[180:183], v[196:199], v[98:101]
	v_mfma_f32_16x16x32_bf16 v[90:93], v[166:169], v[204:207], v[90:93]
	v_mfma_f32_16x16x32_bf16 v[82:85], v[180:183], v[204:207], v[82:85]
	v_mfma_f32_16x16x32_bf16 v[74:77], v[166:169], v[212:215], v[74:77]
	v_mfma_f32_16x16x32_bf16 v[66:69], v[180:183], v[212:215], v[66:69]
	s_barrier
	s_setprio 0
	ds_read_b128 v[184:187], v145 offset:16384
	ds_read_b128 v[188:191], v145 offset:17408
	ds_read_b128 v[192:195], v145 offset:18432
	ds_read_b128 v[196:199], v145 offset:19456
	ds_read_b128 v[200:203], v145 offset:20480
	ds_read_b128 v[204:207], v145 offset:21504
	ds_read_b128 v[208:211], v145 offset:22528
	ds_read_b128 v[212:215], v145 offset:23552
	s_add_i32 s18, s54, s5
	v_lshl_add_u64 v[140:141], s[28:29], 0, v[0:1]
	s_mov_b32 m0, s18
	s_nop 0
	global_load_lds_dwordx4 v[140:141], off
	s_add_i32 m0, s18, 0x2000
	s_add_u32 s18, s28, 0x80000
	v_lshl_add_u64 v[174:175], s[28:29], 0, v[130:131]
	s_addc_u32 s19, s29, 0
	s_add_i32 s54, s55, s5
	global_load_lds_dwordx4 v[174:175], off
	v_lshl_add_u64 v[216:217], s[18:19], 0, v[0:1]
	s_mov_b32 m0, s54
	v_lshl_add_u64 v[218:219], s[34:35], 0, v[132:133]
	global_load_lds_dwordx4 v[216:217], off
	v_lshl_add_u64 v[216:217], s[18:19], 0, v[130:131]
	s_add_i32 m0, s54, 0x2000
	s_nop 0
	global_load_lds_dwordx4 v[216:217], off
	v_lshl_add_u64 v[216:217], s[34:35], 0, v[134:135]
	s_mov_b32 m0, s38
	s_nop 0
	global_load_lds_dwordx4 v[216:217], off
	s_mov_b32 m0, s39
	s_nop 0
	global_load_lds_dwordx4 v[218:219], off
	s_waitcnt vmcnt(8)
	s_waitcnt lgkmcnt(0)
	s_setprio 1
	s_barrier
; #define PG8_STAGE(bufoff, gbase, voff) do { _Pragma("unroll") for (int _i = 0; _i < 2; ++_i) \
;         __builtin_amdgcn_global_load_lds((const unsigned*)((const char*)(gbase) + (voff)[_i]), (LAS unsigned*)(lds + (bufoff) + ldsw + _i * 8192), 16, 0, 0); } while (0)
; #define PG8_LDA(dst, b, h) do { _Pragma("unroll") for (int m = 0; m < 4; ++m) _Pragma("unroll") for (int k = 0; k < 2; ++k) dst[m][k] = *(const LAS bf16x8*)(lds + PG8_SA(b, h) + aoff + m * 2048 + k * 1024); } while (0)
; #define PG8_LDB(dst, b, h) do { _Pragma("unroll") for (int n = 0; n < 2; ++n) _Pragma("unroll") for (int k = 0; k < 2; ++k) dst[n][k] = *(const LAS bf16x8*)(lds + PG8_SB(b, h) + boff + n * 2048 + k * 1024); } while (0)
; #define PG8_MMA(ai, bj, At, Bt) do { __builtin_amdgcn_s_setprio(1); _Pragma("unroll") for (int m = 0; m < 4; ++m) _Pragma("unroll") for (int n = 0; n < 2; ++n) _Pragma("unroll") for (int k = 0; k < 2; ++k) \
;         acc[ai][bj][m][n] = __builtin_amdgcn_mfma_f32_16x16x32_bf16(Bt[n][k], At[m][k], acc[ai][bj][m][n], 0, 0, 0); __builtin_amdgcn_s_setprio(0); } while (0)
; #define PG8_WAIT_V(n) asm volatile("s_waitcnt vmcnt(" #n ")" ::: "memory")
; #define PG8_WAIT_L(n) asm volatile("s_waitcnt lgkmcnt(" #n ")" ::: "memory")
; #define PG8_BAR __builtin_amdgcn_s_barrier()
; #define PG8_SCHED __builtin_amdgcn_sched_barrier(0)
; template <class Epi, class Sched, int LDA, int LDB, bool ALIGN_EPI = true>
; __device__ __forceinline__ void gemm_phase(LAS unsigned char* lds, const Gemm g, const Sched& S, const Epi& E, int wave) {
;     ...
;             PG8_WAIT_V(8); PG8_WAIT_L(0); PG8_BAR; PG8_MMA(1, 0, At, B0); PG8_MMA(1, 1, At, B1); PG8_BAR; PG8_SCHED;
;             PG8_LDB(B0, 1, 0); PG8_LDB(B1, 1, 1); PG8_SCHED; PG8_LDA(At, 1, 0); PG8_STAGE(PG8_SA(0, 1), a2 + hstepA, voffA);
;             PG8_WAIT_V(8); PG8_WAIT_L(0); PG8_BAR; PG8_MMA(0, 0, At, B0); PG8_MMA(0, 1, At, B1); PG8_BAR; PG8_SCHED;
	v_mfma_f32_16x16x32_bf16 v[62:65], v[146:149], v[184:187], v[62:65]
	v_mfma_f32_16x16x32_bf16 v[54:57], v[154:157], v[184:187], v[54:57]
	v_mfma_f32_16x16x32_bf16 v[46:49], v[146:149], v[192:195], v[46:49]
	v_mfma_f32_16x16x32_bf16 v[38:41], v[154:157], v[192:195], v[38:41]
	v_mfma_f32_16x16x32_bf16 v[30:33], v[146:149], v[200:203], v[30:33]
	v_mfma_f32_16x16x32_bf16 v[22:25], v[154:157], v[200:203], v[22:25]
	v_mfma_f32_16x16x32_bf16 v[14:17], v[146:149], v[208:211], v[14:17]
	v_mfma_f32_16x16x32_bf16 v[6:9], v[154:157], v[208:211], v[6:9]
	v_mfma_f32_16x16x32_bf16 v[62:65], v[150:153], v[188:191], v[62:65]
	v_mfma_f32_16x16x32_bf16 v[54:57], v[158:161], v[188:191], v[54:57]
	v_mfma_f32_16x16x32_bf16 v[46:49], v[150:153], v[196:199], v[46:49]
	v_mfma_f32_16x16x32_bf16 v[38:41], v[158:161], v[196:199], v[38:41]
	v_mfma_f32_16x16x32_bf16 v[30:33], v[150:153], v[204:207], v[30:33]
	v_mfma_f32_16x16x32_bf16 v[22:25], v[158:161], v[204:207], v[22:25]
	v_mfma_f32_16x16x32_bf16 v[14:17], v[150:153], v[212:215], v[14:17]
	v_mfma_f32_16x16x32_bf16 v[6:9], v[158:161], v[212:215], v[6:9]
	v_mfma_f32_16x16x32_bf16 v[58:61], v[162:165], v[184:187], v[58:61]
	v_mfma_f32_16x16x32_bf16 v[50:53], v[170:173], v[184:187], v[50:53]
	v_mfma_f32_16x16x32_bf16 v[42:45], v[162:165], v[192:195], v[42:45]
	v_mfma_f32_16x16x32_bf16 v[34:37], v[170:173], v[192:195], v[34:37]
	v_mfma_f32_16x16x32_bf16 v[26:29], v[162:165], v[200:203], v[26:29]
	v_mfma_f32_16x16x32_bf16 v[18:21], v[170:173], v[200:203], v[18:21]
	v_mfma_f32_16x16x32_bf16 v[10:13], v[162:165], v[208:211], v[10:13]
	v_mfma_f32_16x16x32_bf16 v[2:5], v[170:173], v[208:211], v[2:5]
	v_mfma_f32_16x16x32_bf16 v[58:61], v[166:169], v[188:191], v[58:61]
	v_mfma_f32_16x16x32_bf16 v[50:53], v[180:183], v[188:191], v[50:53]
	v_mfma_f32_16x16x32_bf16 v[42:45], v[166:169], v[196:199], v[42:45]
	v_mfma_f32_16x16x32_bf16 v[34:37], v[180:183], v[196:199], v[34:37]
	v_mfma_f32_16x16x32_bf16 v[26:29], v[166:169], v[204:207], v[26:29]
	v_mfma_f32_16x16x32_bf16 v[18:21], v[180:183], v[204:207], v[18:21]
	v_mfma_f32_16x16x32_bf16 v[10:13], v[166:169], v[212:215], v[10:13]
	v_mfma_f32_16x16x32_bf16 v[2:5], v[180:183], v[212:215], v[2:5]
	s_barrier
	s_setprio 0
	ds_read_b128 v[184:187], v145 offset:32768
	ds_read_b128 v[188:191], v145 offset:33792
	ds_read_b128 v[192:195], v145 offset:34816
	ds_read_b128 v[196:199], v145 offset:35840
	ds_read_b128 v[200:203], v145 offset:36864
	ds_read_b128 v[204:207], v145 offset:37888
	ds_read_b128 v[208:211], v145 offset:38912
	ds_read_b128 v[212:215], v145 offset:39936
	s_add_i32 s54, 0, 0x18000
	s_add_i32 s55, 0, 0x1c000
	v_add_u32_e32 v158, s54, v143
	v_add_u32_e32 v180, s55, v143
	ds_read_b128 v[146:149], v158
	ds_read_b128 v[150:153], v158 offset:1024
	ds_read_b128 v[154:157], v158 offset:2048
	ds_read_b128 v[158:161], v158 offset:3072
	ds_read_b128 v[162:165], v180
	ds_read_b128 v[166:169], v180 offset:1024
	ds_read_b128 v[170:173], v180 offset:2048
	ds_read_b128 v[180:183], v180 offset:3072
	s_add_u32 s18, s34, 0x84000
	s_addc_u32 s19, s35, 0
	s_mov_b32 m0, s46
	v_lshl_add_u64 v[220:221], s[18:19], 0, v[134:135]
	global_load_lds_dwordx4 v[220:221], off
	v_lshl_add_u64 v[220:221], s[18:19], 0, v[132:133]
	s_mov_b32 m0, s47
	s_nop 0
	global_load_lds_dwordx4 v[220:221], off
	s_waitcnt vmcnt(8)
	s_waitcnt lgkmcnt(0)
	s_setprio 1
	s_barrier
	v_mfma_f32_16x16x32_bf16 v[126:129], v[146:149], v[184:187], v[126:129]
	v_mfma_f32_16x16x32_bf16 v[118:121], v[154:157], v[184:187], v[118:121]
	v_mfma_f32_16x16x32_bf16 v[110:113], v[146:149], v[192:195], v[110:113]
	v_mfma_f32_16x16x32_bf16 v[102:105], v[154:157], v[192:195], v[102:105]
	v_mfma_f32_16x16x32_bf16 v[94:97], v[146:149], v[200:203], v[94:97]
	v_mfma_f32_16x16x32_bf16 v[86:89], v[154:157], v[200:203], v[86:89]
	v_mfma_f32_16x16x32_bf16 v[78:81], v[146:149], v[208:211], v[78:81]
	v_mfma_f32_16x16x32_bf16 v[70:73], v[154:157], v[208:211], v[70:73]
	v_mfma_f32_16x16x32_bf16 v[126:129], v[150:153], v[188:191], v[126:129]
	v_mfma_f32_16x16x32_bf16 v[118:121], v[158:161], v[188:191], v[118:121]
	v_mfma_f32_16x16x32_bf16 v[110:113], v[150:153], v[196:199], v[110:113]
	v_mfma_f32_16x16x32_bf16 v[102:105], v[158:161], v[196:199], v[102:105]
	v_mfma_f32_16x16x32_bf16 v[94:97], v[150:153], v[204:207], v[94:97]
	v_mfma_f32_16x16x32_bf16 v[86:89], v[158:161], v[204:207], v[86:89]
	v_mfma_f32_16x16x32_bf16 v[78:81], v[150:153], v[212:215], v[78:81]
	v_mfma_f32_16x16x32_bf16 v[70:73], v[158:161], v[212:215], v[70:73]
	v_mfma_f32_16x16x32_bf16 v[122:125], v[162:165], v[184:187], v[122:125]
	v_mfma_f32_16x16x32_bf16 v[114:117], v[170:173], v[184:187], v[114:117]
	v_mfma_f32_16x16x32_bf16 v[106:109], v[162:165], v[192:195], v[106:109]
	v_mfma_f32_16x16x32_bf16 v[98:101], v[170:173], v[192:195], v[98:101]
	v_mfma_f32_16x16x32_bf16 v[90:93], v[162:165], v[200:203], v[90:93]
	v_mfma_f32_16x16x32_bf16 v[82:85], v[170:173], v[200:203], v[82:85]
	v_mfma_f32_16x16x32_bf16 v[74:77], v[162:165], v[208:211], v[74:77]
	v_mfma_f32_16x16x32_bf16 v[66:69], v[170:173], v[208:211], v[66:69]
	v_mfma_f32_16x16x32_bf16 v[122:125], v[166:169], v[188:191], v[122:125]
	v_mfma_f32_16x16x32_bf16 v[114:117], v[180:183], v[188:191], v[114:117]
	v_mfma_f32_16x16x32_bf16 v[106:109], v[166:169], v[196:199], v[106:109]
	v_mfma_f32_16x16x32_bf16 v[98:101], v[180:183], v[196:199], v[98:101]
	v_mfma_f32_16x16x32_bf16 v[90:93], v[166:169], v[204:207], v[90:93]
	v_mfma_f32_16x16x32_bf16 v[82:85], v[180:183], v[204:207], v[82:85]
	v_mfma_f32_16x16x32_bf16 v[74:77], v[166:169], v[212:215], v[74:77]
	v_mfma_f32_16x16x32_bf16 v[66:69], v[180:183], v[212:215], v[66:69]
	s_barrier
; #define PG8_STAGE(bufoff, gbase, voff) do { _Pragma("unroll") for (int _i = 0; _i < 2; ++_i) \
;         __builtin_amdgcn_global_load_lds((const unsigned*)((const char*)(gbase) + (voff)[_i]), (LAS unsigned*)(lds + (bufoff) + ldsw + _i * 8192), 16, 0, 0); } while (0)
; #define PG8_LDA(dst, b, h) do { _Pragma("unroll") for (int m = 0; m < 4; ++m) _Pragma("unroll") for (int k = 0; k < 2; ++k) dst[m][k] = *(const LAS bf16x8*)(lds + PG8_SA(b, h) + aoff + m * 2048 + k * 1024); } while (0)
; #define PG8_MMA(ai, bj, At, Bt) do { __builtin_amdgcn_s_setprio(1); _Pragma("unroll") for (int m = 0; m < 4; ++m) _Pragma("unroll") for (int n = 0; n < 2; ++n) _Pragma("unroll") for (int k = 0; k < 2; ++k) \
;         acc[ai][bj][m][n] = __builtin_amdgcn_mfma_f32_16x16x32_bf16(Bt[n][k], At[m][k], acc[ai][bj][m][n], 0, 0, 0); __builtin_amdgcn_s_setprio(0); } while (0)
; #define PG8_WAIT_V(n) asm volatile("s_waitcnt vmcnt(" #n ")" ::: "memory")
; #define PG8_WAIT_L(n) asm volatile("s_waitcnt lgkmcnt(" #n ")" ::: "memory")
; #define PG8_BAR __builtin_amdgcn_s_barrier()
; #define PG8_SCHED __builtin_amdgcn_sched_barrier(0)
; template <class Epi, class Sched, int LDA, int LDB, bool ALIGN_EPI = true>
; __device__ __forceinline__ void gemm_phase(LAS unsigned char* lds, const Gemm g, const Sched& S, const Epi& E, int wave) {
;     ...
;             PG8_LDA(At, 1, 1); PG8_STAGE(PG8_SB(1, 0), b3, voffB); PG8_STAGE(PG8_SB(1, 1), b3 + hstepB, voffB); PG8_STAGE(PG8_SA(1, 0), a3, voffA);
;             PG8_WAIT_V(8); PG8_WAIT_L(0); PG8_BAR; PG8_MMA(1, 0, At, B0); PG8_MMA(1, 1, At, B1); PG8_BAR; PG8_SCHED;
;         }
;         if constexpr (ALIGN_EPI) { if (wr == 0) PG8_BAR; }
	s_setprio 0
	ds_read_b128 v[184:187], v145 offset:49152
	ds_read_b128 v[188:191], v145 offset:50176
	ds_read_b128 v[192:195], v145 offset:51200
	ds_read_b128 v[196:199], v145 offset:52224
	ds_read_b128 v[200:203], v145 offset:53248
	ds_read_b128 v[204:207], v145 offset:54272
	ds_read_b128 v[208:211], v145 offset:55296
	ds_read_b128 v[212:215], v145 offset:56320
	s_add_i32 s18, s54, s5
	v_lshl_add_u64 v[140:141], v[140:141], 0, s[6:7]
	s_mov_b32 m0, s18
	s_nop 0
	global_load_lds_dwordx4 v[140:141], off
	s_add_i32 m0, s18, 0x2000
	s_add_u32 s18, s28, 0x80080
	v_lshl_add_u64 v[140:141], v[174:175], 0, s[6:7]
	s_addc_u32 s19, s29, 0
	s_add_i32 s28, s55, s5
	global_load_lds_dwordx4 v[140:141], off
	v_lshl_add_u64 v[140:141], s[18:19], 0, v[0:1]
	s_mov_b32 m0, s28
	s_nop 0
	global_load_lds_dwordx4 v[140:141], off
	v_lshl_add_u64 v[140:141], s[18:19], 0, v[130:131]
	s_add_i32 m0, s28, 0x2000
	s_nop 0
	global_load_lds_dwordx4 v[140:141], off
	v_lshl_add_u64 v[140:141], v[216:217], 0, s[6:7]
	s_mov_b32 m0, s48
	s_nop 0
	global_load_lds_dwordx4 v[140:141], off
	v_lshl_add_u64 v[140:141], v[218:219], 0, s[6:7]
	s_mov_b32 m0, s49
	s_nop 0
	global_load_lds_dwordx4 v[140:141], off
	s_waitcnt vmcnt(8)
	s_waitcnt lgkmcnt(0)
	s_setprio 1
	s_barrier
	v_mfma_f32_16x16x32_bf16 v[62:65], v[146:149], v[184:187], v[62:65]
	v_mfma_f32_16x16x32_bf16 v[54:57], v[154:157], v[184:187], v[54:57]
	v_mfma_f32_16x16x32_bf16 v[46:49], v[146:149], v[192:195], v[46:49]
	v_mfma_f32_16x16x32_bf16 v[38:41], v[154:157], v[192:195], v[38:41]
	v_mfma_f32_16x16x32_bf16 v[30:33], v[146:149], v[200:203], v[30:33]
	v_mfma_f32_16x16x32_bf16 v[22:25], v[154:157], v[200:203], v[22:25]
	v_mfma_f32_16x16x32_bf16 v[14:17], v[146:149], v[208:211], v[14:17]
	v_mfma_f32_16x16x32_bf16 v[6:9], v[154:157], v[208:211], v[6:9]
	v_mfma_f32_16x16x32_bf16 v[62:65], v[150:153], v[188:191], v[62:65]
	v_mfma_f32_16x16x32_bf16 v[54:57], v[158:161], v[188:191], v[54:57]
	v_mfma_f32_16x16x32_bf16 v[46:49], v[150:153], v[196:199], v[46:49]
	v_mfma_f32_16x16x32_bf16 v[38:41], v[158:161], v[196:199], v[38:41]
	v_mfma_f32_16x16x32_bf16 v[30:33], v[150:153], v[204:207], v[30:33]
	v_mfma_f32_16x16x32_bf16 v[22:25], v[158:161], v[204:207], v[22:25]
	v_mfma_f32_16x16x32_bf16 v[14:17], v[150:153], v[212:215], v[14:17]
	v_mfma_f32_16x16x32_bf16 v[6:9], v[158:161], v[212:215], v[6:9]
	v_mfma_f32_16x16x32_bf16 v[58:61], v[162:165], v[184:187], v[58:61]
	v_mfma_f32_16x16x32_bf16 v[50:53], v[170:173], v[184:187], v[50:53]
	v_mfma_f32_16x16x32_bf16 v[42:45], v[162:165], v[192:195], v[42:45]
	v_mfma_f32_16x16x32_bf16 v[34:37], v[170:173], v[192:195], v[34:37]
	v_mfma_f32_16x16x32_bf16 v[26:29], v[162:165], v[200:203], v[26:29]
	v_mfma_f32_16x16x32_bf16 v[18:21], v[170:173], v[200:203], v[18:21]
	v_mfma_f32_16x16x32_bf16 v[10:13], v[162:165], v[208:211], v[10:13]
	v_mfma_f32_16x16x32_bf16 v[2:5], v[170:173], v[208:211], v[2:5]
	v_mfma_f32_16x16x32_bf16 v[58:61], v[166:169], v[188:191], v[58:61]
	v_mfma_f32_16x16x32_bf16 v[50:53], v[180:183], v[188:191], v[50:53]
	v_mfma_f32_16x16x32_bf16 v[42:45], v[166:169], v[196:199], v[42:45]
	v_mfma_f32_16x16x32_bf16 v[34:37], v[180:183], v[196:199], v[34:37]
	v_mfma_f32_16x16x32_bf16 v[26:29], v[166:169], v[204:207], v[26:29]
	v_mfma_f32_16x16x32_bf16 v[18:21], v[180:183], v[204:207], v[18:21]
	v_mfma_f32_16x16x32_bf16 v[10:13], v[166:169], v[212:215], v[10:13]
	v_mfma_f32_16x16x32_bf16 v[2:5], v[180:183], v[212:215], v[2:5]
	s_barrier
	s_setprio 0
	s_add_i32 s53, s53, 2
	s_add_u32 s44, s44, 0x100
	s_addc_u32 s45, s45, 0
	s_cmp_gt_u32 s53, 29
	s_mov_b64 s[18:19], s[24:25]
	s_cbranch_scc0 .LBB0_485
	v_readlane_b32 s6, v252, 14
	v_readlane_b32 s7, v252, 15
	s_and_b64 vcc, exec, s[6:7]
	s_cbranch_vccz .LBB0_488
	s_barrier

; #define PG8_STAGE(bufoff, gbase, voff) do { _Pragma("unroll") for (int _i = 0; _i < 2; ++_i) \
;         __builtin_amdgcn_global_load_lds((const unsigned*)((const char*)(gbase) + (voff)[_i]), (LAS unsigned*)(lds + (bufoff) + ldsw + _i * 8192), 16, 0, 0); } while (0)
; #define PG8_LDA(dst, b, h) do { _Pragma("unroll") for (int m = 0; m < 4; ++m) _Pragma("unroll") for (int k = 0; k < 2; ++k) dst[m][k] = *(const LAS bf16x8*)(lds + PG8_SA(b, h) + aoff + m * 2048 + k * 1024); } while (0)
; #define PG8_LDB(dst, b, h) do { _Pragma("unroll") for (int n = 0; n < 2; ++n) _Pragma("unroll") for (int k = 0; k < 2; ++k) dst[n][k] = *(const LAS bf16x8*)(lds + PG8_SB(b, h) + boff + n * 2048 + k * 1024); } while (0)
; #define PG8_MMA(ai, bj, At, Bt) do { __builtin_amdgcn_s_setprio(1); _Pragma("unroll") for (int m = 0; m < 4; ++m) _Pragma("unroll") for (int n = 0; n < 2; ++n) _Pragma("unroll") for (int k = 0; k < 2; ++k) \
;         acc[ai][bj][m][n] = __builtin_amdgcn_mfma_f32_16x16x32_bf16(Bt[n][k], At[m][k], acc[ai][bj][m][n], 0, 0, 0); __builtin_amdgcn_s_setprio(0); } while (0)
; #define PG8_WAIT_V(n) asm volatile("s_waitcnt vmcnt(" #n ")" ::: "memory")
; #define PG8_WAIT_L(n) asm volatile("s_waitcnt lgkmcnt(" #n ")" ::: "memory")
; #define PG8_BAR __builtin_amdgcn_s_barrier()
; #define PG8_SCHED __builtin_amdgcn_sched_barrier(0)
; template <class Epi, class Sched, int LDA, int LDB, bool ALIGN_EPI = true>
; __device__ __forceinline__ void gemm_phase(LAS unsigned char* lds, const Gemm g, const Sched& S, const Epi& E, int wave) {
;     ...
;             const bool last = (t == nt - 2);
;             const char* a1 = cA + (size_t)(t + 1) * kstep;
;             const char* a2 = last ? nA : cA + (size_t)(t + 2) * kstep; const char* b2 = last ? nB : cB + (size_t)(t + 2) * kstep;
;             const char* a3 = a2 + kstep; const char* b3 = b2 + kstep;
;             PG8_LDB(B0, 0, 0); PG8_LDB(B1, 0, 1); PG8_SCHED; PG8_LDA(At, 0, 0); PG8_STAGE(PG8_SA(1, 1), a1 + hstepA, voffA);
;             PG8_WAIT_V(8); PG8_WAIT_L(0); PG8_BAR; PG8_MMA(0, 0, At, B0); PG8_MMA(0, 1, At, B1); PG8_BAR; PG8_SCHED;
;             PG8_LDA(At, 0, 1); PG8_STAGE(PG8_SB(0, 0), b2, voffB); PG8_STAGE(PG8_SB(0, 1), b2 + hstepB, voffB); PG8_STAGE(PG8_SA(0, 0), a2, voffA);
.LBB0_1893:
	ds_read_b128 v[172:175], v236
	ds_read_b128 v[180:183], v236 offset:1024
	ds_read_b128 v[184:187], v236 offset:2048
	ds_read_b128 v[188:191], v236 offset:3072
	ds_read_b128 v[192:195], v236 offset:4096
	ds_read_b128 v[196:199], v236 offset:5120
	ds_read_b128 v[200:203], v236 offset:6144
	ds_read_b128 v[204:207], v236 offset:7168
	s_add_i32 s79, s46, 2
	s_add_u32 s38, s36, 0x100
	s_addc_u32 s39, s37, 0
	s_add_i32 s82, 0, 0x10000
	s_cmp_eq_u32 s25, s46
	s_cselect_b32 s49, s29, s39
	s_cselect_b32 s48, s28, s38
	s_cselect_b32 s47, s35, s78
	s_cselect_b32 s46, s34, s77
	s_add_i32 s85, 0, 0x14000
	v_add_u32_e32 v152, s82, v249
	v_add_u32_e32 v168, s85, v249
	ds_read_b128 v[130:133], v152
	ds_read_b128 v[134:137], v152 offset:1024
	ds_read_b128 v[148:151], v152 offset:2048
	ds_read_b128 v[152:155], v152 offset:3072
	ds_read_b128 v[156:159], v168
	ds_read_b128 v[160:163], v168 offset:1024
	ds_read_b128 v[164:167], v168 offset:2048
	ds_read_b128 v[168:171], v168 offset:3072
	v_lshl_add_u64 v[208:209], s[36:37], 0, v[144:145]
	s_add_i32 m0, s50, 0xc000
	s_nop 0
	global_load_lds_dwordx4 v[208:209], off
	v_lshl_add_u64 v[208:209], s[36:37], 0, v[146:147]
	s_add_i32 m0, s50, 0xe000
	s_nop 0
	global_load_lds_dwordx4 v[208:209], off
	s_waitcnt vmcnt(8)
	s_waitcnt lgkmcnt(0)
	s_setprio 1
	s_barrier
	v_mfma_f32_16x16x32_bf16 v[126:129], v[130:133], v[172:175], v[126:129]
	v_mfma_f32_16x16x32_bf16 v[122:125], v[148:151], v[172:175], v[122:125]
	v_mfma_f32_16x16x32_bf16 v[110:113], v[130:133], v[184:187], v[110:113]
	v_mfma_f32_16x16x32_bf16 v[106:109], v[148:151], v[184:187], v[106:109]
	v_mfma_f32_16x16x32_bf16 v[94:97], v[130:133], v[192:195], v[94:97]
	v_mfma_f32_16x16x32_bf16 v[90:93], v[148:151], v[192:195], v[90:93]
	v_mfma_f32_16x16x32_bf16 v[78:81], v[130:133], v[200:203], v[78:81]
	v_mfma_f32_16x16x32_bf16 v[74:77], v[148:151], v[200:203], v[74:77]
	v_mfma_f32_16x16x32_bf16 v[126:129], v[134:137], v[180:183], v[126:129]
	v_mfma_f32_16x16x32_bf16 v[122:125], v[152:155], v[180:183], v[122:125]
	v_mfma_f32_16x16x32_bf16 v[110:113], v[134:137], v[188:191], v[110:113]
	v_mfma_f32_16x16x32_bf16 v[106:109], v[152:155], v[188:191], v[106:109]
	v_mfma_f32_16x16x32_bf16 v[94:97], v[134:137], v[196:199], v[94:97]
	v_mfma_f32_16x16x32_bf16 v[90:93], v[152:155], v[196:199], v[90:93]
	v_mfma_f32_16x16x32_bf16 v[78:81], v[134:137], v[204:207], v[78:81]
	v_mfma_f32_16x16x32_bf16 v[74:77], v[152:155], v[204:207], v[74:77]
	v_mfma_f32_16x16x32_bf16 v[118:121], v[156:159], v[172:175], v[118:121]
	v_mfma_f32_16x16x32_bf16 v[114:117], v[164:167], v[172:175], v[114:117]
	v_mfma_f32_16x16x32_bf16 v[102:105], v[156:159], v[184:187], v[102:105]
	v_mfma_f32_16x16x32_bf16 v[98:101], v[164:167], v[184:187], v[98:101]
	v_mfma_f32_16x16x32_bf16 v[86:89], v[156:159], v[192:195], v[86:89]
	v_mfma_f32_16x16x32_bf16 v[82:85], v[164:167], v[192:195], v[82:85]
	v_mfma_f32_16x16x32_bf16 v[70:73], v[156:159], v[200:203], v[70:73]
	v_mfma_f32_16x16x32_bf16 v[66:69], v[164:167], v[200:203], v[66:69]
	v_mfma_f32_16x16x32_bf16 v[118:121], v[160:163], v[180:183], v[118:121]
	v_mfma_f32_16x16x32_bf16 v[114:117], v[168:171], v[180:183], v[114:117]
	v_mfma_f32_16x16x32_bf16 v[102:105], v[160:163], v[188:191], v[102:105]
	v_mfma_f32_16x16x32_bf16 v[98:101], v[168:171], v[188:191], v[98:101]
	v_mfma_f32_16x16x32_bf16 v[86:89], v[160:163], v[196:199], v[86:89]
	v_mfma_f32_16x16x32_bf16 v[82:85], v[168:171], v[196:199], v[82:85]
	v_mfma_f32_16x16x32_bf16 v[70:73], v[160:163], v[204:207], v[70:73]
	v_mfma_f32_16x16x32_bf16 v[66:69], v[168:171], v[204:207], v[66:69]
	s_barrier
	s_setprio 0
	ds_read_b128 v[172:175], v236 offset:16384
	ds_read_b128 v[180:183], v236 offset:17408
	ds_read_b128 v[184:187], v236 offset:18432
	ds_read_b128 v[188:191], v236 offset:19456
	ds_read_b128 v[192:195], v236 offset:20480
	ds_read_b128 v[196:199], v236 offset:21504
	ds_read_b128 v[200:203], v236 offset:22528
	ds_read_b128 v[204:207], v236 offset:23552
	s_add_i32 s36, s82, s2
	v_lshl_add_u64 v[208:209], s[46:47], 0, v[0:1]
	s_mov_b32 m0, s36
	s_nop 0
	global_load_lds_dwordx4 v[208:209], off
	s_add_i32 m0, s36, 0x2000
	s_add_u32 s36, s46, 0x160000
	v_lshl_add_u64 v[210:211], s[46:47], 0, v[142:143]
	s_addc_u32 s37, s47, 0
	s_add_i32 s82, s85, s2
	global_load_lds_dwordx4 v[210:211], off
	v_lshl_add_u64 v[212:213], s[36:37], 0, v[0:1]
	s_mov_b32 m0, s82
	v_lshl_add_u64 v[214:215], s[48:49], 0, v[140:141]
	global_load_lds_dwordx4 v[212:213], off
	v_lshl_add_u64 v[212:213], s[36:37], 0, v[142:143]
	s_add_i32 m0, s82, 0x2000
	s_nop 0
	global_load_lds_dwordx4 v[212:213], off
	v_lshl_add_u64 v[212:213], s[48:49], 0, v[138:139]
	s_mov_b32 m0, s50
	s_nop 0
	global_load_lds_dwordx4 v[212:213], off
	s_mov_b32 m0, s51
	s_nop 0
	global_load_lds_dwordx4 v[214:215], off
	s_waitcnt vmcnt(8)
	s_waitcnt lgkmcnt(0)
	s_setprio 1
	s_barrier
; #define PG8_STAGE(bufoff, gbase, voff) do { _Pragma("unroll") for (int _i = 0; _i < 2; ++_i) \
;         __builtin_amdgcn_global_load_lds((const unsigned*)((const char*)(gbase) + (voff)[_i]), (LAS unsigned*)(lds + (bufoff) + ldsw + _i * 8192), 16, 0, 0); } while (0)
; #define PG8_LDA(dst, b, h) do { _Pragma("unroll") for (int m = 0; m < 4; ++m) _Pragma("unroll") for (int k = 0; k < 2; ++k) dst[m][k] = *(const LAS bf16x8*)(lds + PG8_SA(b, h) + aoff + m * 2048 + k * 1024); } while (0)
; #define PG8_LDB(dst, b, h) do { _Pragma("unroll") for (int n = 0; n < 2; ++n) _Pragma("unroll") for (int k = 0; k < 2; ++k) dst[n][k] = *(const LAS bf16x8*)(lds + PG8_SB(b, h) + boff + n * 2048 + k * 1024); } while (0)
; #define PG8_MMA(ai, bj, At, Bt) do { __builtin_amdgcn_s_setprio(1); _Pragma("unroll") for (int m = 0; m < 4; ++m) _Pragma("unroll") for (int n = 0; n < 2; ++n) _Pragma("unroll") for (int k = 0; k < 2; ++k) \
;         acc[ai][bj][m][n] = __builtin_amdgcn_mfma_f32_16x16x32_bf16(Bt[n][k], At[m][k], acc[ai][bj][m][n], 0, 0, 0); __builtin_amdgcn_s_setprio(0); } while (0)
; #define PG8_WAIT_V(n) asm volatile("s_waitcnt vmcnt(" #n ")" ::: "memory")
; #define PG8_WAIT_L(n) asm volatile("s_waitcnt lgkmcnt(" #n ")" ::: "memory")
; #define PG8_BAR __builtin_amdgcn_s_barrier()
; #define PG8_SCHED __builtin_amdgcn_sched_barrier(0)
; template <class Epi, class Sched, int LDA, int LDB, bool ALIGN_EPI = true>
; __device__ __forceinline__ void gemm_phase(LAS unsigned char* lds, const Gemm g, const Sched& S, const Epi& E, int wave) {
;     ...
;             PG8_WAIT_V(8); PG8_WAIT_L(0); PG8_BAR; PG8_MMA(1, 0, At, B0); PG8_MMA(1, 1, At, B1); PG8_BAR; PG8_SCHED;
;             PG8_LDB(B0, 1, 0); PG8_LDB(B1, 1, 1); PG8_SCHED; PG8_LDA(At, 1, 0); PG8_STAGE(PG8_SA(0, 1), a2 + hstepA, voffA);
;             PG8_WAIT_V(8); PG8_WAIT_L(0); PG8_BAR; PG8_MMA(0, 0, At, B0); PG8_MMA(0, 1, At, B1); PG8_BAR; PG8_SCHED;
	v_mfma_f32_16x16x32_bf16 v[62:65], v[130:133], v[172:175], v[62:65]
	v_mfma_f32_16x16x32_bf16 v[58:61], v[148:151], v[172:175], v[58:61]
	v_mfma_f32_16x16x32_bf16 v[46:49], v[130:133], v[184:187], v[46:49]
	v_mfma_f32_16x16x32_bf16 v[42:45], v[148:151], v[184:187], v[42:45]
	v_mfma_f32_16x16x32_bf16 v[30:33], v[130:133], v[192:195], v[30:33]
	v_mfma_f32_16x16x32_bf16 v[26:29], v[148:151], v[192:195], v[26:29]
	v_mfma_f32_16x16x32_bf16 v[14:17], v[130:133], v[200:203], v[14:17]
	v_mfma_f32_16x16x32_bf16 v[10:13], v[148:151], v[200:203], v[10:13]
	v_mfma_f32_16x16x32_bf16 v[62:65], v[134:137], v[180:183], v[62:65]
	v_mfma_f32_16x16x32_bf16 v[58:61], v[152:155], v[180:183], v[58:61]
	v_mfma_f32_16x16x32_bf16 v[46:49], v[134:137], v[188:191], v[46:49]
	v_mfma_f32_16x16x32_bf16 v[42:45], v[152:155], v[188:191], v[42:45]
	v_mfma_f32_16x16x32_bf16 v[30:33], v[134:137], v[196:199], v[30:33]
	v_mfma_f32_16x16x32_bf16 v[26:29], v[152:155], v[196:199], v[26:29]
	v_mfma_f32_16x16x32_bf16 v[14:17], v[134:137], v[204:207], v[14:17]
	v_mfma_f32_16x16x32_bf16 v[10:13], v[152:155], v[204:207], v[10:13]
	v_mfma_f32_16x16x32_bf16 v[54:57], v[156:159], v[172:175], v[54:57]
	v_mfma_f32_16x16x32_bf16 v[50:53], v[164:167], v[172:175], v[50:53]
	v_mfma_f32_16x16x32_bf16 v[38:41], v[156:159], v[184:187], v[38:41]
	v_mfma_f32_16x16x32_bf16 v[34:37], v[164:167], v[184:187], v[34:37]
	v_mfma_f32_16x16x32_bf16 v[22:25], v[156:159], v[192:195], v[22:25]
	v_mfma_f32_16x16x32_bf16 v[18:21], v[164:167], v[192:195], v[18:21]
	v_mfma_f32_16x16x32_bf16 v[6:9], v[156:159], v[200:203], v[6:9]
	v_mfma_f32_16x16x32_bf16 v[2:5], v[164:167], v[200:203], v[2:5]
	v_mfma_f32_16x16x32_bf16 v[54:57], v[160:163], v[180:183], v[54:57]
	v_mfma_f32_16x16x32_bf16 v[50:53], v[168:171], v[180:183], v[50:53]
	v_mfma_f32_16x16x32_bf16 v[38:41], v[160:163], v[188:191], v[38:41]
	v_mfma_f32_16x16x32_bf16 v[34:37], v[168:171], v[188:191], v[34:37]
	v_mfma_f32_16x16x32_bf16 v[22:25], v[160:163], v[196:199], v[22:25]
	v_mfma_f32_16x16x32_bf16 v[18:21], v[168:171], v[196:199], v[18:21]
	v_mfma_f32_16x16x32_bf16 v[6:9], v[160:163], v[204:207], v[6:9]
	v_mfma_f32_16x16x32_bf16 v[2:5], v[168:171], v[204:207], v[2:5]
	s_barrier
	s_setprio 0
	ds_read_b128 v[172:175], v236 offset:32768
	ds_read_b128 v[180:183], v236 offset:33792
	ds_read_b128 v[184:187], v236 offset:34816
	ds_read_b128 v[188:191], v236 offset:35840
	ds_read_b128 v[192:195], v236 offset:36864
	ds_read_b128 v[196:199], v236 offset:37888
	ds_read_b128 v[200:203], v236 offset:38912
	ds_read_b128 v[204:207], v236 offset:39936
	s_add_i32 s82, 0, 0x18000
	s_add_i32 s85, 0, 0x1c000
	v_add_u32_e32 v152, s82, v249
	v_add_u32_e32 v168, s85, v249
	ds_read_b128 v[130:133], v152
	ds_read_b128 v[134:137], v152 offset:1024
	ds_read_b128 v[148:151], v152 offset:2048
	ds_read_b128 v[152:155], v152 offset:3072
	ds_read_b128 v[156:159], v168
	ds_read_b128 v[160:163], v168 offset:1024
	ds_read_b128 v[164:167], v168 offset:2048
	ds_read_b128 v[168:171], v168 offset:3072
	s_add_u32 s36, s48, 0x160000
	s_addc_u32 s37, s49, 0
	s_mov_b32 m0, s52
	v_lshl_add_u64 v[216:217], s[36:37], 0, v[138:139]
	global_load_lds_dwordx4 v[216:217], off
	v_lshl_add_u64 v[216:217], s[36:37], 0, v[140:141]
	s_mov_b32 m0, s53
	s_nop 0
	global_load_lds_dwordx4 v[216:217], off
	s_waitcnt vmcnt(8)
	s_waitcnt lgkmcnt(0)
	s_setprio 1
	s_barrier
	v_mfma_f32_16x16x32_bf16 v[126:129], v[130:133], v[172:175], v[126:129]
	v_mfma_f32_16x16x32_bf16 v[122:125], v[148:151], v[172:175], v[122:125]
	v_mfma_f32_16x16x32_bf16 v[110:113], v[130:133], v[184:187], v[110:113]
	v_mfma_f32_16x16x32_bf16 v[106:109], v[148:151], v[184:187], v[106:109]
	v_mfma_f32_16x16x32_bf16 v[94:97], v[130:133], v[192:195], v[94:97]
	v_mfma_f32_16x16x32_bf16 v[90:93], v[148:151], v[192:195], v[90:93]
	v_mfma_f32_16x16x32_bf16 v[78:81], v[130:133], v[200:203], v[78:81]
	v_mfma_f32_16x16x32_bf16 v[74:77], v[148:151], v[200:203], v[74:77]
	v_mfma_f32_16x16x32_bf16 v[126:129], v[134:137], v[180:183], v[126:129]
	v_mfma_f32_16x16x32_bf16 v[122:125], v[152:155], v[180:183], v[122:125]
	v_mfma_f32_16x16x32_bf16 v[110:113], v[134:137], v[188:191], v[110:113]
	v_mfma_f32_16x16x32_bf16 v[106:109], v[152:155], v[188:191], v[106:109]
	v_mfma_f32_16x16x32_bf16 v[94:97], v[134:137], v[196:199], v[94:97]
	v_mfma_f32_16x16x32_bf16 v[90:93], v[152:155], v[196:199], v[90:93]
	v_mfma_f32_16x16x32_bf16 v[78:81], v[134:137], v[204:207], v[78:81]
	v_mfma_f32_16x16x32_bf16 v[74:77], v[152:155], v[204:207], v[74:77]
	v_mfma_f32_16x16x32_bf16 v[118:121], v[156:159], v[172:175], v[118:121]
	v_mfma_f32_16x16x32_bf16 v[114:117], v[164:167], v[172:175], v[114:117]
	v_mfma_f32_16x16x32_bf16 v[102:105], v[156:159], v[184:187], v[102:105]
	v_mfma_f32_16x16x32_bf16 v[98:101], v[164:167], v[184:187], v[98:101]
	v_mfma_f32_16x16x32_bf16 v[86:89], v[156:159], v[192:195], v[86:89]
	v_mfma_f32_16x16x32_bf16 v[82:85], v[164:167], v[192:195], v[82:85]
	v_mfma_f32_16x16x32_bf16 v[70:73], v[156:159], v[200:203], v[70:73]
	v_mfma_f32_16x16x32_bf16 v[66:69], v[164:167], v[200:203], v[66:69]
	v_mfma_f32_16x16x32_bf16 v[118:121], v[160:163], v[180:183], v[118:121]
	v_mfma_f32_16x16x32_bf16 v[114:117], v[168:171], v[180:183], v[114:117]
	v_mfma_f32_16x16x32_bf16 v[102:105], v[160:163], v[188:191], v[102:105]
	v_mfma_f32_16x16x32_bf16 v[98:101], v[168:171], v[188:191], v[98:101]
	v_mfma_f32_16x16x32_bf16 v[86:89], v[160:163], v[196:199], v[86:89]
	v_mfma_f32_16x16x32_bf16 v[82:85], v[168:171], v[196:199], v[82:85]
	v_mfma_f32_16x16x32_bf16 v[70:73], v[160:163], v[204:207], v[70:73]
	v_mfma_f32_16x16x32_bf16 v[66:69], v[168:171], v[204:207], v[66:69]
	s_barrier
; #define PG8_STAGE(bufoff, gbase, voff) do { _Pragma("unroll") for (int _i = 0; _i < 2; ++_i) \
;         __builtin_amdgcn_global_load_lds((const unsigned*)((const char*)(gbase) + (voff)[_i]), (LAS unsigned*)(lds + (bufoff) + ldsw + _i * 8192), 16, 0, 0); } while (0)
; #define PG8_LDA(dst, b, h) do { _Pragma("unroll") for (int m = 0; m < 4; ++m) _Pragma("unroll") for (int k = 0; k < 2; ++k) dst[m][k] = *(const LAS bf16x8*)(lds + PG8_SA(b, h) + aoff + m * 2048 + k * 1024); } while (0)
; #define PG8_MMA(ai, bj, At, Bt) do { __builtin_amdgcn_s_setprio(1); _Pragma("unroll") for (int m = 0; m < 4; ++m) _Pragma("unroll") for (int n = 0; n < 2; ++n) _Pragma("unroll") for (int k = 0; k < 2; ++k) \
;         acc[ai][bj][m][n] = __builtin_amdgcn_mfma_f32_16x16x32_bf16(Bt[n][k], At[m][k], acc[ai][bj][m][n], 0, 0, 0); __builtin_amdgcn_s_setprio(0); } while (0)
; #define PG8_WAIT_V(n) asm volatile("s_waitcnt vmcnt(" #n ")" ::: "memory")
; #define PG8_WAIT_L(n) asm volatile("s_waitcnt lgkmcnt(" #n ")" ::: "memory")
; #define PG8_BAR __builtin_amdgcn_s_barrier()
; #define PG8_SCHED __builtin_amdgcn_sched_barrier(0)
; template <class Epi, class Sched, int LDA, int LDB, bool ALIGN_EPI = true>
; __device__ __forceinline__ void gemm_phase(LAS unsigned char* lds, const Gemm g, const Sched& S, const Epi& E, int wave) {
;     ...
;             PG8_LDA(At, 1, 1); PG8_STAGE(PG8_SB(1, 0), b3, voffB); PG8_STAGE(PG8_SB(1, 1), b3 + hstepB, voffB); PG8_STAGE(PG8_SA(1, 0), a3, voffA);
;             PG8_WAIT_V(8); PG8_WAIT_L(0); PG8_BAR; PG8_MMA(1, 0, At, B0); PG8_MMA(1, 1, At, B1); PG8_BAR; PG8_SCHED;
;         }
	s_setprio 0
	ds_read_b128 v[172:175], v236 offset:49152
	ds_read_b128 v[180:183], v236 offset:50176
	ds_read_b128 v[184:187], v236 offset:51200
	ds_read_b128 v[188:191], v236 offset:52224
	ds_read_b128 v[192:195], v236 offset:53248
	ds_read_b128 v[196:199], v236 offset:54272
	ds_read_b128 v[200:203], v236 offset:55296
	ds_read_b128 v[204:207], v236 offset:56320
	s_add_i32 s36, s82, s2
	v_lshl_add_u64 v[208:209], v[208:209], 0, s[8:9]
	s_mov_b32 m0, s36
	s_nop 0
	global_load_lds_dwordx4 v[208:209], off
	s_add_i32 m0, s36, 0x2000
	s_add_u32 s36, s46, 0x160080
	v_lshl_add_u64 v[208:209], v[210:211], 0, s[8:9]
	s_addc_u32 s37, s47, 0
	s_add_i32 s46, s85, s2
	global_load_lds_dwordx4 v[208:209], off
	v_lshl_add_u64 v[208:209], s[36:37], 0, v[0:1]
	s_mov_b32 m0, s46
	s_nop 0
	global_load_lds_dwordx4 v[208:209], off
	v_lshl_add_u64 v[208:209], s[36:37], 0, v[142:143]
	s_add_i32 m0, s46, 0x2000
	s_nop 0
	global_load_lds_dwordx4 v[208:209], off
	v_lshl_add_u64 v[208:209], v[212:213], 0, s[8:9]
	s_mov_b32 m0, s5
	s_nop 0
	global_load_lds_dwordx4 v[208:209], off
	v_lshl_add_u64 v[208:209], v[214:215], 0, s[8:9]
	s_mov_b32 m0, s59
	s_nop 0
	global_load_lds_dwordx4 v[208:209], off
	s_waitcnt vmcnt(8)
	s_waitcnt lgkmcnt(0)
	s_setprio 1
	s_barrier
	v_mfma_f32_16x16x32_bf16 v[62:65], v[130:133], v[172:175], v[62:65]
	v_mfma_f32_16x16x32_bf16 v[58:61], v[148:151], v[172:175], v[58:61]
	v_mfma_f32_16x16x32_bf16 v[46:49], v[130:133], v[184:187], v[46:49]
	v_mfma_f32_16x16x32_bf16 v[42:45], v[148:151], v[184:187], v[42:45]
	v_mfma_f32_16x16x32_bf16 v[30:33], v[130:133], v[192:195], v[30:33]
	v_mfma_f32_16x16x32_bf16 v[26:29], v[148:151], v[192:195], v[26:29]
	v_mfma_f32_16x16x32_bf16 v[14:17], v[130:133], v[200:203], v[14:17]
	v_mfma_f32_16x16x32_bf16 v[10:13], v[148:151], v[200:203], v[10:13]
	v_mfma_f32_16x16x32_bf16 v[62:65], v[134:137], v[180:183], v[62:65]
	v_mfma_f32_16x16x32_bf16 v[58:61], v[152:155], v[180:183], v[58:61]
	v_mfma_f32_16x16x32_bf16 v[46:49], v[134:137], v[188:191], v[46:49]
	v_mfma_f32_16x16x32_bf16 v[42:45], v[152:155], v[188:191], v[42:45]
	v_mfma_f32_16x16x32_bf16 v[30:33], v[134:137], v[196:199], v[30:33]
	v_mfma_f32_16x16x32_bf16 v[26:29], v[152:155], v[196:199], v[26:29]
	v_mfma_f32_16x16x32_bf16 v[14:17], v[134:137], v[204:207], v[14:17]
	v_mfma_f32_16x16x32_bf16 v[10:13], v[152:155], v[204:207], v[10:13]
	v_mfma_f32_16x16x32_bf16 v[54:57], v[156:159], v[172:175], v[54:57]
	v_mfma_f32_16x16x32_bf16 v[50:53], v[164:167], v[172:175], v[50:53]
	v_mfma_f32_16x16x32_bf16 v[38:41], v[156:159], v[184:187], v[38:41]
	v_mfma_f32_16x16x32_bf16 v[34:37], v[164:167], v[184:187], v[34:37]
	v_mfma_f32_16x16x32_bf16 v[22:25], v[156:159], v[192:195], v[22:25]
	v_mfma_f32_16x16x32_bf16 v[18:21], v[164:167], v[192:195], v[18:21]
	v_mfma_f32_16x16x32_bf16 v[6:9], v[156:159], v[200:203], v[6:9]
	v_mfma_f32_16x16x32_bf16 v[2:5], v[164:167], v[200:203], v[2:5]
	v_mfma_f32_16x16x32_bf16 v[54:57], v[160:163], v[180:183], v[54:57]
	v_mfma_f32_16x16x32_bf16 v[50:53], v[168:171], v[180:183], v[50:53]
	v_mfma_f32_16x16x32_bf16 v[38:41], v[160:163], v[188:191], v[38:41]
	v_mfma_f32_16x16x32_bf16 v[34:37], v[168:171], v[188:191], v[34:37]
	v_mfma_f32_16x16x32_bf16 v[22:25], v[160:163], v[196:199], v[22:25]
	v_mfma_f32_16x16x32_bf16 v[18:21], v[168:171], v[196:199], v[18:21]
	v_mfma_f32_16x16x32_bf16 v[6:9], v[160:163], v[204:207], v[6:9]
	v_mfma_f32_16x16x32_bf16 v[2:5], v[168:171], v[204:207], v[2:5]
	s_barrier
	s_setprio 0
	s_add_u32 s77, s77, 0x100
	s_addc_u32 s78, s78, 0
	s_cmp_ge_i32 s79, s75
	s_mov_b64 s[36:37], s[38:39]
	s_mov_b32 s46, s79
	s_cbranch_scc0 .LBB0_1893
	v_readlane_b32 s2, v252, 14
	v_readlane_b32 s3, v252, 15
	s_and_b64 vcc, exec, s[2:3]
	s_cbranch_vccz .LBB0_1896
	s_barrier

; #define PG8_STAGE(bufoff, gbase, voff) do { _Pragma("unroll") for (int _i = 0; _i < 2; ++_i) \
;         __builtin_amdgcn_global_load_lds((const unsigned*)((const char*)(gbase) + (voff)[_i]), (LAS unsigned*)(lds + (bufoff) + ldsw + _i * 8192), 16, 0, 0); } while (0)
; #define PG8_LDA(dst, b, h) do { _Pragma("unroll") for (int m = 0; m < 4; ++m) _Pragma("unroll") for (int k = 0; k < 2; ++k) dst[m][k] = *(const LAS bf16x8*)(lds + PG8_SA(b, h) + aoff + m * 2048 + k * 1024); } while (0)
; #define PG8_LDB(dst, b, h) do { _Pragma("unroll") for (int n = 0; n < 2; ++n) _Pragma("unroll") for (int k = 0; k < 2; ++k) dst[n][k] = *(const LAS bf16x8*)(lds + PG8_SB(b, h) + boff + n * 2048 + k * 1024); } while (0)
; #define PG8_MMA(ai, bj, At, Bt) do { __builtin_amdgcn_s_setprio(1); _Pragma("unroll") for (int m = 0; m < 4; ++m) _Pragma("unroll") for (int n = 0; n < 2; ++n) _Pragma("unroll") for (int k = 0; k < 2; ++k) \
;         acc[ai][bj][m][n] = __builtin_amdgcn_mfma_f32_16x16x32_bf16(Bt[n][k], At[m][k], acc[ai][bj][m][n], 0, 0, 0); __builtin_amdgcn_s_setprio(0); } while (0)
; #define PG8_WAIT_V(n) asm volatile("s_waitcnt vmcnt(" #n ")" ::: "memory")
; #define PG8_WAIT_L(n) asm volatile("s_waitcnt lgkmcnt(" #n ")" ::: "memory")
; #define PG8_BAR __builtin_amdgcn_s_barrier()
; #define PG8_SCHED __builtin_amdgcn_sched_barrier(0)
; template <class Epi, class Sched, int LDA, int LDB, bool ALIGN_EPI = true>
; __device__ __forceinline__ void gemm_phase(LAS unsigned char* lds, const Gemm g, const Sched& S, const Epi& E, int wave) {
;     ...
;             PG8_LDB(B0, 0, 0); PG8_LDB(B1, 0, 1); PG8_SCHED; PG8_LDA(At, 0, 0); PG8_STAGE(PG8_SA(1, 1), a1 + hstepA, voffA);
;             PG8_WAIT_V(8); PG8_WAIT_L(0); PG8_BAR; PG8_MMA(0, 0, At, B0); PG8_MMA(0, 1, At, B1); PG8_BAR; PG8_SCHED;
;             PG8_LDA(At, 0, 1); PG8_STAGE(PG8_SB(0, 0), b2, voffB); PG8_STAGE(PG8_SB(0, 1), b2 + hstepB, voffB); PG8_STAGE(PG8_SA(0, 0), a2, voffA);
;             PG8_WAIT_V(8); PG8_WAIT_L(0); PG8_BAR; PG8_MMA(1, 0, At, B0); PG8_MMA(1, 1, At, B1); PG8_BAR; PG8_SCHED;
.LBB0_2254:
	ds_read_b128 v[184:187], v163
	ds_read_b128 v[188:191], v163 offset:1024
	ds_read_b128 v[192:195], v163 offset:2048
	ds_read_b128 v[196:199], v163 offset:3072
	ds_read_b128 v[200:203], v163 offset:4096
	ds_read_b128 v[204:207], v163 offset:5120
	ds_read_b128 v[208:211], v163 offset:6144
	ds_read_b128 v[212:215], v163 offset:7168
	s_add_u32 s2, s0, 0x100
	s_addc_u32 s3, s1, 0
	s_add_i32 s64, 0, 0x10000
	s_cmp_eq_u32 s59, 28
	s_cselect_b32 s29, s15, s3
	s_cselect_b32 s28, s14, s2
	v_add_u32_e32 v0, s64, v161
	s_cselect_b32 s25, s13, s58
	s_cselect_b32 s24, s48, s49
	s_add_i32 s65, 0, 0x14000
	ds_read_b128 v[144:147], v0
	ds_read_b128 v[148:151], v0 offset:1024
	ds_read_b128 v[152:155], v0 offset:2048
	ds_read_b128 v[156:159], v0 offset:3072
	v_add_u32_e32 v0, s65, v161
	ds_read_b128 v[164:167], v0
	ds_read_b128 v[168:171], v0 offset:1024
	ds_read_b128 v[172:175], v0 offset:2048
	ds_read_b128 v[180:183], v0 offset:3072
	v_lshl_add_u64 v[216:217], s[0:1], 0, v[140:141]
	s_add_i32 m0, s19, 0xc000
	s_nop 0
	global_load_lds_dwordx4 v[216:217], off
	v_lshl_add_u64 v[216:217], s[0:1], 0, v[142:143]
	s_add_i32 m0, s19, 0xe000
	s_nop 0
	global_load_lds_dwordx4 v[216:217], off
	s_waitcnt vmcnt(8)
	s_waitcnt lgkmcnt(0)
	s_setprio 1
	s_barrier
	v_mfma_f32_16x16x32_bf16 v[126:129], v[144:147], v[184:187], v[126:129]
	v_mfma_f32_16x16x32_bf16 v[122:125], v[152:155], v[184:187], v[122:125]
	v_mfma_f32_16x16x32_bf16 v[118:121], v[144:147], v[192:195], v[118:121]
	v_mfma_f32_16x16x32_bf16 v[114:117], v[152:155], v[192:195], v[114:117]
	v_mfma_f32_16x16x32_bf16 v[110:113], v[144:147], v[200:203], v[110:113]
	v_mfma_f32_16x16x32_bf16 v[106:109], v[152:155], v[200:203], v[106:109]
	v_mfma_f32_16x16x32_bf16 v[102:105], v[144:147], v[208:211], v[102:105]
	v_mfma_f32_16x16x32_bf16 v[98:101], v[152:155], v[208:211], v[98:101]
	v_mfma_f32_16x16x32_bf16 v[126:129], v[148:151], v[188:191], v[126:129]
	v_mfma_f32_16x16x32_bf16 v[122:125], v[156:159], v[188:191], v[122:125]
	v_mfma_f32_16x16x32_bf16 v[118:121], v[148:151], v[196:199], v[118:121]
	v_mfma_f32_16x16x32_bf16 v[114:117], v[156:159], v[196:199], v[114:117]
	v_mfma_f32_16x16x32_bf16 v[110:113], v[148:151], v[204:207], v[110:113]
	v_mfma_f32_16x16x32_bf16 v[106:109], v[156:159], v[204:207], v[106:109]
	v_mfma_f32_16x16x32_bf16 v[102:105], v[148:151], v[212:215], v[102:105]
	v_mfma_f32_16x16x32_bf16 v[98:101], v[156:159], v[212:215], v[98:101]
	v_mfma_f32_16x16x32_bf16 v[62:65], v[164:167], v[184:187], v[62:65]
	v_mfma_f32_16x16x32_bf16 v[58:61], v[172:175], v[184:187], v[58:61]
	v_mfma_f32_16x16x32_bf16 v[54:57], v[164:167], v[192:195], v[54:57]
	v_mfma_f32_16x16x32_bf16 v[50:53], v[172:175], v[192:195], v[50:53]
	v_mfma_f32_16x16x32_bf16 v[46:49], v[164:167], v[200:203], v[46:49]
	v_mfma_f32_16x16x32_bf16 v[42:45], v[172:175], v[200:203], v[42:45]
	v_mfma_f32_16x16x32_bf16 v[38:41], v[164:167], v[208:211], v[38:41]
	v_mfma_f32_16x16x32_bf16 v[34:37], v[172:175], v[208:211], v[34:37]
	v_mfma_f32_16x16x32_bf16 v[62:65], v[168:171], v[188:191], v[62:65]
	v_mfma_f32_16x16x32_bf16 v[58:61], v[180:183], v[188:191], v[58:61]
	v_mfma_f32_16x16x32_bf16 v[54:57], v[168:171], v[196:199], v[54:57]
	v_mfma_f32_16x16x32_bf16 v[50:53], v[180:183], v[196:199], v[50:53]
	v_mfma_f32_16x16x32_bf16 v[46:49], v[168:171], v[204:207], v[46:49]
	v_mfma_f32_16x16x32_bf16 v[42:45], v[180:183], v[204:207], v[42:45]
	v_mfma_f32_16x16x32_bf16 v[38:41], v[168:171], v[212:215], v[38:41]
	v_mfma_f32_16x16x32_bf16 v[34:37], v[180:183], v[212:215], v[34:37]
	s_barrier
	s_setprio 0
	ds_read_b128 v[184:187], v163 offset:16384
	ds_read_b128 v[188:191], v163 offset:17408
	ds_read_b128 v[192:195], v163 offset:18432
	ds_read_b128 v[196:199], v163 offset:19456
	ds_read_b128 v[200:203], v163 offset:20480
	ds_read_b128 v[204:207], v163 offset:21504
	ds_read_b128 v[208:211], v163 offset:22528
	ds_read_b128 v[212:215], v163 offset:23552
	s_add_i32 s0, s64, s61
	v_lshl_add_u64 v[216:217], s[24:25], 0, v[132:133]
	s_mov_b32 m0, s0
	s_nop 0
	global_load_lds_dwordx4 v[216:217], off
	s_add_i32 m0, s0, 0x2000
	s_add_u32 s0, s24, 0x80000
	v_lshl_add_u64 v[218:219], s[24:25], 0, v[136:137]
	s_addc_u32 s1, s25, 0
	s_add_i32 s64, s65, s61
	global_load_lds_dwordx4 v[218:219], off
	v_lshl_add_u64 v[220:221], s[0:1], 0, v[132:133]
	s_mov_b32 m0, s64
	v_lshl_add_u64 v[222:223], s[28:29], 0, v[134:135]
	global_load_lds_dwordx4 v[220:221], off
	v_lshl_add_u64 v[220:221], s[0:1], 0, v[136:137]
	s_add_i32 m0, s64, 0x2000
	s_nop 0
	global_load_lds_dwordx4 v[220:221], off
	v_lshl_add_u64 v[220:221], s[28:29], 0, v[130:131]
	s_mov_b32 m0, s19
	s_nop 0
	global_load_lds_dwordx4 v[220:221], off
	s_mov_b32 m0, s35
	s_nop 0
	global_load_lds_dwordx4 v[222:223], off
	s_waitcnt vmcnt(8)
	s_waitcnt lgkmcnt(0)
	s_setprio 1
	s_barrier
; #define PG8_STAGE(bufoff, gbase, voff) do { _Pragma("unroll") for (int _i = 0; _i < 2; ++_i) \
;         __builtin_amdgcn_global_load_lds((const unsigned*)((const char*)(gbase) + (voff)[_i]), (LAS unsigned*)(lds + (bufoff) + ldsw + _i * 8192), 16, 0, 0); } while (0)
; #define PG8_LDA(dst, b, h) do { _Pragma("unroll") for (int m = 0; m < 4; ++m) _Pragma("unroll") for (int k = 0; k < 2; ++k) dst[m][k] = *(const LAS bf16x8*)(lds + PG8_SA(b, h) + aoff + m * 2048 + k * 1024); } while (0)
; #define PG8_LDB(dst, b, h) do { _Pragma("unroll") for (int n = 0; n < 2; ++n) _Pragma("unroll") for (int k = 0; k < 2; ++k) dst[n][k] = *(const LAS bf16x8*)(lds + PG8_SB(b, h) + boff + n * 2048 + k * 1024); } while (0)
; #define PG8_MMA(ai, bj, At, Bt) do { __builtin_amdgcn_s_setprio(1); _Pragma("unroll") for (int m = 0; m < 4; ++m) _Pragma("unroll") for (int n = 0; n < 2; ++n) _Pragma("unroll") for (int k = 0; k < 2; ++k) \
;         acc[ai][bj][m][n] = __builtin_amdgcn_mfma_f32_16x16x32_bf16(Bt[n][k], At[m][k], acc[ai][bj][m][n], 0, 0, 0); __builtin_amdgcn_s_setprio(0); } while (0)
; #define PG8_WAIT_V(n) asm volatile("s_waitcnt vmcnt(" #n ")" ::: "memory")
; #define PG8_WAIT_L(n) asm volatile("s_waitcnt lgkmcnt(" #n ")" ::: "memory")
; #define PG8_BAR __builtin_amdgcn_s_barrier()
; #define PG8_SCHED __builtin_amdgcn_sched_barrier(0)
; template <class Epi, class Sched, int LDA, int LDB, bool ALIGN_EPI = true>
; __device__ __forceinline__ void gemm_phase(LAS unsigned char* lds, const Gemm g, const Sched& S, const Epi& E, int wave) {
;     ...
;             PG8_WAIT_V(8); PG8_WAIT_L(0); PG8_BAR; PG8_MMA(1, 0, At, B0); PG8_MMA(1, 1, At, B1); PG8_BAR; PG8_SCHED;
;             PG8_LDB(B0, 1, 0); PG8_LDB(B1, 1, 1); PG8_SCHED; PG8_LDA(At, 1, 0); PG8_STAGE(PG8_SA(0, 1), a2 + hstepA, voffA);
;             PG8_WAIT_V(8); PG8_WAIT_L(0); PG8_BAR; PG8_MMA(0, 0, At, B0); PG8_MMA(0, 1, At, B1); PG8_BAR; PG8_SCHED;
	v_mfma_f32_16x16x32_bf16 v[94:97], v[144:147], v[184:187], v[94:97]
	v_mfma_f32_16x16x32_bf16 v[90:93], v[152:155], v[184:187], v[90:93]
	v_mfma_f32_16x16x32_bf16 v[86:89], v[144:147], v[192:195], v[86:89]
	v_mfma_f32_16x16x32_bf16 v[82:85], v[152:155], v[192:195], v[82:85]
	v_mfma_f32_16x16x32_bf16 v[78:81], v[144:147], v[200:203], v[78:81]
	v_mfma_f32_16x16x32_bf16 v[74:77], v[152:155], v[200:203], v[74:77]
	v_mfma_f32_16x16x32_bf16 v[70:73], v[144:147], v[208:211], v[70:73]
	v_mfma_f32_16x16x32_bf16 v[66:69], v[152:155], v[208:211], v[66:69]
	v_mfma_f32_16x16x32_bf16 v[94:97], v[148:151], v[188:191], v[94:97]
	v_mfma_f32_16x16x32_bf16 v[90:93], v[156:159], v[188:191], v[90:93]
	v_mfma_f32_16x16x32_bf16 v[86:89], v[148:151], v[196:199], v[86:89]
	v_mfma_f32_16x16x32_bf16 v[82:85], v[156:159], v[196:199], v[82:85]
	v_mfma_f32_16x16x32_bf16 v[78:81], v[148:151], v[204:207], v[78:81]
	v_mfma_f32_16x16x32_bf16 v[74:77], v[156:159], v[204:207], v[74:77]
	v_mfma_f32_16x16x32_bf16 v[70:73], v[148:151], v[212:215], v[70:73]
	v_mfma_f32_16x16x32_bf16 v[66:69], v[156:159], v[212:215], v[66:69]
	v_mfma_f32_16x16x32_bf16 v[30:33], v[164:167], v[184:187], v[30:33]
	v_mfma_f32_16x16x32_bf16 v[26:29], v[172:175], v[184:187], v[26:29]
	v_mfma_f32_16x16x32_bf16 v[22:25], v[164:167], v[192:195], v[22:25]
	v_mfma_f32_16x16x32_bf16 v[18:21], v[172:175], v[192:195], v[18:21]
	v_mfma_f32_16x16x32_bf16 v[14:17], v[164:167], v[200:203], v[14:17]
	v_mfma_f32_16x16x32_bf16 v[10:13], v[172:175], v[200:203], v[10:13]
	v_mfma_f32_16x16x32_bf16 v[6:9], v[164:167], v[208:211], v[6:9]
	v_mfma_f32_16x16x32_bf16 v[2:5], v[172:175], v[208:211], v[2:5]
	v_mfma_f32_16x16x32_bf16 v[30:33], v[168:171], v[188:191], v[30:33]
	v_mfma_f32_16x16x32_bf16 v[26:29], v[180:183], v[188:191], v[26:29]
	v_mfma_f32_16x16x32_bf16 v[22:25], v[168:171], v[196:199], v[22:25]
	v_mfma_f32_16x16x32_bf16 v[18:21], v[180:183], v[196:199], v[18:21]
	v_mfma_f32_16x16x32_bf16 v[14:17], v[168:171], v[204:207], v[14:17]
	v_mfma_f32_16x16x32_bf16 v[10:13], v[180:183], v[204:207], v[10:13]
	v_mfma_f32_16x16x32_bf16 v[6:9], v[168:171], v[212:215], v[6:9]
	v_mfma_f32_16x16x32_bf16 v[2:5], v[180:183], v[212:215], v[2:5]
	s_barrier
	s_setprio 0
	ds_read_b128 v[184:187], v163 offset:32768
	ds_read_b128 v[188:191], v163 offset:33792
	ds_read_b128 v[192:195], v163 offset:34816
	ds_read_b128 v[196:199], v163 offset:35840
	ds_read_b128 v[200:203], v163 offset:36864
	ds_read_b128 v[204:207], v163 offset:37888
	ds_read_b128 v[208:211], v163 offset:38912
	ds_read_b128 v[212:215], v163 offset:39936
	s_add_i32 s64, 0, 0x18000
	v_add_u32_e32 v0, s64, v161
	s_add_i32 s65, 0, 0x1c000
	ds_read_b128 v[144:147], v0
	ds_read_b128 v[148:151], v0 offset:1024
	ds_read_b128 v[152:155], v0 offset:2048
	ds_read_b128 v[156:159], v0 offset:3072
	v_add_u32_e32 v0, s65, v161
	ds_read_b128 v[164:167], v0
	ds_read_b128 v[168:171], v0 offset:1024
	ds_read_b128 v[172:175], v0 offset:2048
	ds_read_b128 v[180:183], v0 offset:3072
	s_add_u32 s0, s28, 0x84000
	s_addc_u32 s1, s29, 0
	s_mov_b32 m0, s36
	v_lshl_add_u64 v[224:225], s[0:1], 0, v[130:131]
	global_load_lds_dwordx4 v[224:225], off
	v_lshl_add_u64 v[224:225], s[0:1], 0, v[134:135]
	s_mov_b32 m0, s37
	s_nop 0
	global_load_lds_dwordx4 v[224:225], off
	s_waitcnt vmcnt(8)
	s_waitcnt lgkmcnt(0)
	s_setprio 1
	s_barrier
	v_mfma_f32_16x16x32_bf16 v[126:129], v[144:147], v[184:187], v[126:129]
	v_mfma_f32_16x16x32_bf16 v[122:125], v[152:155], v[184:187], v[122:125]
	v_mfma_f32_16x16x32_bf16 v[118:121], v[144:147], v[192:195], v[118:121]
	v_mfma_f32_16x16x32_bf16 v[114:117], v[152:155], v[192:195], v[114:117]
	v_mfma_f32_16x16x32_bf16 v[110:113], v[144:147], v[200:203], v[110:113]
	v_mfma_f32_16x16x32_bf16 v[106:109], v[152:155], v[200:203], v[106:109]
	v_mfma_f32_16x16x32_bf16 v[102:105], v[144:147], v[208:211], v[102:105]
	v_mfma_f32_16x16x32_bf16 v[98:101], v[152:155], v[208:211], v[98:101]
	v_mfma_f32_16x16x32_bf16 v[126:129], v[148:151], v[188:191], v[126:129]
	v_mfma_f32_16x16x32_bf16 v[122:125], v[156:159], v[188:191], v[122:125]
	v_mfma_f32_16x16x32_bf16 v[118:121], v[148:151], v[196:199], v[118:121]
	v_mfma_f32_16x16x32_bf16 v[114:117], v[156:159], v[196:199], v[114:117]
	v_mfma_f32_16x16x32_bf16 v[110:113], v[148:151], v[204:207], v[110:113]
	v_mfma_f32_16x16x32_bf16 v[106:109], v[156:159], v[204:207], v[106:109]
	v_mfma_f32_16x16x32_bf16 v[102:105], v[148:151], v[212:215], v[102:105]
	v_mfma_f32_16x16x32_bf16 v[98:101], v[156:159], v[212:215], v[98:101]
	v_mfma_f32_16x16x32_bf16 v[62:65], v[164:167], v[184:187], v[62:65]
	v_mfma_f32_16x16x32_bf16 v[58:61], v[172:175], v[184:187], v[58:61]
	v_mfma_f32_16x16x32_bf16 v[54:57], v[164:167], v[192:195], v[54:57]
	v_mfma_f32_16x16x32_bf16 v[50:53], v[172:175], v[192:195], v[50:53]
	v_mfma_f32_16x16x32_bf16 v[46:49], v[164:167], v[200:203], v[46:49]
	v_mfma_f32_16x16x32_bf16 v[42:45], v[172:175], v[200:203], v[42:45]
	v_mfma_f32_16x16x32_bf16 v[38:41], v[164:167], v[208:211], v[38:41]
	v_mfma_f32_16x16x32_bf16 v[34:37], v[172:175], v[208:211], v[34:37]
	v_mfma_f32_16x16x32_bf16 v[62:65], v[168:171], v[188:191], v[62:65]
	v_mfma_f32_16x16x32_bf16 v[58:61], v[180:183], v[188:191], v[58:61]
	v_mfma_f32_16x16x32_bf16 v[54:57], v[168:171], v[196:199], v[54:57]
	v_mfma_f32_16x16x32_bf16 v[50:53], v[180:183], v[196:199], v[50:53]
	v_mfma_f32_16x16x32_bf16 v[46:49], v[168:171], v[204:207], v[46:49]
	v_mfma_f32_16x16x32_bf16 v[42:45], v[180:183], v[204:207], v[42:45]
	v_mfma_f32_16x16x32_bf16 v[38:41], v[168:171], v[212:215], v[38:41]
	v_mfma_f32_16x16x32_bf16 v[34:37], v[180:183], v[212:215], v[34:37]
	s_barrier
; #define PG8_STAGE(bufoff, gbase, voff) do { _Pragma("unroll") for (int _i = 0; _i < 2; ++_i) \
;         __builtin_amdgcn_global_load_lds((const unsigned*)((const char*)(gbase) + (voff)[_i]), (LAS unsigned*)(lds + (bufoff) + ldsw + _i * 8192), 16, 0, 0); } while (0)
; #define PG8_LDA(dst, b, h) do { _Pragma("unroll") for (int m = 0; m < 4; ++m) _Pragma("unroll") for (int k = 0; k < 2; ++k) dst[m][k] = *(const LAS bf16x8*)(lds + PG8_SA(b, h) + aoff + m * 2048 + k * 1024); } while (0)
; #define PG8_MMA(ai, bj, At, Bt) do { __builtin_amdgcn_s_setprio(1); _Pragma("unroll") for (int m = 0; m < 4; ++m) _Pragma("unroll") for (int n = 0; n < 2; ++n) _Pragma("unroll") for (int k = 0; k < 2; ++k) \
;         acc[ai][bj][m][n] = __builtin_amdgcn_mfma_f32_16x16x32_bf16(Bt[n][k], At[m][k], acc[ai][bj][m][n], 0, 0, 0); __builtin_amdgcn_s_setprio(0); } while (0)
; #define PG8_WAIT_V(n) asm volatile("s_waitcnt vmcnt(" #n ")" ::: "memory")
; #define PG8_WAIT_L(n) asm volatile("s_waitcnt lgkmcnt(" #n ")" ::: "memory")
; #define PG8_BAR __builtin_amdgcn_s_barrier()
; #define PG8_SCHED __builtin_amdgcn_sched_barrier(0)
; template <class Epi, class Sched, int LDA, int LDB, bool ALIGN_EPI = true>
; __device__ __forceinline__ void gemm_phase(LAS unsigned char* lds, const Gemm g, const Sched& S, const Epi& E, int wave) {
;     ...
;             PG8_LDA(At, 1, 1); PG8_STAGE(PG8_SB(1, 0), b3, voffB); PG8_STAGE(PG8_SB(1, 1), b3 + hstepB, voffB); PG8_STAGE(PG8_SA(1, 0), a3, voffA);
;             PG8_WAIT_V(8); PG8_WAIT_L(0); PG8_BAR; PG8_MMA(1, 0, At, B0); PG8_MMA(1, 1, At, B1); PG8_BAR; PG8_SCHED;
;         }
	s_setprio 0
	ds_read_b128 v[184:187], v163 offset:49152
	ds_read_b128 v[188:191], v163 offset:50176
	ds_read_b128 v[192:195], v163 offset:51200
	ds_read_b128 v[196:199], v163 offset:52224
	ds_read_b128 v[200:203], v163 offset:53248
	ds_read_b128 v[204:207], v163 offset:54272
	ds_read_b128 v[208:211], v163 offset:55296
	ds_read_b128 v[212:215], v163 offset:56320
	s_add_i32 s0, s64, s61
	v_lshl_add_u64 v[216:217], v[216:217], 0, s[70:71]
	s_mov_b32 m0, s0
	s_nop 0
	global_load_lds_dwordx4 v[216:217], off
	s_add_i32 m0, s0, 0x2000
	s_add_u32 s0, s24, 0x80080
	v_lshl_add_u64 v[216:217], v[218:219], 0, s[70:71]
	s_addc_u32 s1, s25, 0
	s_add_i32 s24, s65, s61
	global_load_lds_dwordx4 v[216:217], off
	v_lshl_add_u64 v[216:217], s[0:1], 0, v[132:133]
	s_mov_b32 m0, s24
	s_nop 0
	global_load_lds_dwordx4 v[216:217], off
	v_lshl_add_u64 v[216:217], s[0:1], 0, v[136:137]
	s_add_i32 m0, s24, 0x2000
	s_nop 0
	global_load_lds_dwordx4 v[216:217], off
	v_lshl_add_u64 v[216:217], v[220:221], 0, s[70:71]
	s_mov_b32 m0, s38
	s_nop 0
	global_load_lds_dwordx4 v[216:217], off
	v_lshl_add_u64 v[216:217], v[222:223], 0, s[70:71]
	s_mov_b32 m0, s39
	s_nop 0
	global_load_lds_dwordx4 v[216:217], off
	s_waitcnt vmcnt(8)
	s_waitcnt lgkmcnt(0)
	s_setprio 1
	s_barrier
	v_mfma_f32_16x16x32_bf16 v[94:97], v[144:147], v[184:187], v[94:97]
	v_mfma_f32_16x16x32_bf16 v[90:93], v[152:155], v[184:187], v[90:93]
	v_mfma_f32_16x16x32_bf16 v[86:89], v[144:147], v[192:195], v[86:89]
	v_mfma_f32_16x16x32_bf16 v[82:85], v[152:155], v[192:195], v[82:85]
	v_mfma_f32_16x16x32_bf16 v[78:81], v[144:147], v[200:203], v[78:81]
	v_mfma_f32_16x16x32_bf16 v[74:77], v[152:155], v[200:203], v[74:77]
	v_mfma_f32_16x16x32_bf16 v[70:73], v[144:147], v[208:211], v[70:73]
	v_mfma_f32_16x16x32_bf16 v[66:69], v[152:155], v[208:211], v[66:69]
	v_mfma_f32_16x16x32_bf16 v[94:97], v[148:151], v[188:191], v[94:97]
	v_mfma_f32_16x16x32_bf16 v[90:93], v[156:159], v[188:191], v[90:93]
	v_mfma_f32_16x16x32_bf16 v[86:89], v[148:151], v[196:199], v[86:89]
	v_mfma_f32_16x16x32_bf16 v[82:85], v[156:159], v[196:199], v[82:85]
	v_mfma_f32_16x16x32_bf16 v[78:81], v[148:151], v[204:207], v[78:81]
	v_mfma_f32_16x16x32_bf16 v[74:77], v[156:159], v[204:207], v[74:77]
	v_mfma_f32_16x16x32_bf16 v[70:73], v[148:151], v[212:215], v[70:73]
	v_mfma_f32_16x16x32_bf16 v[66:69], v[156:159], v[212:215], v[66:69]
	v_mfma_f32_16x16x32_bf16 v[30:33], v[164:167], v[184:187], v[30:33]
	v_mfma_f32_16x16x32_bf16 v[26:29], v[172:175], v[184:187], v[26:29]
	v_mfma_f32_16x16x32_bf16 v[22:25], v[164:167], v[192:195], v[22:25]
	v_mfma_f32_16x16x32_bf16 v[18:21], v[172:175], v[192:195], v[18:21]
	v_mfma_f32_16x16x32_bf16 v[14:17], v[164:167], v[200:203], v[14:17]
	v_mfma_f32_16x16x32_bf16 v[10:13], v[172:175], v[200:203], v[10:13]
	v_mfma_f32_16x16x32_bf16 v[6:9], v[164:167], v[208:211], v[6:9]
	v_mfma_f32_16x16x32_bf16 v[2:5], v[172:175], v[208:211], v[2:5]
	v_mfma_f32_16x16x32_bf16 v[30:33], v[168:171], v[188:191], v[30:33]
	v_mfma_f32_16x16x32_bf16 v[26:29], v[180:183], v[188:191], v[26:29]
	v_mfma_f32_16x16x32_bf16 v[22:25], v[168:171], v[196:199], v[22:25]
	v_mfma_f32_16x16x32_bf16 v[18:21], v[180:183], v[196:199], v[18:21]
	v_mfma_f32_16x16x32_bf16 v[14:17], v[168:171], v[204:207], v[14:17]
	v_mfma_f32_16x16x32_bf16 v[10:13], v[180:183], v[204:207], v[10:13]
	v_mfma_f32_16x16x32_bf16 v[6:9], v[168:171], v[212:215], v[6:9]
	v_mfma_f32_16x16x32_bf16 v[2:5], v[180:183], v[212:215], v[2:5]
	s_barrier
	s_setprio 0
	s_add_i32 s59, s59, 2
	s_add_u32 s49, s49, 0x100
	s_addc_u32 s58, s58, 0
	s_cmp_gt_u32 s59, 29
	s_mov_b64 s[0:1], s[2:3]
	s_cbranch_scc0 .LBB0_2254
	v_readlane_b32 s0, v252, 14
	v_readlane_b32 s1, v252, 15
	s_and_b64 vcc, exec, s[0:1]
	s_cbranch_vccz .LBB0_2257
	s_barrier

; #define PG8_STAGE(bufoff, gbase, voff) do { _Pragma("unroll") for (int _i = 0; _i < 2; ++_i) \
;         __builtin_amdgcn_global_load_lds((const unsigned*)((const char*)(gbase) + (voff)[_i]), (LAS unsigned*)(lds + (bufoff) + ldsw + _i * 8192), 16, 0, 0); } while (0)
; #define PG8_LDA(dst, b, h) do { _Pragma("unroll") for (int m = 0; m < 4; ++m) _Pragma("unroll") for (int k = 0; k < 2; ++k) dst[m][k] = *(const LAS bf16x8*)(lds + PG8_SA(b, h) + aoff + m * 2048 + k * 1024); } while (0)
; #define PG8_LDB(dst, b, h) do { _Pragma("unroll") for (int n = 0; n < 2; ++n) _Pragma("unroll") for (int k = 0; k < 2; ++k) dst[n][k] = *(const LAS bf16x8*)(lds + PG8_SB(b, h) + boff + n * 2048 + k * 1024); } while (0)
; #define PG8_MMA(ai, bj, At, Bt) do { __builtin_amdgcn_s_setprio(1); _Pragma("unroll") for (int m = 0; m < 4; ++m) _Pragma("unroll") for (int n = 0; n < 2; ++n) _Pragma("unroll") for (int k = 0; k < 2; ++k) \
;         acc[ai][bj][m][n] = __builtin_amdgcn_mfma_f32_16x16x32_bf16(Bt[n][k], At[m][k], acc[ai][bj][m][n], 0, 0, 0); __builtin_amdgcn_s_setprio(0); } while (0)
; #define PG8_WAIT_V(n) asm volatile("s_waitcnt vmcnt(" #n ")" ::: "memory")
; #define PG8_WAIT_L(n) asm volatile("s_waitcnt lgkmcnt(" #n ")" ::: "memory")
; #define PG8_BAR __builtin_amdgcn_s_barrier()
; #define PG8_SCHED __builtin_amdgcn_sched_barrier(0)
; template <class Epi, class Sched, int LDA, int LDB, bool ALIGN_EPI = true>
; __device__ __forceinline__ void gemm_phase(LAS unsigned char* lds, const Gemm g, const Sched& S, const Epi& E, int wave) {
;     ...
;             PG8_LDB(B0, 0, 0); PG8_LDB(B1, 0, 1); PG8_SCHED; PG8_LDA(At, 0, 0); PG8_STAGE(PG8_SA(1, 1), a1 + hstepA, voffA);
;             PG8_WAIT_V(8); PG8_WAIT_L(0); PG8_BAR; PG8_MMA(0, 0, At, B0); PG8_MMA(0, 1, At, B1); PG8_BAR; PG8_SCHED;
;             PG8_LDA(At, 0, 1); PG8_STAGE(PG8_SB(0, 0), b2, voffB); PG8_STAGE(PG8_SB(0, 1), b2 + hstepB, voffB); PG8_STAGE(PG8_SA(0, 0), a2, voffA);
;             PG8_WAIT_V(8); PG8_WAIT_L(0); PG8_BAR; PG8_MMA(1, 0, At, B0); PG8_MMA(1, 1, At, B1); PG8_BAR; PG8_SCHED;
.LBB0_2415:
	ds_read_b128 v[184:187], v145
	ds_read_b128 v[188:191], v145 offset:1024
	ds_read_b128 v[192:195], v145 offset:2048
	ds_read_b128 v[196:199], v145 offset:3072
	ds_read_b128 v[200:203], v145 offset:4096
	ds_read_b128 v[204:207], v145 offset:5120
	ds_read_b128 v[208:211], v145 offset:6144
	ds_read_b128 v[212:215], v145 offset:7168
	s_add_u32 s12, s10, 0xfff80080
	s_addc_u32 s13, s11, -1
	s_add_i32 s39, 0, 0x10000
	s_cmp_eq_u32 s38, 28
	s_cselect_b32 s15, s1, s13
	s_cselect_b32 s14, s3, s12
	v_add_u32_e32 v140, s39, v143
	s_cselect_b32 s13, s7, s37
	s_cselect_b32 s12, s6, s36
	s_add_i32 s46, 0, 0x14000
	ds_read_b128 v[146:149], v140
	ds_read_b128 v[150:153], v140 offset:1024
	ds_read_b128 v[154:157], v140 offset:2048
	ds_read_b128 v[158:161], v140 offset:3072
	v_add_u32_e32 v140, s46, v143
	ds_read_b128 v[162:165], v140
	ds_read_b128 v[166:169], v140 offset:1024
	ds_read_b128 v[170:173], v140 offset:2048
	ds_read_b128 v[180:183], v140 offset:3072
	v_lshl_add_u64 v[140:141], s[10:11], 0, v[136:137]
	s_add_i32 m0, s18, 0xc000
	s_nop 0
	global_load_lds_dwordx4 v[140:141], off
	v_lshl_add_u64 v[140:141], s[10:11], 0, v[138:139]
	s_add_i32 m0, s18, 0xe000
	s_nop 0
	global_load_lds_dwordx4 v[140:141], off
	s_waitcnt vmcnt(8)
	s_waitcnt lgkmcnt(0)
	s_setprio 1
	s_barrier
	v_mfma_f32_16x16x32_bf16 v[126:129], v[146:149], v[184:187], v[126:129]
	v_mfma_f32_16x16x32_bf16 v[122:125], v[154:157], v[184:187], v[122:125]
	v_mfma_f32_16x16x32_bf16 v[114:117], v[146:149], v[192:195], v[114:117]
	v_mfma_f32_16x16x32_bf16 v[106:109], v[154:157], v[192:195], v[106:109]
	v_mfma_f32_16x16x32_bf16 v[98:101], v[146:149], v[200:203], v[98:101]
	v_mfma_f32_16x16x32_bf16 v[90:93], v[154:157], v[200:203], v[90:93]
	v_mfma_f32_16x16x32_bf16 v[82:85], v[146:149], v[208:211], v[82:85]
	v_mfma_f32_16x16x32_bf16 v[74:77], v[154:157], v[208:211], v[74:77]
	v_mfma_f32_16x16x32_bf16 v[126:129], v[150:153], v[188:191], v[126:129]
	v_mfma_f32_16x16x32_bf16 v[122:125], v[158:161], v[188:191], v[122:125]
	v_mfma_f32_16x16x32_bf16 v[114:117], v[150:153], v[196:199], v[114:117]
	v_mfma_f32_16x16x32_bf16 v[106:109], v[158:161], v[196:199], v[106:109]
	v_mfma_f32_16x16x32_bf16 v[98:101], v[150:153], v[204:207], v[98:101]
	v_mfma_f32_16x16x32_bf16 v[90:93], v[158:161], v[204:207], v[90:93]
	v_mfma_f32_16x16x32_bf16 v[82:85], v[150:153], v[212:215], v[82:85]
	v_mfma_f32_16x16x32_bf16 v[74:77], v[158:161], v[212:215], v[74:77]
	v_mfma_f32_16x16x32_bf16 v[118:121], v[162:165], v[184:187], v[118:121]
	v_mfma_f32_16x16x32_bf16 v[110:113], v[170:173], v[184:187], v[110:113]
	v_mfma_f32_16x16x32_bf16 v[102:105], v[162:165], v[192:195], v[102:105]
	v_mfma_f32_16x16x32_bf16 v[94:97], v[170:173], v[192:195], v[94:97]
	v_mfma_f32_16x16x32_bf16 v[86:89], v[162:165], v[200:203], v[86:89]
	v_mfma_f32_16x16x32_bf16 v[78:81], v[170:173], v[200:203], v[78:81]
	v_mfma_f32_16x16x32_bf16 v[70:73], v[162:165], v[208:211], v[70:73]
	v_mfma_f32_16x16x32_bf16 v[66:69], v[170:173], v[208:211], v[66:69]
	v_mfma_f32_16x16x32_bf16 v[118:121], v[166:169], v[188:191], v[118:121]
	v_mfma_f32_16x16x32_bf16 v[110:113], v[180:183], v[188:191], v[110:113]
	v_mfma_f32_16x16x32_bf16 v[102:105], v[166:169], v[196:199], v[102:105]
	v_mfma_f32_16x16x32_bf16 v[94:97], v[180:183], v[196:199], v[94:97]
	v_mfma_f32_16x16x32_bf16 v[86:89], v[166:169], v[204:207], v[86:89]
	v_mfma_f32_16x16x32_bf16 v[78:81], v[180:183], v[204:207], v[78:81]
	v_mfma_f32_16x16x32_bf16 v[70:73], v[166:169], v[212:215], v[70:73]
	v_mfma_f32_16x16x32_bf16 v[66:69], v[180:183], v[212:215], v[66:69]
	s_barrier
	s_setprio 0
	ds_read_b128 v[184:187], v145 offset:16384
	ds_read_b128 v[188:191], v145 offset:17408
	ds_read_b128 v[192:195], v145 offset:18432
	ds_read_b128 v[196:199], v145 offset:19456
	ds_read_b128 v[200:203], v145 offset:20480
	ds_read_b128 v[204:207], v145 offset:21504
	ds_read_b128 v[208:211], v145 offset:22528
	ds_read_b128 v[212:215], v145 offset:23552
	s_add_i32 s39, s39, s47
	v_lshl_add_u64 v[140:141], s[12:13], 0, v[0:1]
	s_mov_b32 m0, s39
	s_nop 0
	global_load_lds_dwordx4 v[140:141], off
	s_add_i32 m0, s39, 0x2000
	s_add_u32 s44, s12, 0x84000
	v_lshl_add_u64 v[174:175], s[12:13], 0, v[134:135]
	s_addc_u32 s45, s13, 0
	s_add_i32 s39, s46, s47
	global_load_lds_dwordx4 v[174:175], off
	v_lshl_add_u64 v[216:217], s[44:45], 0, v[0:1]
	s_mov_b32 m0, s39
	v_lshl_add_u64 v[218:219], s[14:15], 0, v[132:133]
	global_load_lds_dwordx4 v[216:217], off
	v_lshl_add_u64 v[216:217], s[44:45], 0, v[134:135]
	s_add_i32 m0, s39, 0x2000
	s_nop 0
	global_load_lds_dwordx4 v[216:217], off
	v_lshl_add_u64 v[216:217], s[14:15], 0, v[130:131]
	s_mov_b32 m0, s18
	s_nop 0
	global_load_lds_dwordx4 v[216:217], off
	s_mov_b32 m0, s19
	s_nop 0
	global_load_lds_dwordx4 v[218:219], off
	s_waitcnt vmcnt(8)
	s_waitcnt lgkmcnt(0)
	s_setprio 1
	s_barrier
; #define PG8_STAGE(bufoff, gbase, voff) do { _Pragma("unroll") for (int _i = 0; _i < 2; ++_i) \
;         __builtin_amdgcn_global_load_lds((const unsigned*)((const char*)(gbase) + (voff)[_i]), (LAS unsigned*)(lds + (bufoff) + ldsw + _i * 8192), 16, 0, 0); } while (0)
; #define PG8_LDA(dst, b, h) do { _Pragma("unroll") for (int m = 0; m < 4; ++m) _Pragma("unroll") for (int k = 0; k < 2; ++k) dst[m][k] = *(const LAS bf16x8*)(lds + PG8_SA(b, h) + aoff + m * 2048 + k * 1024); } while (0)
; #define PG8_LDB(dst, b, h) do { _Pragma("unroll") for (int n = 0; n < 2; ++n) _Pragma("unroll") for (int k = 0; k < 2; ++k) dst[n][k] = *(const LAS bf16x8*)(lds + PG8_SB(b, h) + boff + n * 2048 + k * 1024); } while (0)
; #define PG8_MMA(ai, bj, At, Bt) do { __builtin_amdgcn_s_setprio(1); _Pragma("unroll") for (int m = 0; m < 4; ++m) _Pragma("unroll") for (int n = 0; n < 2; ++n) _Pragma("unroll") for (int k = 0; k < 2; ++k) \
;         acc[ai][bj][m][n] = __builtin_amdgcn_mfma_f32_16x16x32_bf16(Bt[n][k], At[m][k], acc[ai][bj][m][n], 0, 0, 0); __builtin_amdgcn_s_setprio(0); } while (0)
; #define PG8_WAIT_V(n) asm volatile("s_waitcnt vmcnt(" #n ")" ::: "memory")
; #define PG8_WAIT_L(n) asm volatile("s_waitcnt lgkmcnt(" #n ")" ::: "memory")
; #define PG8_BAR __builtin_amdgcn_s_barrier()
; #define PG8_SCHED __builtin_amdgcn_sched_barrier(0)
; template <class Epi, class Sched, int LDA, int LDB, bool ALIGN_EPI = true>
; __device__ __forceinline__ void gemm_phase(LAS unsigned char* lds, const Gemm g, const Sched& S, const Epi& E, int wave) {
;     ...
;             PG8_WAIT_V(8); PG8_WAIT_L(0); PG8_BAR; PG8_MMA(1, 0, At, B0); PG8_MMA(1, 1, At, B1); PG8_BAR; PG8_SCHED;
;             PG8_LDB(B0, 1, 0); PG8_LDB(B1, 1, 1); PG8_SCHED; PG8_LDA(At, 1, 0); PG8_STAGE(PG8_SA(0, 1), a2 + hstepA, voffA);
;             PG8_WAIT_V(8); PG8_WAIT_L(0); PG8_BAR; PG8_MMA(0, 0, At, B0); PG8_MMA(0, 1, At, B1); PG8_BAR; PG8_SCHED;
	v_mfma_f32_16x16x32_bf16 v[62:65], v[146:149], v[184:187], v[62:65]
	v_mfma_f32_16x16x32_bf16 v[58:61], v[154:157], v[184:187], v[58:61]
	v_mfma_f32_16x16x32_bf16 v[50:53], v[146:149], v[192:195], v[50:53]
	v_mfma_f32_16x16x32_bf16 v[42:45], v[154:157], v[192:195], v[42:45]
	v_mfma_f32_16x16x32_bf16 v[34:37], v[146:149], v[200:203], v[34:37]
	v_mfma_f32_16x16x32_bf16 v[26:29], v[154:157], v[200:203], v[26:29]
	v_mfma_f32_16x16x32_bf16 v[18:21], v[146:149], v[208:211], v[18:21]
	v_mfma_f32_16x16x32_bf16 v[10:13], v[154:157], v[208:211], v[10:13]
	v_mfma_f32_16x16x32_bf16 v[62:65], v[150:153], v[188:191], v[62:65]
	v_mfma_f32_16x16x32_bf16 v[58:61], v[158:161], v[188:191], v[58:61]
	v_mfma_f32_16x16x32_bf16 v[50:53], v[150:153], v[196:199], v[50:53]
	v_mfma_f32_16x16x32_bf16 v[42:45], v[158:161], v[196:199], v[42:45]
	v_mfma_f32_16x16x32_bf16 v[34:37], v[150:153], v[204:207], v[34:37]
	v_mfma_f32_16x16x32_bf16 v[26:29], v[158:161], v[204:207], v[26:29]
	v_mfma_f32_16x16x32_bf16 v[18:21], v[150:153], v[212:215], v[18:21]
	v_mfma_f32_16x16x32_bf16 v[10:13], v[158:161], v[212:215], v[10:13]
	v_mfma_f32_16x16x32_bf16 v[54:57], v[162:165], v[184:187], v[54:57]
	v_mfma_f32_16x16x32_bf16 v[46:49], v[170:173], v[184:187], v[46:49]
	v_mfma_f32_16x16x32_bf16 v[38:41], v[162:165], v[192:195], v[38:41]
	v_mfma_f32_16x16x32_bf16 v[30:33], v[170:173], v[192:195], v[30:33]
	v_mfma_f32_16x16x32_bf16 v[22:25], v[162:165], v[200:203], v[22:25]
	v_mfma_f32_16x16x32_bf16 v[14:17], v[170:173], v[200:203], v[14:17]
	v_mfma_f32_16x16x32_bf16 v[6:9], v[162:165], v[208:211], v[6:9]
	v_mfma_f32_16x16x32_bf16 v[2:5], v[170:173], v[208:211], v[2:5]
	v_mfma_f32_16x16x32_bf16 v[54:57], v[166:169], v[188:191], v[54:57]
	v_mfma_f32_16x16x32_bf16 v[46:49], v[180:183], v[188:191], v[46:49]
	v_mfma_f32_16x16x32_bf16 v[38:41], v[166:169], v[196:199], v[38:41]
	v_mfma_f32_16x16x32_bf16 v[30:33], v[180:183], v[196:199], v[30:33]
	v_mfma_f32_16x16x32_bf16 v[22:25], v[166:169], v[204:207], v[22:25]
	v_mfma_f32_16x16x32_bf16 v[14:17], v[180:183], v[204:207], v[14:17]
	v_mfma_f32_16x16x32_bf16 v[6:9], v[166:169], v[212:215], v[6:9]
	v_mfma_f32_16x16x32_bf16 v[2:5], v[180:183], v[212:215], v[2:5]
	s_barrier
	s_setprio 0
	ds_read_b128 v[184:187], v145 offset:32768
	ds_read_b128 v[188:191], v145 offset:33792
	ds_read_b128 v[192:195], v145 offset:34816
	ds_read_b128 v[196:199], v145 offset:35840
	ds_read_b128 v[200:203], v145 offset:36864
	ds_read_b128 v[204:207], v145 offset:37888
	ds_read_b128 v[208:211], v145 offset:38912
	ds_read_b128 v[212:215], v145 offset:39936
	s_add_i32 s39, 0, 0x18000
	s_add_i32 s44, 0, 0x1c000
	v_add_u32_e32 v158, s39, v143
	v_add_u32_e32 v180, s44, v143
	ds_read_b128 v[146:149], v158
	ds_read_b128 v[150:153], v158 offset:1024
	ds_read_b128 v[154:157], v158 offset:2048
	ds_read_b128 v[158:161], v158 offset:3072
	ds_read_b128 v[162:165], v180
	ds_read_b128 v[166:169], v180 offset:1024
	ds_read_b128 v[170:173], v180 offset:2048
	ds_read_b128 v[180:183], v180 offset:3072
	s_add_u32 s14, s14, 0x80000
	s_addc_u32 s15, s15, 0
	s_mov_b32 m0, s24
	v_lshl_add_u64 v[220:221], s[14:15], 0, v[130:131]
	global_load_lds_dwordx4 v[220:221], off
	v_lshl_add_u64 v[220:221], s[14:15], 0, v[132:133]
	s_mov_b32 m0, s25
	s_nop 0
	global_load_lds_dwordx4 v[220:221], off
	s_waitcnt vmcnt(8)
	s_waitcnt lgkmcnt(0)
	s_setprio 1
	s_barrier
	v_mfma_f32_16x16x32_bf16 v[126:129], v[146:149], v[184:187], v[126:129]
	v_mfma_f32_16x16x32_bf16 v[122:125], v[154:157], v[184:187], v[122:125]
	v_mfma_f32_16x16x32_bf16 v[114:117], v[146:149], v[192:195], v[114:117]
	v_mfma_f32_16x16x32_bf16 v[106:109], v[154:157], v[192:195], v[106:109]
	v_mfma_f32_16x16x32_bf16 v[98:101], v[146:149], v[200:203], v[98:101]
	v_mfma_f32_16x16x32_bf16 v[90:93], v[154:157], v[200:203], v[90:93]
	v_mfma_f32_16x16x32_bf16 v[82:85], v[146:149], v[208:211], v[82:85]
	v_mfma_f32_16x16x32_bf16 v[74:77], v[154:157], v[208:211], v[74:77]
	v_mfma_f32_16x16x32_bf16 v[126:129], v[150:153], v[188:191], v[126:129]
	v_mfma_f32_16x16x32_bf16 v[122:125], v[158:161], v[188:191], v[122:125]
	v_mfma_f32_16x16x32_bf16 v[114:117], v[150:153], v[196:199], v[114:117]
	v_mfma_f32_16x16x32_bf16 v[106:109], v[158:161], v[196:199], v[106:109]
	v_mfma_f32_16x16x32_bf16 v[98:101], v[150:153], v[204:207], v[98:101]
	v_mfma_f32_16x16x32_bf16 v[90:93], v[158:161], v[204:207], v[90:93]
	v_mfma_f32_16x16x32_bf16 v[82:85], v[150:153], v[212:215], v[82:85]
	v_mfma_f32_16x16x32_bf16 v[74:77], v[158:161], v[212:215], v[74:77]
	v_mfma_f32_16x16x32_bf16 v[118:121], v[162:165], v[184:187], v[118:121]
	v_mfma_f32_16x16x32_bf16 v[110:113], v[170:173], v[184:187], v[110:113]
	v_mfma_f32_16x16x32_bf16 v[102:105], v[162:165], v[192:195], v[102:105]
	v_mfma_f32_16x16x32_bf16 v[94:97], v[170:173], v[192:195], v[94:97]
	v_mfma_f32_16x16x32_bf16 v[86:89], v[162:165], v[200:203], v[86:89]
	v_mfma_f32_16x16x32_bf16 v[78:81], v[170:173], v[200:203], v[78:81]
	v_mfma_f32_16x16x32_bf16 v[70:73], v[162:165], v[208:211], v[70:73]
	v_mfma_f32_16x16x32_bf16 v[66:69], v[170:173], v[208:211], v[66:69]
	v_mfma_f32_16x16x32_bf16 v[118:121], v[166:169], v[188:191], v[118:121]
	v_mfma_f32_16x16x32_bf16 v[110:113], v[180:183], v[188:191], v[110:113]
	v_mfma_f32_16x16x32_bf16 v[102:105], v[166:169], v[196:199], v[102:105]
	v_mfma_f32_16x16x32_bf16 v[94:97], v[180:183], v[196:199], v[94:97]
	v_mfma_f32_16x16x32_bf16 v[86:89], v[166:169], v[204:207], v[86:89]
	v_mfma_f32_16x16x32_bf16 v[78:81], v[180:183], v[204:207], v[78:81]
	v_mfma_f32_16x16x32_bf16 v[70:73], v[166:169], v[212:215], v[70:73]
	v_mfma_f32_16x16x32_bf16 v[66:69], v[180:183], v[212:215], v[66:69]
	s_barrier
; #define PG8_STAGE(bufoff, gbase, voff) do { _Pragma("unroll") for (int _i = 0; _i < 2; ++_i) \
;         __builtin_amdgcn_global_load_lds((const unsigned*)((const char*)(gbase) + (voff)[_i]), (LAS unsigned*)(lds + (bufoff) + ldsw + _i * 8192), 16, 0, 0); } while (0)
; #define PG8_LDA(dst, b, h) do { _Pragma("unroll") for (int m = 0; m < 4; ++m) _Pragma("unroll") for (int k = 0; k < 2; ++k) dst[m][k] = *(const LAS bf16x8*)(lds + PG8_SA(b, h) + aoff + m * 2048 + k * 1024); } while (0)
; #define PG8_MMA(ai, bj, At, Bt) do { __builtin_amdgcn_s_setprio(1); _Pragma("unroll") for (int m = 0; m < 4; ++m) _Pragma("unroll") for (int n = 0; n < 2; ++n) _Pragma("unroll") for (int k = 0; k < 2; ++k) \
;         acc[ai][bj][m][n] = __builtin_amdgcn_mfma_f32_16x16x32_bf16(Bt[n][k], At[m][k], acc[ai][bj][m][n], 0, 0, 0); __builtin_amdgcn_s_setprio(0); } while (0)
; #define PG8_WAIT_V(n) asm volatile("s_waitcnt vmcnt(" #n ")" ::: "memory")
; #define PG8_WAIT_L(n) asm volatile("s_waitcnt lgkmcnt(" #n ")" ::: "memory")
; #define PG8_BAR __builtin_amdgcn_s_barrier()
; #define PG8_SCHED __builtin_amdgcn_sched_barrier(0)
; template <class Epi, class Sched, int LDA, int LDB, bool ALIGN_EPI = true>
; __device__ __forceinline__ void gemm_phase(LAS unsigned char* lds, const Gemm g, const Sched& S, const Epi& E, int wave) {
;     ...
;             PG8_LDA(At, 1, 1); PG8_STAGE(PG8_SB(1, 0), b3, voffB); PG8_STAGE(PG8_SB(1, 1), b3 + hstepB, voffB); PG8_STAGE(PG8_SA(1, 0), a3, voffA);
;             PG8_WAIT_V(8); PG8_WAIT_L(0); PG8_BAR; PG8_MMA(1, 0, At, B0); PG8_MMA(1, 1, At, B1); PG8_BAR; PG8_SCHED;
;         }
	s_setprio 0
	ds_read_b128 v[184:187], v145 offset:49152
	ds_read_b128 v[188:191], v145 offset:50176
	ds_read_b128 v[192:195], v145 offset:51200
	ds_read_b128 v[196:199], v145 offset:52224
	ds_read_b128 v[200:203], v145 offset:53248
	ds_read_b128 v[204:207], v145 offset:54272
	ds_read_b128 v[208:211], v145 offset:55296
	ds_read_b128 v[212:215], v145 offset:56320
	s_add_i32 s14, s39, s47
	v_lshl_add_u64 v[140:141], v[140:141], 0, s[48:49]
	s_mov_b32 m0, s14
	s_nop 0
	global_load_lds_dwordx4 v[140:141], off
	s_add_i32 m0, s14, 0x2000
	s_add_u32 s12, s12, 0x84080
	v_lshl_add_u64 v[140:141], v[174:175], 0, s[48:49]
	s_addc_u32 s13, s13, 0
	s_add_i32 s14, s44, s47
	global_load_lds_dwordx4 v[140:141], off
	v_lshl_add_u64 v[140:141], s[12:13], 0, v[0:1]
	s_mov_b32 m0, s14
	s_nop 0
	global_load_lds_dwordx4 v[140:141], off
	v_lshl_add_u64 v[140:141], s[12:13], 0, v[134:135]
	s_add_i32 m0, s14, 0x2000
	s_nop 0
	global_load_lds_dwordx4 v[140:141], off
	v_lshl_add_u64 v[140:141], v[216:217], 0, s[48:49]
	s_mov_b32 m0, s26
	s_nop 0
	global_load_lds_dwordx4 v[140:141], off
	v_lshl_add_u64 v[140:141], v[218:219], 0, s[48:49]
	s_mov_b32 m0, s27
	s_nop 0
	global_load_lds_dwordx4 v[140:141], off
	s_waitcnt vmcnt(8)
	s_waitcnt lgkmcnt(0)
	s_setprio 1
	s_barrier
	v_mfma_f32_16x16x32_bf16 v[62:65], v[146:149], v[184:187], v[62:65]
	v_mfma_f32_16x16x32_bf16 v[58:61], v[154:157], v[184:187], v[58:61]
	v_mfma_f32_16x16x32_bf16 v[50:53], v[146:149], v[192:195], v[50:53]
	v_mfma_f32_16x16x32_bf16 v[42:45], v[154:157], v[192:195], v[42:45]
	v_mfma_f32_16x16x32_bf16 v[34:37], v[146:149], v[200:203], v[34:37]
	v_mfma_f32_16x16x32_bf16 v[26:29], v[154:157], v[200:203], v[26:29]
	v_mfma_f32_16x16x32_bf16 v[18:21], v[146:149], v[208:211], v[18:21]
	v_mfma_f32_16x16x32_bf16 v[10:13], v[154:157], v[208:211], v[10:13]
	v_mfma_f32_16x16x32_bf16 v[62:65], v[150:153], v[188:191], v[62:65]
	v_mfma_f32_16x16x32_bf16 v[58:61], v[158:161], v[188:191], v[58:61]
	v_mfma_f32_16x16x32_bf16 v[50:53], v[150:153], v[196:199], v[50:53]
	v_mfma_f32_16x16x32_bf16 v[42:45], v[158:161], v[196:199], v[42:45]
	v_mfma_f32_16x16x32_bf16 v[34:37], v[150:153], v[204:207], v[34:37]
	v_mfma_f32_16x16x32_bf16 v[26:29], v[158:161], v[204:207], v[26:29]
	v_mfma_f32_16x16x32_bf16 v[18:21], v[150:153], v[212:215], v[18:21]
	v_mfma_f32_16x16x32_bf16 v[10:13], v[158:161], v[212:215], v[10:13]
	v_mfma_f32_16x16x32_bf16 v[54:57], v[162:165], v[184:187], v[54:57]
	v_mfma_f32_16x16x32_bf16 v[46:49], v[170:173], v[184:187], v[46:49]
	v_mfma_f32_16x16x32_bf16 v[38:41], v[162:165], v[192:195], v[38:41]
	v_mfma_f32_16x16x32_bf16 v[30:33], v[170:173], v[192:195], v[30:33]
	v_mfma_f32_16x16x32_bf16 v[22:25], v[162:165], v[200:203], v[22:25]
	v_mfma_f32_16x16x32_bf16 v[14:17], v[170:173], v[200:203], v[14:17]
	v_mfma_f32_16x16x32_bf16 v[6:9], v[162:165], v[208:211], v[6:9]
	v_mfma_f32_16x16x32_bf16 v[2:5], v[170:173], v[208:211], v[2:5]
	v_mfma_f32_16x16x32_bf16 v[54:57], v[166:169], v[188:191], v[54:57]
	v_mfma_f32_16x16x32_bf16 v[46:49], v[180:183], v[188:191], v[46:49]
	v_mfma_f32_16x16x32_bf16 v[38:41], v[166:169], v[196:199], v[38:41]
	v_mfma_f32_16x16x32_bf16 v[30:33], v[180:183], v[196:199], v[30:33]
	v_mfma_f32_16x16x32_bf16 v[22:25], v[166:169], v[204:207], v[22:25]
	v_mfma_f32_16x16x32_bf16 v[14:17], v[180:183], v[204:207], v[14:17]
	v_mfma_f32_16x16x32_bf16 v[6:9], v[166:169], v[212:215], v[6:9]
	v_mfma_f32_16x16x32_bf16 v[2:5], v[180:183], v[212:215], v[2:5]
	s_barrier
	s_setprio 0
	s_add_i32 s38, s38, 2
	s_add_u32 s10, s10, 0x100
	s_addc_u32 s11, s11, 0
	s_add_u32 s36, s36, 0x100
	s_addc_u32 s37, s37, 0
	s_cmp_gt_u32 s38, 29
	s_cbranch_scc0 .LBB0_2415
	v_readlane_b32 s10, v252, 14
	v_readlane_b32 s11, v252, 15
	s_and_b64 vcc, exec, s[10:11]
	s_cbranch_vccz .LBB0_2418
	s_barrier

; #define PG8_STAGE(bufoff, gbase, voff) do { _Pragma("unroll") for (int _i = 0; _i < 2; ++_i) \
;         __builtin_amdgcn_global_load_lds((const unsigned*)((const char*)(gbase) + (voff)[_i]), (LAS unsigned*)(lds + (bufoff) + ldsw + _i * 8192), 16, 0, 0); } while (0)
; #define PG8_LDA(dst, b, h) do { _Pragma("unroll") for (int m = 0; m < 4; ++m) _Pragma("unroll") for (int k = 0; k < 2; ++k) dst[m][k] = *(const LAS bf16x8*)(lds + PG8_SA(b, h) + aoff + m * 2048 + k * 1024); } while (0)
; #define PG8_LDB(dst, b, h) do { _Pragma("unroll") for (int n = 0; n < 2; ++n) _Pragma("unroll") for (int k = 0; k < 2; ++k) dst[n][k] = *(const LAS bf16x8*)(lds + PG8_SB(b, h) + boff + n * 2048 + k * 1024); } while (0)
; #define PG8_MMA(ai, bj, At, Bt) do { __builtin_amdgcn_s_setprio(1); _Pragma("unroll") for (int m = 0; m < 4; ++m) _Pragma("unroll") for (int n = 0; n < 2; ++n) _Pragma("unroll") for (int k = 0; k < 2; ++k) \
;         acc[ai][bj][m][n] = __builtin_amdgcn_mfma_f32_16x16x32_bf16(Bt[n][k], At[m][k], acc[ai][bj][m][n], 0, 0, 0); __builtin_amdgcn_s_setprio(0); } while (0)
; #define PG8_WAIT_V(n) asm volatile("s_waitcnt vmcnt(" #n ")" ::: "memory")
; #define PG8_WAIT_L(n) asm volatile("s_waitcnt lgkmcnt(" #n ")" ::: "memory")
; #define PG8_BAR __builtin_amdgcn_s_barrier()
; #define PG8_SCHED __builtin_amdgcn_sched_barrier(0)
; template <class Epi, class Sched, int LDA, int LDB, bool ALIGN_EPI = true>
; __device__ __forceinline__ void gemm_phase(LAS unsigned char* lds, const Gemm g, const Sched& S, const Epi& E, int wave) {
;     ...
;             PG8_LDB(B0, 0, 0); PG8_LDB(B1, 0, 1); PG8_SCHED; PG8_LDA(At, 0, 0); PG8_STAGE(PG8_SA(1, 1), a1 + hstepA, voffA);
;             PG8_WAIT_V(8); PG8_WAIT_L(0); PG8_BAR; PG8_MMA(0, 0, At, B0); PG8_MMA(0, 1, At, B1); PG8_BAR; PG8_SCHED;
;             PG8_LDA(At, 0, 1); PG8_STAGE(PG8_SB(0, 0), b2, voffB); PG8_STAGE(PG8_SB(0, 1), b2 + hstepB, voffB); PG8_STAGE(PG8_SA(0, 0), a2, voffA);
;             PG8_WAIT_V(8); PG8_WAIT_L(0); PG8_BAR; PG8_MMA(1, 0, At, B0); PG8_MMA(1, 1, At, B1); PG8_BAR; PG8_SCHED;
.LBB0_2513:
	ds_read_b128 v[184:187], v145
	ds_read_b128 v[188:191], v145 offset:1024
	ds_read_b128 v[192:195], v145 offset:2048
	ds_read_b128 v[196:199], v145 offset:3072
	ds_read_b128 v[200:203], v145 offset:4096
	ds_read_b128 v[204:207], v145 offset:5120
	ds_read_b128 v[208:211], v145 offset:6144
	ds_read_b128 v[212:215], v145 offset:7168
	s_add_u32 s14, s12, 0xfff80080
	s_addc_u32 s15, s13, -1
	s_add_i32 s44, 0, 0x10000
	s_cmp_eq_u32 s39, 28
	s_cselect_b32 s17, s1, s15
	s_cselect_b32 s16, s3, s14
	v_add_u32_e32 v140, s44, v143
	s_cselect_b32 s15, s9, s38
	s_cselect_b32 s14, s8, s37
	s_add_i32 s46, 0, 0x14000
	ds_read_b128 v[146:149], v140
	ds_read_b128 v[150:153], v140 offset:1024
	ds_read_b128 v[154:157], v140 offset:2048
	ds_read_b128 v[158:161], v140 offset:3072
	v_add_u32_e32 v140, s46, v143
	ds_read_b128 v[162:165], v140
	ds_read_b128 v[166:169], v140 offset:1024
	ds_read_b128 v[170:173], v140 offset:2048
	ds_read_b128 v[180:183], v140 offset:3072
	v_lshl_add_u64 v[140:141], s[12:13], 0, v[136:137]
	s_add_i32 m0, s24, 0xc000
	s_nop 0
	global_load_lds_dwordx4 v[140:141], off
	v_lshl_add_u64 v[140:141], s[12:13], 0, v[138:139]
	s_add_i32 m0, s24, 0xe000
	s_nop 0
	global_load_lds_dwordx4 v[140:141], off
	s_waitcnt vmcnt(8)
	s_waitcnt lgkmcnt(0)
	s_setprio 1
	s_barrier
	v_mfma_f32_16x16x32_bf16 v[126:129], v[146:149], v[184:187], v[126:129]
	v_mfma_f32_16x16x32_bf16 v[122:125], v[154:157], v[184:187], v[122:125]
	v_mfma_f32_16x16x32_bf16 v[114:117], v[146:149], v[192:195], v[114:117]
	v_mfma_f32_16x16x32_bf16 v[106:109], v[154:157], v[192:195], v[106:109]
	v_mfma_f32_16x16x32_bf16 v[98:101], v[146:149], v[200:203], v[98:101]
	v_mfma_f32_16x16x32_bf16 v[90:93], v[154:157], v[200:203], v[90:93]
	v_mfma_f32_16x16x32_bf16 v[82:85], v[146:149], v[208:211], v[82:85]
	v_mfma_f32_16x16x32_bf16 v[74:77], v[154:157], v[208:211], v[74:77]
	v_mfma_f32_16x16x32_bf16 v[126:129], v[150:153], v[188:191], v[126:129]
	v_mfma_f32_16x16x32_bf16 v[122:125], v[158:161], v[188:191], v[122:125]
	v_mfma_f32_16x16x32_bf16 v[114:117], v[150:153], v[196:199], v[114:117]
	v_mfma_f32_16x16x32_bf16 v[106:109], v[158:161], v[196:199], v[106:109]
	v_mfma_f32_16x16x32_bf16 v[98:101], v[150:153], v[204:207], v[98:101]
	v_mfma_f32_16x16x32_bf16 v[90:93], v[158:161], v[204:207], v[90:93]
	v_mfma_f32_16x16x32_bf16 v[82:85], v[150:153], v[212:215], v[82:85]
	v_mfma_f32_16x16x32_bf16 v[74:77], v[158:161], v[212:215], v[74:77]
	v_mfma_f32_16x16x32_bf16 v[118:121], v[162:165], v[184:187], v[118:121]
	v_mfma_f32_16x16x32_bf16 v[110:113], v[170:173], v[184:187], v[110:113]
	v_mfma_f32_16x16x32_bf16 v[102:105], v[162:165], v[192:195], v[102:105]
	v_mfma_f32_16x16x32_bf16 v[94:97], v[170:173], v[192:195], v[94:97]
	v_mfma_f32_16x16x32_bf16 v[86:89], v[162:165], v[200:203], v[86:89]
	v_mfma_f32_16x16x32_bf16 v[78:81], v[170:173], v[200:203], v[78:81]
	v_mfma_f32_16x16x32_bf16 v[70:73], v[162:165], v[208:211], v[70:73]
	v_mfma_f32_16x16x32_bf16 v[66:69], v[170:173], v[208:211], v[66:69]
	v_mfma_f32_16x16x32_bf16 v[118:121], v[166:169], v[188:191], v[118:121]
	v_mfma_f32_16x16x32_bf16 v[110:113], v[180:183], v[188:191], v[110:113]
	v_mfma_f32_16x16x32_bf16 v[102:105], v[166:169], v[196:199], v[102:105]
	v_mfma_f32_16x16x32_bf16 v[94:97], v[180:183], v[196:199], v[94:97]
	v_mfma_f32_16x16x32_bf16 v[86:89], v[166:169], v[204:207], v[86:89]
	v_mfma_f32_16x16x32_bf16 v[78:81], v[180:183], v[204:207], v[78:81]
	v_mfma_f32_16x16x32_bf16 v[70:73], v[166:169], v[212:215], v[70:73]
	v_mfma_f32_16x16x32_bf16 v[66:69], v[180:183], v[212:215], v[66:69]
	s_barrier
	s_setprio 0
	ds_read_b128 v[184:187], v145 offset:16384
	ds_read_b128 v[188:191], v145 offset:17408
	ds_read_b128 v[192:195], v145 offset:18432
	ds_read_b128 v[196:199], v145 offset:19456
	ds_read_b128 v[200:203], v145 offset:20480
	ds_read_b128 v[204:207], v145 offset:21504
	ds_read_b128 v[208:211], v145 offset:22528
	ds_read_b128 v[212:215], v145 offset:23552
	s_add_i32 s44, s44, s47
	v_lshl_add_u64 v[140:141], s[14:15], 0, v[0:1]
	s_mov_b32 m0, s44
	s_nop 0
	global_load_lds_dwordx4 v[140:141], off
	s_add_i32 m0, s44, 0x2000
	s_add_u32 s44, s14, 0x84000
	v_lshl_add_u64 v[174:175], s[14:15], 0, v[134:135]
	s_addc_u32 s45, s15, 0
	s_add_i32 s46, s46, s47
	global_load_lds_dwordx4 v[174:175], off
	v_lshl_add_u64 v[216:217], s[44:45], 0, v[0:1]
	s_mov_b32 m0, s46
	v_lshl_add_u64 v[218:219], s[16:17], 0, v[132:133]
	global_load_lds_dwordx4 v[216:217], off
	v_lshl_add_u64 v[216:217], s[44:45], 0, v[134:135]
	s_add_i32 m0, s46, 0x2000
	s_nop 0
	global_load_lds_dwordx4 v[216:217], off
	v_lshl_add_u64 v[216:217], s[16:17], 0, v[130:131]
	s_mov_b32 m0, s24
	s_nop 0
	global_load_lds_dwordx4 v[216:217], off
	s_mov_b32 m0, s25
	s_nop 0
	global_load_lds_dwordx4 v[218:219], off
	s_waitcnt vmcnt(8)
	s_waitcnt lgkmcnt(0)
	s_setprio 1
	s_barrier
; #define PG8_STAGE(bufoff, gbase, voff) do { _Pragma("unroll") for (int _i = 0; _i < 2; ++_i) \
;         __builtin_amdgcn_global_load_lds((const unsigned*)((const char*)(gbase) + (voff)[_i]), (LAS unsigned*)(lds + (bufoff) + ldsw + _i * 8192), 16, 0, 0); } while (0)
; #define PG8_LDA(dst, b, h) do { _Pragma("unroll") for (int m = 0; m < 4; ++m) _Pragma("unroll") for (int k = 0; k < 2; ++k) dst[m][k] = *(const LAS bf16x8*)(lds + PG8_SA(b, h) + aoff + m * 2048 + k * 1024); } while (0)
; #define PG8_LDB(dst, b, h) do { _Pragma("unroll") for (int n = 0; n < 2; ++n) _Pragma("unroll") for (int k = 0; k < 2; ++k) dst[n][k] = *(const LAS bf16x8*)(lds + PG8_SB(b, h) + boff + n * 2048 + k * 1024); } while (0)
; #define PG8_MMA(ai, bj, At, Bt) do { __builtin_amdgcn_s_setprio(1); _Pragma("unroll") for (int m = 0; m < 4; ++m) _Pragma("unroll") for (int n = 0; n < 2; ++n) _Pragma("unroll") for (int k = 0; k < 2; ++k) \
;         acc[ai][bj][m][n] = __builtin_amdgcn_mfma_f32_16x16x32_bf16(Bt[n][k], At[m][k], acc[ai][bj][m][n], 0, 0, 0); __builtin_amdgcn_s_setprio(0); } while (0)
; #define PG8_WAIT_V(n) asm volatile("s_waitcnt vmcnt(" #n ")" ::: "memory")
; #define PG8_WAIT_L(n) asm volatile("s_waitcnt lgkmcnt(" #n ")" ::: "memory")
; #define PG8_BAR __builtin_amdgcn_s_barrier()
; #define PG8_SCHED __builtin_amdgcn_sched_barrier(0)
; template <class Epi, class Sched, int LDA, int LDB, bool ALIGN_EPI = true>
; __device__ __forceinline__ void gemm_phase(LAS unsigned char* lds, const Gemm g, const Sched& S, const Epi& E, int wave) {
;     ...
;             PG8_WAIT_V(8); PG8_WAIT_L(0); PG8_BAR; PG8_MMA(1, 0, At, B0); PG8_MMA(1, 1, At, B1); PG8_BAR; PG8_SCHED;
;             PG8_LDB(B0, 1, 0); PG8_LDB(B1, 1, 1); PG8_SCHED; PG8_LDA(At, 1, 0); PG8_STAGE(PG8_SA(0, 1), a2 + hstepA, voffA);
;             PG8_WAIT_V(8); PG8_WAIT_L(0); PG8_BAR; PG8_MMA(0, 0, At, B0); PG8_MMA(0, 1, At, B1); PG8_BAR; PG8_SCHED;
	v_mfma_f32_16x16x32_bf16 v[62:65], v[146:149], v[184:187], v[62:65]
	v_mfma_f32_16x16x32_bf16 v[58:61], v[154:157], v[184:187], v[58:61]
	v_mfma_f32_16x16x32_bf16 v[50:53], v[146:149], v[192:195], v[50:53]
	v_mfma_f32_16x16x32_bf16 v[42:45], v[154:157], v[192:195], v[42:45]
	v_mfma_f32_16x16x32_bf16 v[34:37], v[146:149], v[200:203], v[34:37]
	v_mfma_f32_16x16x32_bf16 v[26:29], v[154:157], v[200:203], v[26:29]
	v_mfma_f32_16x16x32_bf16 v[18:21], v[146:149], v[208:211], v[18:21]
	v_mfma_f32_16x16x32_bf16 v[10:13], v[154:157], v[208:211], v[10:13]
	v_mfma_f32_16x16x32_bf16 v[62:65], v[150:153], v[188:191], v[62:65]
	v_mfma_f32_16x16x32_bf16 v[58:61], v[158:161], v[188:191], v[58:61]
	v_mfma_f32_16x16x32_bf16 v[50:53], v[150:153], v[196:199], v[50:53]
	v_mfma_f32_16x16x32_bf16 v[42:45], v[158:161], v[196:199], v[42:45]
	v_mfma_f32_16x16x32_bf16 v[34:37], v[150:153], v[204:207], v[34:37]
	v_mfma_f32_16x16x32_bf16 v[26:29], v[158:161], v[204:207], v[26:29]
	v_mfma_f32_16x16x32_bf16 v[18:21], v[150:153], v[212:215], v[18:21]
	v_mfma_f32_16x16x32_bf16 v[10:13], v[158:161], v[212:215], v[10:13]
	v_mfma_f32_16x16x32_bf16 v[54:57], v[162:165], v[184:187], v[54:57]
	v_mfma_f32_16x16x32_bf16 v[46:49], v[170:173], v[184:187], v[46:49]
	v_mfma_f32_16x16x32_bf16 v[38:41], v[162:165], v[192:195], v[38:41]
	v_mfma_f32_16x16x32_bf16 v[30:33], v[170:173], v[192:195], v[30:33]
	v_mfma_f32_16x16x32_bf16 v[22:25], v[162:165], v[200:203], v[22:25]
	v_mfma_f32_16x16x32_bf16 v[14:17], v[170:173], v[200:203], v[14:17]
	v_mfma_f32_16x16x32_bf16 v[6:9], v[162:165], v[208:211], v[6:9]
	v_mfma_f32_16x16x32_bf16 v[2:5], v[170:173], v[208:211], v[2:5]
	v_mfma_f32_16x16x32_bf16 v[54:57], v[166:169], v[188:191], v[54:57]
	v_mfma_f32_16x16x32_bf16 v[46:49], v[180:183], v[188:191], v[46:49]
	v_mfma_f32_16x16x32_bf16 v[38:41], v[166:169], v[196:199], v[38:41]
	v_mfma_f32_16x16x32_bf16 v[30:33], v[180:183], v[196:199], v[30:33]
	v_mfma_f32_16x16x32_bf16 v[22:25], v[166:169], v[204:207], v[22:25]
	v_mfma_f32_16x16x32_bf16 v[14:17], v[180:183], v[204:207], v[14:17]
	v_mfma_f32_16x16x32_bf16 v[6:9], v[166:169], v[212:215], v[6:9]
	v_mfma_f32_16x16x32_bf16 v[2:5], v[180:183], v[212:215], v[2:5]
	s_barrier
	s_setprio 0
	ds_read_b128 v[184:187], v145 offset:32768
	ds_read_b128 v[188:191], v145 offset:33792
	ds_read_b128 v[192:195], v145 offset:34816
	ds_read_b128 v[196:199], v145 offset:35840
	ds_read_b128 v[200:203], v145 offset:36864
	ds_read_b128 v[204:207], v145 offset:37888
	ds_read_b128 v[208:211], v145 offset:38912
	ds_read_b128 v[212:215], v145 offset:39936
	s_add_i32 s44, 0, 0x18000
	s_add_i32 s45, 0, 0x1c000
	v_add_u32_e32 v158, s44, v143
	v_add_u32_e32 v180, s45, v143
	ds_read_b128 v[146:149], v158
	ds_read_b128 v[150:153], v158 offset:1024
	ds_read_b128 v[154:157], v158 offset:2048
	ds_read_b128 v[158:161], v158 offset:3072
	ds_read_b128 v[162:165], v180
	ds_read_b128 v[166:169], v180 offset:1024
	ds_read_b128 v[170:173], v180 offset:2048
	ds_read_b128 v[180:183], v180 offset:3072
	s_add_u32 s16, s16, 0x80000
	s_addc_u32 s17, s17, 0
	s_mov_b32 m0, s26
	v_lshl_add_u64 v[220:221], s[16:17], 0, v[130:131]
	global_load_lds_dwordx4 v[220:221], off
	v_lshl_add_u64 v[220:221], s[16:17], 0, v[132:133]
	s_mov_b32 m0, s27
	s_nop 0
	global_load_lds_dwordx4 v[220:221], off
	s_waitcnt vmcnt(8)
	s_waitcnt lgkmcnt(0)
	s_setprio 1
	s_barrier
	v_mfma_f32_16x16x32_bf16 v[126:129], v[146:149], v[184:187], v[126:129]
	v_mfma_f32_16x16x32_bf16 v[122:125], v[154:157], v[184:187], v[122:125]
	v_mfma_f32_16x16x32_bf16 v[114:117], v[146:149], v[192:195], v[114:117]
	v_mfma_f32_16x16x32_bf16 v[106:109], v[154:157], v[192:195], v[106:109]
	v_mfma_f32_16x16x32_bf16 v[98:101], v[146:149], v[200:203], v[98:101]
	v_mfma_f32_16x16x32_bf16 v[90:93], v[154:157], v[200:203], v[90:93]
	v_mfma_f32_16x16x32_bf16 v[82:85], v[146:149], v[208:211], v[82:85]
	v_mfma_f32_16x16x32_bf16 v[74:77], v[154:157], v[208:211], v[74:77]
	v_mfma_f32_16x16x32_bf16 v[126:129], v[150:153], v[188:191], v[126:129]
	v_mfma_f32_16x16x32_bf16 v[122:125], v[158:161], v[188:191], v[122:125]
	v_mfma_f32_16x16x32_bf16 v[114:117], v[150:153], v[196:199], v[114:117]
	v_mfma_f32_16x16x32_bf16 v[106:109], v[158:161], v[196:199], v[106:109]
	v_mfma_f32_16x16x32_bf16 v[98:101], v[150:153], v[204:207], v[98:101]
	v_mfma_f32_16x16x32_bf16 v[90:93], v[158:161], v[204:207], v[90:93]
	v_mfma_f32_16x16x32_bf16 v[82:85], v[150:153], v[212:215], v[82:85]
	v_mfma_f32_16x16x32_bf16 v[74:77], v[158:161], v[212:215], v[74:77]
	v_mfma_f32_16x16x32_bf16 v[118:121], v[162:165], v[184:187], v[118:121]
	v_mfma_f32_16x16x32_bf16 v[110:113], v[170:173], v[184:187], v[110:113]
	v_mfma_f32_16x16x32_bf16 v[102:105], v[162:165], v[192:195], v[102:105]
	v_mfma_f32_16x16x32_bf16 v[94:97], v[170:173], v[192:195], v[94:97]
	v_mfma_f32_16x16x32_bf16 v[86:89], v[162:165], v[200:203], v[86:89]
	v_mfma_f32_16x16x32_bf16 v[78:81], v[170:173], v[200:203], v[78:81]
	v_mfma_f32_16x16x32_bf16 v[70:73], v[162:165], v[208:211], v[70:73]
	v_mfma_f32_16x16x32_bf16 v[66:69], v[170:173], v[208:211], v[66:69]
	v_mfma_f32_16x16x32_bf16 v[118:121], v[166:169], v[188:191], v[118:121]
	v_mfma_f32_16x16x32_bf16 v[110:113], v[180:183], v[188:191], v[110:113]
	v_mfma_f32_16x16x32_bf16 v[102:105], v[166:169], v[196:199], v[102:105]
	v_mfma_f32_16x16x32_bf16 v[94:97], v[180:183], v[196:199], v[94:97]
	v_mfma_f32_16x16x32_bf16 v[86:89], v[166:169], v[204:207], v[86:89]
	v_mfma_f32_16x16x32_bf16 v[78:81], v[180:183], v[204:207], v[78:81]
	v_mfma_f32_16x16x32_bf16 v[70:73], v[166:169], v[212:215], v[70:73]
	v_mfma_f32_16x16x32_bf16 v[66:69], v[180:183], v[212:215], v[66:69]
	s_barrier
; #define PG8_STAGE(bufoff, gbase, voff) do { _Pragma("unroll") for (int _i = 0; _i < 2; ++_i) \
;         __builtin_amdgcn_global_load_lds((const unsigned*)((const char*)(gbase) + (voff)[_i]), (LAS unsigned*)(lds + (bufoff) + ldsw + _i * 8192), 16, 0, 0); } while (0)
; #define PG8_LDA(dst, b, h) do { _Pragma("unroll") for (int m = 0; m < 4; ++m) _Pragma("unroll") for (int k = 0; k < 2; ++k) dst[m][k] = *(const LAS bf16x8*)(lds + PG8_SA(b, h) + aoff + m * 2048 + k * 1024); } while (0)
; #define PG8_MMA(ai, bj, At, Bt) do { __builtin_amdgcn_s_setprio(1); _Pragma("unroll") for (int m = 0; m < 4; ++m) _Pragma("unroll") for (int n = 0; n < 2; ++n) _Pragma("unroll") for (int k = 0; k < 2; ++k) \
;         acc[ai][bj][m][n] = __builtin_amdgcn_mfma_f32_16x16x32_bf16(Bt[n][k], At[m][k], acc[ai][bj][m][n], 0, 0, 0); __builtin_amdgcn_s_setprio(0); } while (0)
; #define PG8_WAIT_V(n) asm volatile("s_waitcnt vmcnt(" #n ")" ::: "memory")
; #define PG8_WAIT_L(n) asm volatile("s_waitcnt lgkmcnt(" #n ")" ::: "memory")
; #define PG8_BAR __builtin_amdgcn_s_barrier()
; #define PG8_SCHED __builtin_amdgcn_sched_barrier(0)
; template <class Epi, class Sched, int LDA, int LDB, bool ALIGN_EPI = true>
; __device__ __forceinline__ void gemm_phase(LAS unsigned char* lds, const Gemm g, const Sched& S, const Epi& E, int wave) {
;     ...
;             PG8_LDA(At, 1, 1); PG8_STAGE(PG8_SB(1, 0), b3, voffB); PG8_STAGE(PG8_SB(1, 1), b3 + hstepB, voffB); PG8_STAGE(PG8_SA(1, 0), a3, voffA);
;             PG8_WAIT_V(8); PG8_WAIT_L(0); PG8_BAR; PG8_MMA(1, 0, At, B0); PG8_MMA(1, 1, At, B1); PG8_BAR; PG8_SCHED;
;         }
	s_setprio 0
	ds_read_b128 v[184:187], v145 offset:49152
	ds_read_b128 v[188:191], v145 offset:50176
	ds_read_b128 v[192:195], v145 offset:51200
	ds_read_b128 v[196:199], v145 offset:52224
	ds_read_b128 v[200:203], v145 offset:53248
	ds_read_b128 v[204:207], v145 offset:54272
	ds_read_b128 v[208:211], v145 offset:55296
	ds_read_b128 v[212:215], v145 offset:56320
	s_add_i32 s16, s44, s47
	v_lshl_add_u64 v[140:141], v[140:141], 0, s[72:73]
	s_mov_b32 m0, s16
	s_nop 0
	global_load_lds_dwordx4 v[140:141], off
	s_add_i32 m0, s16, 0x2000
	s_add_u32 s14, s14, 0x84080
	v_lshl_add_u64 v[140:141], v[174:175], 0, s[72:73]
	s_addc_u32 s15, s15, 0
	s_add_i32 s16, s45, s47
	global_load_lds_dwordx4 v[140:141], off
	v_lshl_add_u64 v[140:141], s[14:15], 0, v[0:1]
	s_mov_b32 m0, s16
	s_nop 0
	global_load_lds_dwordx4 v[140:141], off
	v_lshl_add_u64 v[140:141], s[14:15], 0, v[134:135]
	s_add_i32 m0, s16, 0x2000
	s_nop 0
	global_load_lds_dwordx4 v[140:141], off
	v_lshl_add_u64 v[140:141], v[216:217], 0, s[72:73]
	s_mov_b32 m0, s28
	s_nop 0
	global_load_lds_dwordx4 v[140:141], off
	v_lshl_add_u64 v[140:141], v[218:219], 0, s[72:73]
	s_mov_b32 m0, s29
	s_nop 0
	global_load_lds_dwordx4 v[140:141], off
	s_waitcnt vmcnt(8)
	s_waitcnt lgkmcnt(0)
	s_setprio 1
	s_barrier
	v_mfma_f32_16x16x32_bf16 v[62:65], v[146:149], v[184:187], v[62:65]
	v_mfma_f32_16x16x32_bf16 v[58:61], v[154:157], v[184:187], v[58:61]
	v_mfma_f32_16x16x32_bf16 v[50:53], v[146:149], v[192:195], v[50:53]
	v_mfma_f32_16x16x32_bf16 v[42:45], v[154:157], v[192:195], v[42:45]
	v_mfma_f32_16x16x32_bf16 v[34:37], v[146:149], v[200:203], v[34:37]
	v_mfma_f32_16x16x32_bf16 v[26:29], v[154:157], v[200:203], v[26:29]
	v_mfma_f32_16x16x32_bf16 v[18:21], v[146:149], v[208:211], v[18:21]
	v_mfma_f32_16x16x32_bf16 v[10:13], v[154:157], v[208:211], v[10:13]
	v_mfma_f32_16x16x32_bf16 v[62:65], v[150:153], v[188:191], v[62:65]
	v_mfma_f32_16x16x32_bf16 v[58:61], v[158:161], v[188:191], v[58:61]
	v_mfma_f32_16x16x32_bf16 v[50:53], v[150:153], v[196:199], v[50:53]
	v_mfma_f32_16x16x32_bf16 v[42:45], v[158:161], v[196:199], v[42:45]
	v_mfma_f32_16x16x32_bf16 v[34:37], v[150:153], v[204:207], v[34:37]
	v_mfma_f32_16x16x32_bf16 v[26:29], v[158:161], v[204:207], v[26:29]
	v_mfma_f32_16x16x32_bf16 v[18:21], v[150:153], v[212:215], v[18:21]
	v_mfma_f32_16x16x32_bf16 v[10:13], v[158:161], v[212:215], v[10:13]
	v_mfma_f32_16x16x32_bf16 v[54:57], v[162:165], v[184:187], v[54:57]
	v_mfma_f32_16x16x32_bf16 v[46:49], v[170:173], v[184:187], v[46:49]
	v_mfma_f32_16x16x32_bf16 v[38:41], v[162:165], v[192:195], v[38:41]
	v_mfma_f32_16x16x32_bf16 v[30:33], v[170:173], v[192:195], v[30:33]
	v_mfma_f32_16x16x32_bf16 v[22:25], v[162:165], v[200:203], v[22:25]
	v_mfma_f32_16x16x32_bf16 v[14:17], v[170:173], v[200:203], v[14:17]
	v_mfma_f32_16x16x32_bf16 v[6:9], v[162:165], v[208:211], v[6:9]
	v_mfma_f32_16x16x32_bf16 v[2:5], v[170:173], v[208:211], v[2:5]
	v_mfma_f32_16x16x32_bf16 v[54:57], v[166:169], v[188:191], v[54:57]
	v_mfma_f32_16x16x32_bf16 v[46:49], v[180:183], v[188:191], v[46:49]
	v_mfma_f32_16x16x32_bf16 v[38:41], v[166:169], v[196:199], v[38:41]
	v_mfma_f32_16x16x32_bf16 v[30:33], v[180:183], v[196:199], v[30:33]
	v_mfma_f32_16x16x32_bf16 v[22:25], v[166:169], v[204:207], v[22:25]
	v_mfma_f32_16x16x32_bf16 v[14:17], v[180:183], v[204:207], v[14:17]
	v_mfma_f32_16x16x32_bf16 v[6:9], v[166:169], v[212:215], v[6:9]
	v_mfma_f32_16x16x32_bf16 v[2:5], v[180:183], v[212:215], v[2:5]
	s_barrier
	s_setprio 0
	s_add_i32 s39, s39, 2
	s_add_u32 s12, s12, 0x100
	s_addc_u32 s13, s13, 0
	s_add_u32 s37, s37, 0x100
	s_addc_u32 s38, s38, 0
	s_cmp_gt_u32 s39, 29
	s_cbranch_scc0 .LBB0_2513
	v_readlane_b32 s12, v252, 14
	v_readlane_b32 s13, v252, 15
	s_and_b64 vcc, exec, s[12:13]
	s_cbranch_vccz .LBB0_2516
	s_barrier

; #define PG8_STAGE(bufoff, gbase, voff) do { _Pragma("unroll") for (int _i = 0; _i < 2; ++_i) \
;         __builtin_amdgcn_global_load_lds((const unsigned*)((const char*)(gbase) + (voff)[_i]), (LAS unsigned*)(lds + (bufoff) + ldsw + _i * 8192), 16, 0, 0); } while (0)
; #define PG8_LDA(dst, b, h) do { _Pragma("unroll") for (int m = 0; m < 4; ++m) _Pragma("unroll") for (int k = 0; k < 2; ++k) dst[m][k] = *(const LAS bf16x8*)(lds + PG8_SA(b, h) + aoff + m * 2048 + k * 1024); } while (0)
; #define PG8_LDB(dst, b, h) do { _Pragma("unroll") for (int n = 0; n < 2; ++n) _Pragma("unroll") for (int k = 0; k < 2; ++k) dst[n][k] = *(const LAS bf16x8*)(lds + PG8_SB(b, h) + boff + n * 2048 + k * 1024); } while (0)
; #define PG8_MMA(ai, bj, At, Bt) do { __builtin_amdgcn_s_setprio(1); _Pragma("unroll") for (int m = 0; m < 4; ++m) _Pragma("unroll") for (int n = 0; n < 2; ++n) _Pragma("unroll") for (int k = 0; k < 2; ++k) \
;         acc[ai][bj][m][n] = __builtin_amdgcn_mfma_f32_16x16x32_bf16(Bt[n][k], At[m][k], acc[ai][bj][m][n], 0, 0, 0); __builtin_amdgcn_s_setprio(0); } while (0)
; #define PG8_WAIT_V(n) asm volatile("s_waitcnt vmcnt(" #n ")" ::: "memory")
; #define PG8_WAIT_L(n) asm volatile("s_waitcnt lgkmcnt(" #n ")" ::: "memory")
; #define PG8_BAR __builtin_amdgcn_s_barrier()
; #define PG8_SCHED __builtin_amdgcn_sched_barrier(0)
; template <class Epi, class Sched, int LDA, int LDB, bool ALIGN_EPI = true>
; __device__ __forceinline__ void gemm_phase(LAS unsigned char* lds, const Gemm g, const Sched& S, const Epi& E, int wave) {
;     ...
;             PG8_LDB(B0, 0, 0); PG8_LDB(B1, 0, 1); PG8_SCHED; PG8_LDA(At, 0, 0); PG8_STAGE(PG8_SA(1, 1), a1 + hstepA, voffA);
;             PG8_WAIT_V(8); PG8_WAIT_L(0); PG8_BAR; PG8_MMA(0, 0, At, B0); PG8_MMA(0, 1, At, B1); PG8_BAR; PG8_SCHED;
;             PG8_LDA(At, 0, 1); PG8_STAGE(PG8_SB(0, 0), b2, voffB); PG8_STAGE(PG8_SB(0, 1), b2 + hstepB, voffB); PG8_STAGE(PG8_SA(0, 0), a2, voffA);
;             PG8_WAIT_V(8); PG8_WAIT_L(0); PG8_BAR; PG8_MMA(1, 0, At, B0); PG8_MMA(1, 1, At, B1); PG8_BAR; PG8_SCHED;
.LBB0_2551:
	ds_read_b128 v[188:191], v156
	ds_read_b128 v[192:195], v156 offset:1024
	ds_read_b128 v[196:199], v156 offset:2048
	ds_read_b128 v[200:203], v156 offset:3072
	ds_read_b128 v[204:207], v156 offset:4096
	ds_read_b128 v[208:211], v156 offset:5120
	ds_read_b128 v[212:215], v156 offset:6144
	ds_read_b128 v[216:219], v156 offset:7168
	s_add_u32 s2, s0, 0x100
	s_addc_u32 s3, s1, 0
	s_add_i32 s50, 0, 0x10000
	s_cmp_eq_u32 s49, 8
	s_cselect_b32 s17, s11, s3
	s_cselect_b32 s16, s10, s2
	v_add_u32_e32 v0, s50, v154
	s_cselect_b32 s15, s13, s47
	s_cselect_b32 s14, s12, s46
	s_add_i32 s51, 0, 0x14000
	ds_read_b128 v[130:133], v0
	ds_read_b128 v[148:151], v0 offset:1024
	ds_read_b128 v[158:161], v0 offset:2048
	ds_read_b128 v[162:165], v0 offset:3072
	v_add_u32_e32 v0, s51, v154
	ds_read_b128 v[166:169], v0
	ds_read_b128 v[170:173], v0 offset:1024
	ds_read_b128 v[180:183], v0 offset:2048
	ds_read_b128 v[184:187], v0 offset:3072
	v_lshl_add_u64 v[152:153], s[0:1], 0, v[144:145]
	s_add_i32 m0, s28, 0xc000
	s_nop 0
	global_load_lds_dwordx4 v[152:153], off
	v_lshl_add_u64 v[152:153], s[0:1], 0, v[146:147]
	s_add_i32 m0, s28, 0xe000
	s_nop 0
	global_load_lds_dwordx4 v[152:153], off
	s_waitcnt vmcnt(8)
	s_waitcnt lgkmcnt(0)
	s_setprio 1
	s_barrier
	v_mfma_f32_16x16x32_bf16 v[126:129], v[130:133], v[188:191], v[126:129]
	v_mfma_f32_16x16x32_bf16 v[122:125], v[158:161], v[188:191], v[122:125]
	v_mfma_f32_16x16x32_bf16 v[118:121], v[130:133], v[196:199], v[118:121]
	v_mfma_f32_16x16x32_bf16 v[114:117], v[158:161], v[196:199], v[114:117]
	v_mfma_f32_16x16x32_bf16 v[110:113], v[130:133], v[204:207], v[110:113]
	v_mfma_f32_16x16x32_bf16 v[106:109], v[158:161], v[204:207], v[106:109]
	v_mfma_f32_16x16x32_bf16 v[102:105], v[130:133], v[212:215], v[102:105]
	v_mfma_f32_16x16x32_bf16 v[98:101], v[158:161], v[212:215], v[98:101]
	v_mfma_f32_16x16x32_bf16 v[126:129], v[148:151], v[192:195], v[126:129]
	v_mfma_f32_16x16x32_bf16 v[122:125], v[162:165], v[192:195], v[122:125]
	v_mfma_f32_16x16x32_bf16 v[118:121], v[148:151], v[200:203], v[118:121]
	v_mfma_f32_16x16x32_bf16 v[114:117], v[162:165], v[200:203], v[114:117]
	v_mfma_f32_16x16x32_bf16 v[110:113], v[148:151], v[208:211], v[110:113]
	v_mfma_f32_16x16x32_bf16 v[106:109], v[162:165], v[208:211], v[106:109]
	v_mfma_f32_16x16x32_bf16 v[102:105], v[148:151], v[216:219], v[102:105]
	v_mfma_f32_16x16x32_bf16 v[98:101], v[162:165], v[216:219], v[98:101]
	v_mfma_f32_16x16x32_bf16 v[62:65], v[166:169], v[188:191], v[62:65]
	v_mfma_f32_16x16x32_bf16 v[58:61], v[180:183], v[188:191], v[58:61]
	v_mfma_f32_16x16x32_bf16 v[54:57], v[166:169], v[196:199], v[54:57]
	v_mfma_f32_16x16x32_bf16 v[50:53], v[180:183], v[196:199], v[50:53]
	v_mfma_f32_16x16x32_bf16 v[46:49], v[166:169], v[204:207], v[46:49]
	v_mfma_f32_16x16x32_bf16 v[42:45], v[180:183], v[204:207], v[42:45]
	v_mfma_f32_16x16x32_bf16 v[38:41], v[166:169], v[212:215], v[38:41]
	v_mfma_f32_16x16x32_bf16 v[34:37], v[180:183], v[212:215], v[34:37]
	v_mfma_f32_16x16x32_bf16 v[62:65], v[170:173], v[192:195], v[62:65]
	v_mfma_f32_16x16x32_bf16 v[58:61], v[184:187], v[192:195], v[58:61]
	v_mfma_f32_16x16x32_bf16 v[54:57], v[170:173], v[200:203], v[54:57]
	v_mfma_f32_16x16x32_bf16 v[50:53], v[184:187], v[200:203], v[50:53]
	v_mfma_f32_16x16x32_bf16 v[46:49], v[170:173], v[208:211], v[46:49]
	v_mfma_f32_16x16x32_bf16 v[42:45], v[184:187], v[208:211], v[42:45]
	v_mfma_f32_16x16x32_bf16 v[38:41], v[170:173], v[216:219], v[38:41]
	v_mfma_f32_16x16x32_bf16 v[34:37], v[184:187], v[216:219], v[34:37]
	s_barrier
	s_setprio 0
	ds_read_b128 v[188:191], v156 offset:16384
	ds_read_b128 v[192:195], v156 offset:17408
	ds_read_b128 v[196:199], v156 offset:18432
	ds_read_b128 v[200:203], v156 offset:19456
	ds_read_b128 v[204:207], v156 offset:20480
	ds_read_b128 v[208:211], v156 offset:21504
	ds_read_b128 v[212:215], v156 offset:22528
	ds_read_b128 v[216:219], v156 offset:23552
	s_add_i32 s0, s50, s54
	v_lshl_add_u64 v[152:153], s[14:15], 0, v[136:137]
	s_mov_b32 m0, s0
	s_nop 0
	global_load_lds_dwordx4 v[152:153], off
	s_add_i32 m0, s0, 0x2000
	s_add_u32 s0, s14, 0x30000
	v_lshl_add_u64 v[174:175], s[14:15], 0, v[140:141]
	s_addc_u32 s1, s15, 0
	s_add_i32 s50, s51, s54
	global_load_lds_dwordx4 v[174:175], off
	v_lshl_add_u64 v[220:221], s[0:1], 0, v[136:137]
	s_mov_b32 m0, s50
	v_lshl_add_u64 v[222:223], s[16:17], 0, v[138:139]
	global_load_lds_dwordx4 v[220:221], off
	v_lshl_add_u64 v[220:221], s[0:1], 0, v[140:141]
	s_add_i32 m0, s50, 0x2000
	s_nop 0
	global_load_lds_dwordx4 v[220:221], off
	v_lshl_add_u64 v[220:221], s[16:17], 0, v[134:135]
	s_mov_b32 m0, s28
	s_nop 0
	global_load_lds_dwordx4 v[220:221], off
	s_mov_b32 m0, s29
	s_nop 0
	global_load_lds_dwordx4 v[222:223], off
	s_waitcnt vmcnt(8)
	s_waitcnt lgkmcnt(0)
	s_setprio 1
	s_barrier
; #define PG8_STAGE(bufoff, gbase, voff) do { _Pragma("unroll") for (int _i = 0; _i < 2; ++_i) \
;         __builtin_amdgcn_global_load_lds((const unsigned*)((const char*)(gbase) + (voff)[_i]), (LAS unsigned*)(lds + (bufoff) + ldsw + _i * 8192), 16, 0, 0); } while (0)
; #define PG8_LDA(dst, b, h) do { _Pragma("unroll") for (int m = 0; m < 4; ++m) _Pragma("unroll") for (int k = 0; k < 2; ++k) dst[m][k] = *(const LAS bf16x8*)(lds + PG8_SA(b, h) + aoff + m * 2048 + k * 1024); } while (0)
; #define PG8_LDB(dst, b, h) do { _Pragma("unroll") for (int n = 0; n < 2; ++n) _Pragma("unroll") for (int k = 0; k < 2; ++k) dst[n][k] = *(const LAS bf16x8*)(lds + PG8_SB(b, h) + boff + n * 2048 + k * 1024); } while (0)
; #define PG8_MMA(ai, bj, At, Bt) do { __builtin_amdgcn_s_setprio(1); _Pragma("unroll") for (int m = 0; m < 4; ++m) _Pragma("unroll") for (int n = 0; n < 2; ++n) _Pragma("unroll") for (int k = 0; k < 2; ++k) \
;         acc[ai][bj][m][n] = __builtin_amdgcn_mfma_f32_16x16x32_bf16(Bt[n][k], At[m][k], acc[ai][bj][m][n], 0, 0, 0); __builtin_amdgcn_s_setprio(0); } while (0)
; #define PG8_WAIT_V(n) asm volatile("s_waitcnt vmcnt(" #n ")" ::: "memory")
; #define PG8_WAIT_L(n) asm volatile("s_waitcnt lgkmcnt(" #n ")" ::: "memory")
; #define PG8_BAR __builtin_amdgcn_s_barrier()
; #define PG8_SCHED __builtin_amdgcn_sched_barrier(0)
; template <class Epi, class Sched, int LDA, int LDB, bool ALIGN_EPI = true>
; __device__ __forceinline__ void gemm_phase(LAS unsigned char* lds, const Gemm g, const Sched& S, const Epi& E, int wave) {
;     ...
;             PG8_WAIT_V(8); PG8_WAIT_L(0); PG8_BAR; PG8_MMA(1, 0, At, B0); PG8_MMA(1, 1, At, B1); PG8_BAR; PG8_SCHED;
;             PG8_LDB(B0, 1, 0); PG8_LDB(B1, 1, 1); PG8_SCHED; PG8_LDA(At, 1, 0); PG8_STAGE(PG8_SA(0, 1), a2 + hstepA, voffA);
;             PG8_WAIT_V(8); PG8_WAIT_L(0); PG8_BAR; PG8_MMA(0, 0, At, B0); PG8_MMA(0, 1, At, B1); PG8_BAR; PG8_SCHED;
	v_mfma_f32_16x16x32_bf16 v[94:97], v[130:133], v[188:191], v[94:97]
	v_mfma_f32_16x16x32_bf16 v[90:93], v[158:161], v[188:191], v[90:93]
	v_mfma_f32_16x16x32_bf16 v[86:89], v[130:133], v[196:199], v[86:89]
	v_mfma_f32_16x16x32_bf16 v[82:85], v[158:161], v[196:199], v[82:85]
	v_mfma_f32_16x16x32_bf16 v[78:81], v[130:133], v[204:207], v[78:81]
	v_mfma_f32_16x16x32_bf16 v[74:77], v[158:161], v[204:207], v[74:77]
	v_mfma_f32_16x16x32_bf16 v[70:73], v[130:133], v[212:215], v[70:73]
	v_mfma_f32_16x16x32_bf16 v[66:69], v[158:161], v[212:215], v[66:69]
	v_mfma_f32_16x16x32_bf16 v[94:97], v[148:151], v[192:195], v[94:97]
	v_mfma_f32_16x16x32_bf16 v[90:93], v[162:165], v[192:195], v[90:93]
	v_mfma_f32_16x16x32_bf16 v[86:89], v[148:151], v[200:203], v[86:89]
	v_mfma_f32_16x16x32_bf16 v[82:85], v[162:165], v[200:203], v[82:85]
	v_mfma_f32_16x16x32_bf16 v[78:81], v[148:151], v[208:211], v[78:81]
	v_mfma_f32_16x16x32_bf16 v[74:77], v[162:165], v[208:211], v[74:77]
	v_mfma_f32_16x16x32_bf16 v[70:73], v[148:151], v[216:219], v[70:73]
	v_mfma_f32_16x16x32_bf16 v[66:69], v[162:165], v[216:219], v[66:69]
	v_mfma_f32_16x16x32_bf16 v[30:33], v[166:169], v[188:191], v[30:33]
	v_mfma_f32_16x16x32_bf16 v[26:29], v[180:183], v[188:191], v[26:29]
	v_mfma_f32_16x16x32_bf16 v[22:25], v[166:169], v[196:199], v[22:25]
	v_mfma_f32_16x16x32_bf16 v[18:21], v[180:183], v[196:199], v[18:21]
	v_mfma_f32_16x16x32_bf16 v[14:17], v[166:169], v[204:207], v[14:17]
	v_mfma_f32_16x16x32_bf16 v[10:13], v[180:183], v[204:207], v[10:13]
	v_mfma_f32_16x16x32_bf16 v[6:9], v[166:169], v[212:215], v[6:9]
	v_mfma_f32_16x16x32_bf16 v[2:5], v[180:183], v[212:215], v[2:5]
	v_mfma_f32_16x16x32_bf16 v[30:33], v[170:173], v[192:195], v[30:33]
	v_mfma_f32_16x16x32_bf16 v[26:29], v[184:187], v[192:195], v[26:29]
	v_mfma_f32_16x16x32_bf16 v[22:25], v[170:173], v[200:203], v[22:25]
	v_mfma_f32_16x16x32_bf16 v[18:21], v[184:187], v[200:203], v[18:21]
	v_mfma_f32_16x16x32_bf16 v[14:17], v[170:173], v[208:211], v[14:17]
	v_mfma_f32_16x16x32_bf16 v[10:13], v[184:187], v[208:211], v[10:13]
	v_mfma_f32_16x16x32_bf16 v[6:9], v[170:173], v[216:219], v[6:9]
	v_mfma_f32_16x16x32_bf16 v[2:5], v[184:187], v[216:219], v[2:5]
	s_barrier
	s_setprio 0
	ds_read_b128 v[188:191], v156 offset:32768
	ds_read_b128 v[192:195], v156 offset:33792
	ds_read_b128 v[196:199], v156 offset:34816
	ds_read_b128 v[200:203], v156 offset:35840
	ds_read_b128 v[204:207], v156 offset:36864
	ds_read_b128 v[208:211], v156 offset:37888
	ds_read_b128 v[212:215], v156 offset:38912
	ds_read_b128 v[216:219], v156 offset:39936
	s_add_i32 s50, 0, 0x18000
	v_add_u32_e32 v0, s50, v154
	s_add_i32 s51, 0, 0x1c000
	ds_read_b128 v[130:133], v0
	ds_read_b128 v[148:151], v0 offset:1024
	ds_read_b128 v[158:161], v0 offset:2048
	ds_read_b128 v[162:165], v0 offset:3072
	v_add_u32_e32 v0, s51, v154
	ds_read_b128 v[166:169], v0
	ds_read_b128 v[170:173], v0 offset:1024
	ds_read_b128 v[180:183], v0 offset:2048
	ds_read_b128 v[184:187], v0 offset:3072
	s_add_u32 s0, s16, 0x30000
	s_addc_u32 s1, s17, 0
	s_mov_b32 m0, s34
	v_lshl_add_u64 v[224:225], s[0:1], 0, v[134:135]
	global_load_lds_dwordx4 v[224:225], off
	v_lshl_add_u64 v[224:225], s[0:1], 0, v[138:139]
	s_mov_b32 m0, s35
	s_nop 0
	global_load_lds_dwordx4 v[224:225], off
	s_waitcnt vmcnt(8)
	s_waitcnt lgkmcnt(0)
	s_setprio 1
	s_barrier
	v_mfma_f32_16x16x32_bf16 v[126:129], v[130:133], v[188:191], v[126:129]
	v_mfma_f32_16x16x32_bf16 v[122:125], v[158:161], v[188:191], v[122:125]
	v_mfma_f32_16x16x32_bf16 v[118:121], v[130:133], v[196:199], v[118:121]
	v_mfma_f32_16x16x32_bf16 v[114:117], v[158:161], v[196:199], v[114:117]
	v_mfma_f32_16x16x32_bf16 v[110:113], v[130:133], v[204:207], v[110:113]
	v_mfma_f32_16x16x32_bf16 v[106:109], v[158:161], v[204:207], v[106:109]
	v_mfma_f32_16x16x32_bf16 v[102:105], v[130:133], v[212:215], v[102:105]
	v_mfma_f32_16x16x32_bf16 v[98:101], v[158:161], v[212:215], v[98:101]
	v_mfma_f32_16x16x32_bf16 v[126:129], v[148:151], v[192:195], v[126:129]
	v_mfma_f32_16x16x32_bf16 v[122:125], v[162:165], v[192:195], v[122:125]
	v_mfma_f32_16x16x32_bf16 v[118:121], v[148:151], v[200:203], v[118:121]
	v_mfma_f32_16x16x32_bf16 v[114:117], v[162:165], v[200:203], v[114:117]
	v_mfma_f32_16x16x32_bf16 v[110:113], v[148:151], v[208:211], v[110:113]
	v_mfma_f32_16x16x32_bf16 v[106:109], v[162:165], v[208:211], v[106:109]
	v_mfma_f32_16x16x32_bf16 v[102:105], v[148:151], v[216:219], v[102:105]
	v_mfma_f32_16x16x32_bf16 v[98:101], v[162:165], v[216:219], v[98:101]
	v_mfma_f32_16x16x32_bf16 v[62:65], v[166:169], v[188:191], v[62:65]
	v_mfma_f32_16x16x32_bf16 v[58:61], v[180:183], v[188:191], v[58:61]
	v_mfma_f32_16x16x32_bf16 v[54:57], v[166:169], v[196:199], v[54:57]
	v_mfma_f32_16x16x32_bf16 v[50:53], v[180:183], v[196:199], v[50:53]
	v_mfma_f32_16x16x32_bf16 v[46:49], v[166:169], v[204:207], v[46:49]
	v_mfma_f32_16x16x32_bf16 v[42:45], v[180:183], v[204:207], v[42:45]
	v_mfma_f32_16x16x32_bf16 v[38:41], v[166:169], v[212:215], v[38:41]
	v_mfma_f32_16x16x32_bf16 v[34:37], v[180:183], v[212:215], v[34:37]
	v_mfma_f32_16x16x32_bf16 v[62:65], v[170:173], v[192:195], v[62:65]
	v_mfma_f32_16x16x32_bf16 v[58:61], v[184:187], v[192:195], v[58:61]
	v_mfma_f32_16x16x32_bf16 v[54:57], v[170:173], v[200:203], v[54:57]
	v_mfma_f32_16x16x32_bf16 v[50:53], v[184:187], v[200:203], v[50:53]
	v_mfma_f32_16x16x32_bf16 v[46:49], v[170:173], v[208:211], v[46:49]
	v_mfma_f32_16x16x32_bf16 v[42:45], v[184:187], v[208:211], v[42:45]
	v_mfma_f32_16x16x32_bf16 v[38:41], v[170:173], v[216:219], v[38:41]
	v_mfma_f32_16x16x32_bf16 v[34:37], v[184:187], v[216:219], v[34:37]
	s_barrier
; #define PG8_STAGE(bufoff, gbase, voff) do { _Pragma("unroll") for (int _i = 0; _i < 2; ++_i) \
;         __builtin_amdgcn_global_load_lds((const unsigned*)((const char*)(gbase) + (voff)[_i]), (LAS unsigned*)(lds + (bufoff) + ldsw + _i * 8192), 16, 0, 0); } while (0)
; #define PG8_LDA(dst, b, h) do { _Pragma("unroll") for (int m = 0; m < 4; ++m) _Pragma("unroll") for (int k = 0; k < 2; ++k) dst[m][k] = *(const LAS bf16x8*)(lds + PG8_SA(b, h) + aoff + m * 2048 + k * 1024); } while (0)
; #define PG8_MMA(ai, bj, At, Bt) do { __builtin_amdgcn_s_setprio(1); _Pragma("unroll") for (int m = 0; m < 4; ++m) _Pragma("unroll") for (int n = 0; n < 2; ++n) _Pragma("unroll") for (int k = 0; k < 2; ++k) \
;         acc[ai][bj][m][n] = __builtin_amdgcn_mfma_f32_16x16x32_bf16(Bt[n][k], At[m][k], acc[ai][bj][m][n], 0, 0, 0); __builtin_amdgcn_s_setprio(0); } while (0)
; #define PG8_WAIT_V(n) asm volatile("s_waitcnt vmcnt(" #n ")" ::: "memory")
; #define PG8_WAIT_L(n) asm volatile("s_waitcnt lgkmcnt(" #n ")" ::: "memory")
; #define PG8_BAR __builtin_amdgcn_s_barrier()
; #define PG8_SCHED __builtin_amdgcn_sched_barrier(0)
; template <class Epi, class Sched, int LDA, int LDB, bool ALIGN_EPI = true>
; __device__ __forceinline__ void gemm_phase(LAS unsigned char* lds, const Gemm g, const Sched& S, const Epi& E, int wave) {
;     ...
;             PG8_LDA(At, 1, 1); PG8_STAGE(PG8_SB(1, 0), b3, voffB); PG8_STAGE(PG8_SB(1, 1), b3 + hstepB, voffB); PG8_STAGE(PG8_SA(1, 0), a3, voffA);
;             PG8_WAIT_V(8); PG8_WAIT_L(0); PG8_BAR; PG8_MMA(1, 0, At, B0); PG8_MMA(1, 1, At, B1); PG8_BAR; PG8_SCHED;
;         }
	s_setprio 0
	ds_read_b128 v[188:191], v156 offset:49152
	ds_read_b128 v[192:195], v156 offset:50176
	ds_read_b128 v[196:199], v156 offset:51200
	ds_read_b128 v[200:203], v156 offset:52224
	ds_read_b128 v[204:207], v156 offset:53248
	ds_read_b128 v[208:211], v156 offset:54272
	ds_read_b128 v[212:215], v156 offset:55296
	ds_read_b128 v[216:219], v156 offset:56320
	s_add_i32 s0, s50, s54
	v_lshl_add_u64 v[152:153], v[152:153], 0, s[72:73]
	s_mov_b32 m0, s0
	s_nop 0
	global_load_lds_dwordx4 v[152:153], off
	s_add_i32 m0, s0, 0x2000
	s_add_u32 s0, s14, 0x30080
	v_lshl_add_u64 v[152:153], v[174:175], 0, s[72:73]
	s_addc_u32 s1, s15, 0
	s_add_i32 s14, s51, s54
	global_load_lds_dwordx4 v[152:153], off
	v_lshl_add_u64 v[152:153], s[0:1], 0, v[136:137]
	s_mov_b32 m0, s14
	s_nop 0
	global_load_lds_dwordx4 v[152:153], off
	v_lshl_add_u64 v[152:153], s[0:1], 0, v[140:141]
	s_add_i32 m0, s14, 0x2000
	s_nop 0
	global_load_lds_dwordx4 v[152:153], off
	v_lshl_add_u64 v[152:153], v[220:221], 0, s[72:73]
	s_mov_b32 m0, s36
	s_nop 0
	global_load_lds_dwordx4 v[152:153], off
	v_lshl_add_u64 v[152:153], v[222:223], 0, s[72:73]
	s_mov_b32 m0, s37
	s_nop 0
	global_load_lds_dwordx4 v[152:153], off
	s_waitcnt vmcnt(8)
	s_waitcnt lgkmcnt(0)
	s_setprio 1
	s_barrier
	v_mfma_f32_16x16x32_bf16 v[94:97], v[130:133], v[188:191], v[94:97]
	v_mfma_f32_16x16x32_bf16 v[90:93], v[158:161], v[188:191], v[90:93]
	v_mfma_f32_16x16x32_bf16 v[86:89], v[130:133], v[196:199], v[86:89]
	v_mfma_f32_16x16x32_bf16 v[82:85], v[158:161], v[196:199], v[82:85]
	v_mfma_f32_16x16x32_bf16 v[78:81], v[130:133], v[204:207], v[78:81]
	v_mfma_f32_16x16x32_bf16 v[74:77], v[158:161], v[204:207], v[74:77]
	v_mfma_f32_16x16x32_bf16 v[70:73], v[130:133], v[212:215], v[70:73]
	v_mfma_f32_16x16x32_bf16 v[66:69], v[158:161], v[212:215], v[66:69]
	v_mfma_f32_16x16x32_bf16 v[94:97], v[148:151], v[192:195], v[94:97]
	v_mfma_f32_16x16x32_bf16 v[90:93], v[162:165], v[192:195], v[90:93]
	v_mfma_f32_16x16x32_bf16 v[86:89], v[148:151], v[200:203], v[86:89]
	v_mfma_f32_16x16x32_bf16 v[82:85], v[162:165], v[200:203], v[82:85]
	v_mfma_f32_16x16x32_bf16 v[78:81], v[148:151], v[208:211], v[78:81]
	v_mfma_f32_16x16x32_bf16 v[74:77], v[162:165], v[208:211], v[74:77]
	v_mfma_f32_16x16x32_bf16 v[70:73], v[148:151], v[216:219], v[70:73]
	v_mfma_f32_16x16x32_bf16 v[66:69], v[162:165], v[216:219], v[66:69]
	v_mfma_f32_16x16x32_bf16 v[30:33], v[166:169], v[188:191], v[30:33]
	v_mfma_f32_16x16x32_bf16 v[26:29], v[180:183], v[188:191], v[26:29]
	v_mfma_f32_16x16x32_bf16 v[22:25], v[166:169], v[196:199], v[22:25]
	v_mfma_f32_16x16x32_bf16 v[18:21], v[180:183], v[196:199], v[18:21]
	v_mfma_f32_16x16x32_bf16 v[14:17], v[166:169], v[204:207], v[14:17]
	v_mfma_f32_16x16x32_bf16 v[10:13], v[180:183], v[204:207], v[10:13]
	v_mfma_f32_16x16x32_bf16 v[6:9], v[166:169], v[212:215], v[6:9]
	v_mfma_f32_16x16x32_bf16 v[2:5], v[180:183], v[212:215], v[2:5]
	v_mfma_f32_16x16x32_bf16 v[30:33], v[170:173], v[192:195], v[30:33]
	v_mfma_f32_16x16x32_bf16 v[26:29], v[184:187], v[192:195], v[26:29]
	v_mfma_f32_16x16x32_bf16 v[22:25], v[170:173], v[200:203], v[22:25]
	v_mfma_f32_16x16x32_bf16 v[18:21], v[184:187], v[200:203], v[18:21]
	v_mfma_f32_16x16x32_bf16 v[14:17], v[170:173], v[208:211], v[14:17]
	v_mfma_f32_16x16x32_bf16 v[10:13], v[184:187], v[208:211], v[10:13]
	v_mfma_f32_16x16x32_bf16 v[6:9], v[170:173], v[216:219], v[6:9]
	v_mfma_f32_16x16x32_bf16 v[2:5], v[184:187], v[216:219], v[2:5]
	s_barrier
	s_setprio 0
	s_add_i32 s49, s49, 2
	s_add_u32 s46, s46, 0x100
	s_addc_u32 s47, s47, 0
	s_cmp_gt_u32 s49, 9
	s_mov_b64 s[0:1], s[2:3]
	s_cbranch_scc0 .LBB0_2551
	v_readlane_b32 s0, v252, 14
	v_readlane_b32 s1, v252, 15
	s_and_b64 vcc, exec, s[0:1]
	s_cbranch_vccz .LBB0_2554
	s_barrier

; #define PG8_STAGE(bufoff, gbase, voff) do { _Pragma("unroll") for (int _i = 0; _i < 2; ++_i) \
;         __builtin_amdgcn_global_load_lds((const unsigned*)((const char*)(gbase) + (voff)[_i]), (LAS unsigned*)(lds + (bufoff) + ldsw + _i * 8192), 16, 0, 0); } while (0)
; #define PG8_LDA(dst, b, h) do { _Pragma("unroll") for (int m = 0; m < 4; ++m) _Pragma("unroll") for (int k = 0; k < 2; ++k) dst[m][k] = *(const LAS bf16x8*)(lds + PG8_SA(b, h) + aoff + m * 2048 + k * 1024); } while (0)
; #define PG8_LDB(dst, b, h) do { _Pragma("unroll") for (int n = 0; n < 2; ++n) _Pragma("unroll") for (int k = 0; k < 2; ++k) dst[n][k] = *(const LAS bf16x8*)(lds + PG8_SB(b, h) + boff + n * 2048 + k * 1024); } while (0)
; #define PG8_MMA(ai, bj, At, Bt) do { __builtin_amdgcn_s_setprio(1); _Pragma("unroll") for (int m = 0; m < 4; ++m) _Pragma("unroll") for (int n = 0; n < 2; ++n) _Pragma("unroll") for (int k = 0; k < 2; ++k) \
;         acc[ai][bj][m][n] = __builtin_amdgcn_mfma_f32_16x16x32_bf16(Bt[n][k], At[m][k], acc[ai][bj][m][n], 0, 0, 0); __builtin_amdgcn_s_setprio(0); } while (0)
; #define PG8_WAIT_V(n) asm volatile("s_waitcnt vmcnt(" #n ")" ::: "memory")
; #define PG8_WAIT_L(n) asm volatile("s_waitcnt lgkmcnt(" #n ")" ::: "memory")
; #define PG8_BAR __builtin_amdgcn_s_barrier()
; #define PG8_SCHED __builtin_amdgcn_sched_barrier(0)
; template <class Epi, class Sched, int LDA, int LDB, bool ALIGN_EPI = true>
; __device__ __forceinline__ void gemm_phase(LAS unsigned char* lds, const Gemm g, const Sched& S, const Epi& E, int wave) {
;     ...
;             PG8_LDB(B0, 0, 0); PG8_LDB(B1, 0, 1); PG8_SCHED; PG8_LDA(At, 0, 0); PG8_STAGE(PG8_SA(1, 1), a1 + hstepA, voffA);
;             PG8_WAIT_V(8); PG8_WAIT_L(0); PG8_BAR; PG8_MMA(0, 0, At, B0); PG8_MMA(0, 1, At, B1); PG8_BAR; PG8_SCHED;
;             PG8_LDA(At, 0, 1); PG8_STAGE(PG8_SB(0, 0), b2, voffB); PG8_STAGE(PG8_SB(0, 1), b2 + hstepB, voffB); PG8_STAGE(PG8_SA(0, 0), a2, voffA);
;             PG8_WAIT_V(8); PG8_WAIT_L(0); PG8_BAR; PG8_MMA(1, 0, At, B0); PG8_MMA(1, 1, At, B1); PG8_BAR; PG8_SCHED;
.LBB0_2619:
	ds_read_b128 v[184:187], v151
	ds_read_b128 v[188:191], v151 offset:1024
	ds_read_b128 v[192:195], v151 offset:2048
	ds_read_b128 v[196:199], v151 offset:3072
	ds_read_b128 v[200:203], v151 offset:4096
	ds_read_b128 v[204:207], v151 offset:5120
	ds_read_b128 v[208:211], v151 offset:6144
	ds_read_b128 v[212:215], v151 offset:7168
	s_add_u32 s16, s14, 0xfffe0080
	s_addc_u32 s17, s15, -1
	s_add_i32 s53, 0, 0x10000
	s_cmp_eq_u32 s52, 4
	s_cselect_b32 s19, s7, s17
	s_cselect_b32 s18, s13, s16
	v_add_u32_e32 v0, s53, v150
	s_cselect_b32 s17, s3, s51
	s_cselect_b32 s16, s44, s45
	s_add_i32 s58, 0, 0x14000
	ds_read_b128 v[144:147], v0
	ds_read_b128 v[152:155], v0 offset:1024
	ds_read_b128 v[156:159], v0 offset:2048
	ds_read_b128 v[160:163], v0 offset:3072
	v_add_u32_e32 v0, s58, v150
	ds_read_b128 v[164:167], v0
	ds_read_b128 v[168:171], v0 offset:1024
	ds_read_b128 v[172:175], v0 offset:2048
	ds_read_b128 v[180:183], v0 offset:3072
	v_lshl_add_u64 v[148:149], s[14:15], 0, v[140:141]
	s_add_i32 m0, s36, 0xc000
	s_nop 0
	global_load_lds_dwordx4 v[148:149], off
	v_lshl_add_u64 v[148:149], s[14:15], 0, v[142:143]
	s_add_i32 m0, s36, 0xe000
	s_nop 0
	global_load_lds_dwordx4 v[148:149], off
	s_waitcnt vmcnt(8)
	s_waitcnt lgkmcnt(0)
	s_setprio 1
	s_barrier
	v_mfma_f32_16x16x32_bf16 v[126:129], v[144:147], v[184:187], v[126:129]
	v_mfma_f32_16x16x32_bf16 v[122:125], v[156:159], v[184:187], v[122:125]
	v_mfma_f32_16x16x32_bf16 v[118:121], v[144:147], v[192:195], v[118:121]
	v_mfma_f32_16x16x32_bf16 v[114:117], v[156:159], v[192:195], v[114:117]
	v_mfma_f32_16x16x32_bf16 v[110:113], v[144:147], v[200:203], v[110:113]
	v_mfma_f32_16x16x32_bf16 v[106:109], v[156:159], v[200:203], v[106:109]
	v_mfma_f32_16x16x32_bf16 v[102:105], v[144:147], v[208:211], v[102:105]
	v_mfma_f32_16x16x32_bf16 v[98:101], v[156:159], v[208:211], v[98:101]
	v_mfma_f32_16x16x32_bf16 v[126:129], v[152:155], v[188:191], v[126:129]
	v_mfma_f32_16x16x32_bf16 v[122:125], v[160:163], v[188:191], v[122:125]
	v_mfma_f32_16x16x32_bf16 v[118:121], v[152:155], v[196:199], v[118:121]
	v_mfma_f32_16x16x32_bf16 v[114:117], v[160:163], v[196:199], v[114:117]
	v_mfma_f32_16x16x32_bf16 v[110:113], v[152:155], v[204:207], v[110:113]
	v_mfma_f32_16x16x32_bf16 v[106:109], v[160:163], v[204:207], v[106:109]
	v_mfma_f32_16x16x32_bf16 v[102:105], v[152:155], v[212:215], v[102:105]
	v_mfma_f32_16x16x32_bf16 v[98:101], v[160:163], v[212:215], v[98:101]
	v_mfma_f32_16x16x32_bf16 v[62:65], v[164:167], v[184:187], v[62:65]
	v_mfma_f32_16x16x32_bf16 v[58:61], v[172:175], v[184:187], v[58:61]
	v_mfma_f32_16x16x32_bf16 v[54:57], v[164:167], v[192:195], v[54:57]
	v_mfma_f32_16x16x32_bf16 v[50:53], v[172:175], v[192:195], v[50:53]
	v_mfma_f32_16x16x32_bf16 v[46:49], v[164:167], v[200:203], v[46:49]
	v_mfma_f32_16x16x32_bf16 v[42:45], v[172:175], v[200:203], v[42:45]
	v_mfma_f32_16x16x32_bf16 v[38:41], v[164:167], v[208:211], v[38:41]
	v_mfma_f32_16x16x32_bf16 v[34:37], v[172:175], v[208:211], v[34:37]
	v_mfma_f32_16x16x32_bf16 v[62:65], v[168:171], v[188:191], v[62:65]
	v_mfma_f32_16x16x32_bf16 v[58:61], v[180:183], v[188:191], v[58:61]
	v_mfma_f32_16x16x32_bf16 v[54:57], v[168:171], v[196:199], v[54:57]
	v_mfma_f32_16x16x32_bf16 v[50:53], v[180:183], v[196:199], v[50:53]
	v_mfma_f32_16x16x32_bf16 v[46:49], v[168:171], v[204:207], v[46:49]
	v_mfma_f32_16x16x32_bf16 v[42:45], v[180:183], v[204:207], v[42:45]
	v_mfma_f32_16x16x32_bf16 v[38:41], v[168:171], v[212:215], v[38:41]
	v_mfma_f32_16x16x32_bf16 v[34:37], v[180:183], v[212:215], v[34:37]
	s_barrier
	s_setprio 0
	ds_read_b128 v[184:187], v151 offset:16384
	ds_read_b128 v[188:191], v151 offset:17408
	ds_read_b128 v[192:195], v151 offset:18432
	ds_read_b128 v[196:199], v151 offset:19456
	ds_read_b128 v[200:203], v151 offset:20480
	ds_read_b128 v[204:207], v151 offset:21504
	ds_read_b128 v[208:211], v151 offset:22528
	ds_read_b128 v[212:215], v151 offset:23552
	s_add_i32 s53, s53, s59
	v_lshl_add_u64 v[148:149], s[16:17], 0, v[132:133]
	s_mov_b32 m0, s53
	s_nop 0
	global_load_lds_dwordx4 v[148:149], off
	s_add_i32 m0, s53, 0x2000
	s_add_u32 s54, s16, 0x20000
	v_lshl_add_u64 v[216:217], s[16:17], 0, v[136:137]
	s_addc_u32 s55, s17, 0
	s_add_i32 s53, s58, s59
	global_load_lds_dwordx4 v[216:217], off
	v_lshl_add_u64 v[218:219], s[54:55], 0, v[132:133]
	s_mov_b32 m0, s53
	v_lshl_add_u64 v[220:221], s[18:19], 0, v[134:135]
	global_load_lds_dwordx4 v[218:219], off
	v_lshl_add_u64 v[218:219], s[54:55], 0, v[136:137]
	s_add_i32 m0, s53, 0x2000
	s_nop 0
	global_load_lds_dwordx4 v[218:219], off
	v_lshl_add_u64 v[218:219], s[18:19], 0, v[130:131]
	s_mov_b32 m0, s36
	s_nop 0
	global_load_lds_dwordx4 v[218:219], off
	s_mov_b32 m0, s37
	s_nop 0
	global_load_lds_dwordx4 v[220:221], off
	s_waitcnt vmcnt(8)
	s_waitcnt lgkmcnt(0)
	s_setprio 1
	s_barrier
; #define PG8_STAGE(bufoff, gbase, voff) do { _Pragma("unroll") for (int _i = 0; _i < 2; ++_i) \
;         __builtin_amdgcn_global_load_lds((const unsigned*)((const char*)(gbase) + (voff)[_i]), (LAS unsigned*)(lds + (bufoff) + ldsw + _i * 8192), 16, 0, 0); } while (0)
; #define PG8_LDA(dst, b, h) do { _Pragma("unroll") for (int m = 0; m < 4; ++m) _Pragma("unroll") for (int k = 0; k < 2; ++k) dst[m][k] = *(const LAS bf16x8*)(lds + PG8_SA(b, h) + aoff + m * 2048 + k * 1024); } while (0)
; #define PG8_LDB(dst, b, h) do { _Pragma("unroll") for (int n = 0; n < 2; ++n) _Pragma("unroll") for (int k = 0; k < 2; ++k) dst[n][k] = *(const LAS bf16x8*)(lds + PG8_SB(b, h) + boff + n * 2048 + k * 1024); } while (0)
; #define PG8_MMA(ai, bj, At, Bt) do { __builtin_amdgcn_s_setprio(1); _Pragma("unroll") for (int m = 0; m < 4; ++m) _Pragma("unroll") for (int n = 0; n < 2; ++n) _Pragma("unroll") for (int k = 0; k < 2; ++k) \
;         acc[ai][bj][m][n] = __builtin_amdgcn_mfma_f32_16x16x32_bf16(Bt[n][k], At[m][k], acc[ai][bj][m][n], 0, 0, 0); __builtin_amdgcn_s_setprio(0); } while (0)
; #define PG8_WAIT_V(n) asm volatile("s_waitcnt vmcnt(" #n ")" ::: "memory")
; #define PG8_WAIT_L(n) asm volatile("s_waitcnt lgkmcnt(" #n ")" ::: "memory")
; #define PG8_BAR __builtin_amdgcn_s_barrier()
; #define PG8_SCHED __builtin_amdgcn_sched_barrier(0)
; template <class Epi, class Sched, int LDA, int LDB, bool ALIGN_EPI = true>
; __device__ __forceinline__ void gemm_phase(LAS unsigned char* lds, const Gemm g, const Sched& S, const Epi& E, int wave) {
;     ...
;             PG8_WAIT_V(8); PG8_WAIT_L(0); PG8_BAR; PG8_MMA(1, 0, At, B0); PG8_MMA(1, 1, At, B1); PG8_BAR; PG8_SCHED;
;             PG8_LDB(B0, 1, 0); PG8_LDB(B1, 1, 1); PG8_SCHED; PG8_LDA(At, 1, 0); PG8_STAGE(PG8_SA(0, 1), a2 + hstepA, voffA);
;             PG8_WAIT_V(8); PG8_WAIT_L(0); PG8_BAR; PG8_MMA(0, 0, At, B0); PG8_MMA(0, 1, At, B1); PG8_BAR; PG8_SCHED;
	v_mfma_f32_16x16x32_bf16 v[94:97], v[144:147], v[184:187], v[94:97]
	v_mfma_f32_16x16x32_bf16 v[90:93], v[156:159], v[184:187], v[90:93]
	v_mfma_f32_16x16x32_bf16 v[86:89], v[144:147], v[192:195], v[86:89]
	v_mfma_f32_16x16x32_bf16 v[82:85], v[156:159], v[192:195], v[82:85]
	v_mfma_f32_16x16x32_bf16 v[78:81], v[144:147], v[200:203], v[78:81]
	v_mfma_f32_16x16x32_bf16 v[74:77], v[156:159], v[200:203], v[74:77]
	v_mfma_f32_16x16x32_bf16 v[70:73], v[144:147], v[208:211], v[70:73]
	v_mfma_f32_16x16x32_bf16 v[66:69], v[156:159], v[208:211], v[66:69]
	v_mfma_f32_16x16x32_bf16 v[94:97], v[152:155], v[188:191], v[94:97]
	v_mfma_f32_16x16x32_bf16 v[90:93], v[160:163], v[188:191], v[90:93]
	v_mfma_f32_16x16x32_bf16 v[86:89], v[152:155], v[196:199], v[86:89]
	v_mfma_f32_16x16x32_bf16 v[82:85], v[160:163], v[196:199], v[82:85]
	v_mfma_f32_16x16x32_bf16 v[78:81], v[152:155], v[204:207], v[78:81]
	v_mfma_f32_16x16x32_bf16 v[74:77], v[160:163], v[204:207], v[74:77]
	v_mfma_f32_16x16x32_bf16 v[70:73], v[152:155], v[212:215], v[70:73]
	v_mfma_f32_16x16x32_bf16 v[66:69], v[160:163], v[212:215], v[66:69]
	v_mfma_f32_16x16x32_bf16 v[30:33], v[164:167], v[184:187], v[30:33]
	v_mfma_f32_16x16x32_bf16 v[26:29], v[172:175], v[184:187], v[26:29]
	v_mfma_f32_16x16x32_bf16 v[22:25], v[164:167], v[192:195], v[22:25]
	v_mfma_f32_16x16x32_bf16 v[18:21], v[172:175], v[192:195], v[18:21]
	v_mfma_f32_16x16x32_bf16 v[14:17], v[164:167], v[200:203], v[14:17]
	v_mfma_f32_16x16x32_bf16 v[10:13], v[172:175], v[200:203], v[10:13]
	v_mfma_f32_16x16x32_bf16 v[6:9], v[164:167], v[208:211], v[6:9]
	v_mfma_f32_16x16x32_bf16 v[2:5], v[172:175], v[208:211], v[2:5]
	v_mfma_f32_16x16x32_bf16 v[30:33], v[168:171], v[188:191], v[30:33]
	v_mfma_f32_16x16x32_bf16 v[26:29], v[180:183], v[188:191], v[26:29]
	v_mfma_f32_16x16x32_bf16 v[22:25], v[168:171], v[196:199], v[22:25]
	v_mfma_f32_16x16x32_bf16 v[18:21], v[180:183], v[196:199], v[18:21]
	v_mfma_f32_16x16x32_bf16 v[14:17], v[168:171], v[204:207], v[14:17]
	v_mfma_f32_16x16x32_bf16 v[10:13], v[180:183], v[204:207], v[10:13]
	v_mfma_f32_16x16x32_bf16 v[6:9], v[168:171], v[212:215], v[6:9]
	v_mfma_f32_16x16x32_bf16 v[2:5], v[180:183], v[212:215], v[2:5]
	s_barrier
	s_setprio 0
	ds_read_b128 v[184:187], v151 offset:32768
	ds_read_b128 v[188:191], v151 offset:33792
	ds_read_b128 v[192:195], v151 offset:34816
	ds_read_b128 v[196:199], v151 offset:35840
	ds_read_b128 v[200:203], v151 offset:36864
	ds_read_b128 v[204:207], v151 offset:37888
	ds_read_b128 v[208:211], v151 offset:38912
	ds_read_b128 v[212:215], v151 offset:39936
	s_add_i32 s53, 0, 0x18000
	v_add_u32_e32 v0, s53, v150
	s_add_i32 s54, 0, 0x1c000
	ds_read_b128 v[144:147], v0
	ds_read_b128 v[152:155], v0 offset:1024
	ds_read_b128 v[156:159], v0 offset:2048
	ds_read_b128 v[160:163], v0 offset:3072
	v_add_u32_e32 v0, s54, v150
	ds_read_b128 v[164:167], v0
	ds_read_b128 v[168:171], v0 offset:1024
	ds_read_b128 v[172:175], v0 offset:2048
	ds_read_b128 v[180:183], v0 offset:3072
	s_add_u32 s18, s18, 0x20000
	s_addc_u32 s19, s19, 0
	s_mov_b32 m0, s38
	v_lshl_add_u64 v[222:223], s[18:19], 0, v[130:131]
	global_load_lds_dwordx4 v[222:223], off
	v_lshl_add_u64 v[222:223], s[18:19], 0, v[134:135]
	s_mov_b32 m0, s39
	s_nop 0
	global_load_lds_dwordx4 v[222:223], off
	s_waitcnt vmcnt(8)
	s_waitcnt lgkmcnt(0)
	s_setprio 1
	s_barrier
	v_mfma_f32_16x16x32_bf16 v[126:129], v[144:147], v[184:187], v[126:129]
	v_mfma_f32_16x16x32_bf16 v[122:125], v[156:159], v[184:187], v[122:125]
	v_mfma_f32_16x16x32_bf16 v[118:121], v[144:147], v[192:195], v[118:121]
	v_mfma_f32_16x16x32_bf16 v[114:117], v[156:159], v[192:195], v[114:117]
	v_mfma_f32_16x16x32_bf16 v[110:113], v[144:147], v[200:203], v[110:113]
	v_mfma_f32_16x16x32_bf16 v[106:109], v[156:159], v[200:203], v[106:109]
	v_mfma_f32_16x16x32_bf16 v[102:105], v[144:147], v[208:211], v[102:105]
	v_mfma_f32_16x16x32_bf16 v[98:101], v[156:159], v[208:211], v[98:101]
	v_mfma_f32_16x16x32_bf16 v[126:129], v[152:155], v[188:191], v[126:129]
	v_mfma_f32_16x16x32_bf16 v[122:125], v[160:163], v[188:191], v[122:125]
	v_mfma_f32_16x16x32_bf16 v[118:121], v[152:155], v[196:199], v[118:121]
	v_mfma_f32_16x16x32_bf16 v[114:117], v[160:163], v[196:199], v[114:117]
	v_mfma_f32_16x16x32_bf16 v[110:113], v[152:155], v[204:207], v[110:113]
	v_mfma_f32_16x16x32_bf16 v[106:109], v[160:163], v[204:207], v[106:109]
	v_mfma_f32_16x16x32_bf16 v[102:105], v[152:155], v[212:215], v[102:105]
	v_mfma_f32_16x16x32_bf16 v[98:101], v[160:163], v[212:215], v[98:101]
	v_mfma_f32_16x16x32_bf16 v[62:65], v[164:167], v[184:187], v[62:65]
	v_mfma_f32_16x16x32_bf16 v[58:61], v[172:175], v[184:187], v[58:61]
	v_mfma_f32_16x16x32_bf16 v[54:57], v[164:167], v[192:195], v[54:57]
	v_mfma_f32_16x16x32_bf16 v[50:53], v[172:175], v[192:195], v[50:53]
	v_mfma_f32_16x16x32_bf16 v[46:49], v[164:167], v[200:203], v[46:49]
	v_mfma_f32_16x16x32_bf16 v[42:45], v[172:175], v[200:203], v[42:45]
	v_mfma_f32_16x16x32_bf16 v[38:41], v[164:167], v[208:211], v[38:41]
	v_mfma_f32_16x16x32_bf16 v[34:37], v[172:175], v[208:211], v[34:37]
	v_mfma_f32_16x16x32_bf16 v[62:65], v[168:171], v[188:191], v[62:65]
	v_mfma_f32_16x16x32_bf16 v[58:61], v[180:183], v[188:191], v[58:61]
	v_mfma_f32_16x16x32_bf16 v[54:57], v[168:171], v[196:199], v[54:57]
	v_mfma_f32_16x16x32_bf16 v[50:53], v[180:183], v[196:199], v[50:53]
	v_mfma_f32_16x16x32_bf16 v[46:49], v[168:171], v[204:207], v[46:49]
	v_mfma_f32_16x16x32_bf16 v[42:45], v[180:183], v[204:207], v[42:45]
	v_mfma_f32_16x16x32_bf16 v[38:41], v[168:171], v[212:215], v[38:41]
	v_mfma_f32_16x16x32_bf16 v[34:37], v[180:183], v[212:215], v[34:37]
	s_barrier
; #define PG8_STAGE(bufoff, gbase, voff) do { _Pragma("unroll") for (int _i = 0; _i < 2; ++_i) \
;         __builtin_amdgcn_global_load_lds((const unsigned*)((const char*)(gbase) + (voff)[_i]), (LAS unsigned*)(lds + (bufoff) + ldsw + _i * 8192), 16, 0, 0); } while (0)
; #define PG8_LDA(dst, b, h) do { _Pragma("unroll") for (int m = 0; m < 4; ++m) _Pragma("unroll") for (int k = 0; k < 2; ++k) dst[m][k] = *(const LAS bf16x8*)(lds + PG8_SA(b, h) + aoff + m * 2048 + k * 1024); } while (0)
; #define PG8_MMA(ai, bj, At, Bt) do { __builtin_amdgcn_s_setprio(1); _Pragma("unroll") for (int m = 0; m < 4; ++m) _Pragma("unroll") for (int n = 0; n < 2; ++n) _Pragma("unroll") for (int k = 0; k < 2; ++k) \
;         acc[ai][bj][m][n] = __builtin_amdgcn_mfma_f32_16x16x32_bf16(Bt[n][k], At[m][k], acc[ai][bj][m][n], 0, 0, 0); __builtin_amdgcn_s_setprio(0); } while (0)
; #define PG8_WAIT_V(n) asm volatile("s_waitcnt vmcnt(" #n ")" ::: "memory")
; #define PG8_WAIT_L(n) asm volatile("s_waitcnt lgkmcnt(" #n ")" ::: "memory")
; #define PG8_BAR __builtin_amdgcn_s_barrier()
; #define PG8_SCHED __builtin_amdgcn_sched_barrier(0)
; template <class Epi, class Sched, int LDA, int LDB, bool ALIGN_EPI = true>
; __device__ __forceinline__ void gemm_phase(LAS unsigned char* lds, const Gemm g, const Sched& S, const Epi& E, int wave) {
;     ...
;             PG8_LDA(At, 1, 1); PG8_STAGE(PG8_SB(1, 0), b3, voffB); PG8_STAGE(PG8_SB(1, 1), b3 + hstepB, voffB); PG8_STAGE(PG8_SA(1, 0), a3, voffA);
;             PG8_WAIT_V(8); PG8_WAIT_L(0); PG8_BAR; PG8_MMA(1, 0, At, B0); PG8_MMA(1, 1, At, B1); PG8_BAR; PG8_SCHED;
;         }
	s_setprio 0
	ds_read_b128 v[184:187], v151 offset:49152
	ds_read_b128 v[188:191], v151 offset:50176
	ds_read_b128 v[192:195], v151 offset:51200
	ds_read_b128 v[196:199], v151 offset:52224
	ds_read_b128 v[200:203], v151 offset:53248
	ds_read_b128 v[204:207], v151 offset:54272
	ds_read_b128 v[208:211], v151 offset:55296
	ds_read_b128 v[212:215], v151 offset:56320
	s_add_i32 s18, s53, s59
	v_lshl_add_u64 v[148:149], v[148:149], 0, s[70:71]
	s_mov_b32 m0, s18
	s_nop 0
	global_load_lds_dwordx4 v[148:149], off
	s_add_i32 m0, s18, 0x2000
	s_add_u32 s16, s16, 0x20080
	v_lshl_add_u64 v[148:149], v[216:217], 0, s[70:71]
	s_addc_u32 s17, s17, 0
	s_add_i32 s18, s54, s59
	global_load_lds_dwordx4 v[148:149], off
	v_lshl_add_u64 v[148:149], s[16:17], 0, v[132:133]
	s_mov_b32 m0, s18
	s_nop 0
	global_load_lds_dwordx4 v[148:149], off
	v_lshl_add_u64 v[148:149], s[16:17], 0, v[136:137]
	s_add_i32 m0, s18, 0x2000
	s_nop 0
	global_load_lds_dwordx4 v[148:149], off
	v_lshl_add_u64 v[148:149], v[218:219], 0, s[70:71]
	s_mov_b32 m0, s46
	s_nop 0
	global_load_lds_dwordx4 v[148:149], off
	v_lshl_add_u64 v[148:149], v[220:221], 0, s[70:71]
	s_mov_b32 m0, s47
	s_nop 0
	global_load_lds_dwordx4 v[148:149], off
	s_waitcnt vmcnt(8)
	s_waitcnt lgkmcnt(0)
	s_setprio 1
	s_barrier
	v_mfma_f32_16x16x32_bf16 v[94:97], v[144:147], v[184:187], v[94:97]
	v_mfma_f32_16x16x32_bf16 v[90:93], v[156:159], v[184:187], v[90:93]
	v_mfma_f32_16x16x32_bf16 v[86:89], v[144:147], v[192:195], v[86:89]
	v_mfma_f32_16x16x32_bf16 v[82:85], v[156:159], v[192:195], v[82:85]
	v_mfma_f32_16x16x32_bf16 v[78:81], v[144:147], v[200:203], v[78:81]
	v_mfma_f32_16x16x32_bf16 v[74:77], v[156:159], v[200:203], v[74:77]
	v_mfma_f32_16x16x32_bf16 v[70:73], v[144:147], v[208:211], v[70:73]
	v_mfma_f32_16x16x32_bf16 v[66:69], v[156:159], v[208:211], v[66:69]
	v_mfma_f32_16x16x32_bf16 v[94:97], v[152:155], v[188:191], v[94:97]
	v_mfma_f32_16x16x32_bf16 v[90:93], v[160:163], v[188:191], v[90:93]
	v_mfma_f32_16x16x32_bf16 v[86:89], v[152:155], v[196:199], v[86:89]
	v_mfma_f32_16x16x32_bf16 v[82:85], v[160:163], v[196:199], v[82:85]
	v_mfma_f32_16x16x32_bf16 v[78:81], v[152:155], v[204:207], v[78:81]
	v_mfma_f32_16x16x32_bf16 v[74:77], v[160:163], v[204:207], v[74:77]
	v_mfma_f32_16x16x32_bf16 v[70:73], v[152:155], v[212:215], v[70:73]
	v_mfma_f32_16x16x32_bf16 v[66:69], v[160:163], v[212:215], v[66:69]
	v_mfma_f32_16x16x32_bf16 v[30:33], v[164:167], v[184:187], v[30:33]
	v_mfma_f32_16x16x32_bf16 v[26:29], v[172:175], v[184:187], v[26:29]
	v_mfma_f32_16x16x32_bf16 v[22:25], v[164:167], v[192:195], v[22:25]
	v_mfma_f32_16x16x32_bf16 v[18:21], v[172:175], v[192:195], v[18:21]
	v_mfma_f32_16x16x32_bf16 v[14:17], v[164:167], v[200:203], v[14:17]
	v_mfma_f32_16x16x32_bf16 v[10:13], v[172:175], v[200:203], v[10:13]
	v_mfma_f32_16x16x32_bf16 v[6:9], v[164:167], v[208:211], v[6:9]
	v_mfma_f32_16x16x32_bf16 v[2:5], v[172:175], v[208:211], v[2:5]
	v_mfma_f32_16x16x32_bf16 v[30:33], v[168:171], v[188:191], v[30:33]
	v_mfma_f32_16x16x32_bf16 v[26:29], v[180:183], v[188:191], v[26:29]
	v_mfma_f32_16x16x32_bf16 v[22:25], v[168:171], v[196:199], v[22:25]
	v_mfma_f32_16x16x32_bf16 v[18:21], v[180:183], v[196:199], v[18:21]
	v_mfma_f32_16x16x32_bf16 v[14:17], v[168:171], v[204:207], v[14:17]
	v_mfma_f32_16x16x32_bf16 v[10:13], v[180:183], v[204:207], v[10:13]
	v_mfma_f32_16x16x32_bf16 v[6:9], v[168:171], v[212:215], v[6:9]
	v_mfma_f32_16x16x32_bf16 v[2:5], v[180:183], v[212:215], v[2:5]
	s_barrier
	s_setprio 0
	s_add_i32 s52, s52, 2
	s_add_u32 s14, s14, 0x100
	s_addc_u32 s15, s15, 0
	s_add_u32 s45, s45, 0x100
	s_addc_u32 s51, s51, 0
	s_cmp_gt_u32 s52, 5
	s_cbranch_scc0 .LBB0_2619
	v_readlane_b32 s14, v252, 14
	v_readlane_b32 s15, v252, 15
	s_and_b64 vcc, exec, s[14:15]
	s_cbranch_vccz .LBB0_2622
	s_barrier

; #define PG8_STAGE(bufoff, gbase, voff) do { _Pragma("unroll") for (int _i = 0; _i < 2; ++_i) \
;         __builtin_amdgcn_global_load_lds((const unsigned*)((const char*)(gbase) + (voff)[_i]), (LAS unsigned*)(lds + (bufoff) + ldsw + _i * 8192), 16, 0, 0); } while (0)
; #define PG8_LDA(dst, b, h) do { _Pragma("unroll") for (int m = 0; m < 4; ++m) _Pragma("unroll") for (int k = 0; k < 2; ++k) dst[m][k] = *(const LAS bf16x8*)(lds + PG8_SA(b, h) + aoff + m * 2048 + k * 1024); } while (0)
; #define PG8_LDB(dst, b, h) do { _Pragma("unroll") for (int n = 0; n < 2; ++n) _Pragma("unroll") for (int k = 0; k < 2; ++k) dst[n][k] = *(const LAS bf16x8*)(lds + PG8_SB(b, h) + boff + n * 2048 + k * 1024); } while (0)
; #define PG8_MMA(ai, bj, At, Bt) do { __builtin_amdgcn_s_setprio(1); _Pragma("unroll") for (int m = 0; m < 4; ++m) _Pragma("unroll") for (int n = 0; n < 2; ++n) _Pragma("unroll") for (int k = 0; k < 2; ++k) \
;         acc[ai][bj][m][n] = __builtin_amdgcn_mfma_f32_16x16x32_bf16(Bt[n][k], At[m][k], acc[ai][bj][m][n], 0, 0, 0); __builtin_amdgcn_s_setprio(0); } while (0)
; #define PG8_WAIT_V(n) asm volatile("s_waitcnt vmcnt(" #n ")" ::: "memory")
; #define PG8_WAIT_L(n) asm volatile("s_waitcnt lgkmcnt(" #n ")" ::: "memory")
; #define PG8_BAR __builtin_amdgcn_s_barrier()
; #define PG8_SCHED __builtin_amdgcn_sched_barrier(0)
; template <class Epi, class Sched, int LDA, int LDB, bool ALIGN_EPI = true>
; __device__ __forceinline__ void gemm_phase(LAS unsigned char* lds, const Gemm g, const Sched& S, const Epi& E, int wave) {
;     ...
;             PG8_LDB(B0, 0, 0); PG8_LDB(B1, 0, 1); PG8_SCHED; PG8_LDA(At, 0, 0); PG8_STAGE(PG8_SA(1, 1), a1 + hstepA, voffA);
;             PG8_WAIT_V(8); PG8_WAIT_L(0); PG8_BAR; PG8_MMA(0, 0, At, B0); PG8_MMA(0, 1, At, B1); PG8_BAR; PG8_SCHED;
;             PG8_LDA(At, 0, 1); PG8_STAGE(PG8_SB(0, 0), b2, voffB); PG8_STAGE(PG8_SB(0, 1), b2 + hstepB, voffB); PG8_STAGE(PG8_SA(0, 0), a2, voffA);
;             PG8_WAIT_V(8); PG8_WAIT_L(0); PG8_BAR; PG8_MMA(1, 0, At, B0); PG8_MMA(1, 1, At, B1); PG8_BAR; PG8_SCHED;
.LBB0_2649:
	ds_read_b128 v[180:183], v163
	ds_read_b128 v[184:187], v163 offset:1024
	ds_read_b128 v[188:191], v163 offset:2048
	ds_read_b128 v[192:195], v163 offset:3072
	ds_read_b128 v[196:199], v163 offset:4096
	ds_read_b128 v[200:203], v163 offset:5120
	ds_read_b128 v[204:207], v163 offset:6144
	ds_read_b128 v[208:211], v163 offset:7168
	s_add_u32 s18, s16, 0xfffe0080
	s_addc_u32 s19, s17, -1
	s_add_i32 s48, 0, 0x10000
	s_cmp_eq_u32 s47, 4
	s_cselect_b32 s25, s7, s19
	s_cselect_b32 s24, s13, s18
	s_cselect_b32 s19, s3, s46
	s_cselect_b32 s18, s44, s45
	s_add_i32 s50, 0, 0x14000
	v_add_u32_e32 v152, s48, v161
	v_add_u32_e32 v172, s50, v161
	ds_read_b128 v[130:133], v152
	ds_read_b128 v[134:137], v152 offset:1024
	ds_read_b128 v[148:151], v152 offset:2048
	ds_read_b128 v[152:155], v152 offset:3072
	ds_read_b128 v[156:159], v172
	ds_read_b128 v[164:167], v172 offset:1024
	ds_read_b128 v[168:171], v172 offset:2048
	ds_read_b128 v[172:175], v172 offset:3072
	v_lshl_add_u64 v[212:213], s[16:17], 0, v[144:145]
	s_add_i32 m0, s15, 0xc000
	s_nop 0
	global_load_lds_dwordx4 v[212:213], off
	v_lshl_add_u64 v[212:213], s[16:17], 0, v[146:147]
	s_add_i32 m0, s15, 0xe000
	s_nop 0
	global_load_lds_dwordx4 v[212:213], off
	s_waitcnt vmcnt(8)
	s_waitcnt lgkmcnt(0)
	s_setprio 1
	s_barrier
	v_mfma_f32_16x16x32_bf16 v[126:129], v[130:133], v[180:183], v[126:129]
	v_mfma_f32_16x16x32_bf16 v[122:125], v[148:151], v[180:183], v[122:125]
	v_mfma_f32_16x16x32_bf16 v[110:113], v[130:133], v[188:191], v[110:113]
	v_mfma_f32_16x16x32_bf16 v[106:109], v[148:151], v[188:191], v[106:109]
	v_mfma_f32_16x16x32_bf16 v[94:97], v[130:133], v[196:199], v[94:97]
	v_mfma_f32_16x16x32_bf16 v[90:93], v[148:151], v[196:199], v[90:93]
	v_mfma_f32_16x16x32_bf16 v[78:81], v[130:133], v[204:207], v[78:81]
	v_mfma_f32_16x16x32_bf16 v[74:77], v[148:151], v[204:207], v[74:77]
	v_mfma_f32_16x16x32_bf16 v[126:129], v[134:137], v[184:187], v[126:129]
	v_mfma_f32_16x16x32_bf16 v[122:125], v[152:155], v[184:187], v[122:125]
	v_mfma_f32_16x16x32_bf16 v[110:113], v[134:137], v[192:195], v[110:113]
	v_mfma_f32_16x16x32_bf16 v[106:109], v[152:155], v[192:195], v[106:109]
	v_mfma_f32_16x16x32_bf16 v[94:97], v[134:137], v[200:203], v[94:97]
	v_mfma_f32_16x16x32_bf16 v[90:93], v[152:155], v[200:203], v[90:93]
	v_mfma_f32_16x16x32_bf16 v[78:81], v[134:137], v[208:211], v[78:81]
	v_mfma_f32_16x16x32_bf16 v[74:77], v[152:155], v[208:211], v[74:77]
	v_mfma_f32_16x16x32_bf16 v[118:121], v[156:159], v[180:183], v[118:121]
	v_mfma_f32_16x16x32_bf16 v[114:117], v[168:171], v[180:183], v[114:117]
	v_mfma_f32_16x16x32_bf16 v[102:105], v[156:159], v[188:191], v[102:105]
	v_mfma_f32_16x16x32_bf16 v[98:101], v[168:171], v[188:191], v[98:101]
	v_mfma_f32_16x16x32_bf16 v[86:89], v[156:159], v[196:199], v[86:89]
	v_mfma_f32_16x16x32_bf16 v[82:85], v[168:171], v[196:199], v[82:85]
	v_mfma_f32_16x16x32_bf16 v[70:73], v[156:159], v[204:207], v[70:73]
	v_mfma_f32_16x16x32_bf16 v[66:69], v[168:171], v[204:207], v[66:69]
	v_mfma_f32_16x16x32_bf16 v[118:121], v[164:167], v[184:187], v[118:121]
	v_mfma_f32_16x16x32_bf16 v[114:117], v[172:175], v[184:187], v[114:117]
	v_mfma_f32_16x16x32_bf16 v[102:105], v[164:167], v[192:195], v[102:105]
	v_mfma_f32_16x16x32_bf16 v[98:101], v[172:175], v[192:195], v[98:101]
	v_mfma_f32_16x16x32_bf16 v[86:89], v[164:167], v[200:203], v[86:89]
	v_mfma_f32_16x16x32_bf16 v[82:85], v[172:175], v[200:203], v[82:85]
	v_mfma_f32_16x16x32_bf16 v[70:73], v[164:167], v[208:211], v[70:73]
	v_mfma_f32_16x16x32_bf16 v[66:69], v[172:175], v[208:211], v[66:69]
	s_barrier
	s_setprio 0
	ds_read_b128 v[180:183], v163 offset:16384
	ds_read_b128 v[184:187], v163 offset:17408
	ds_read_b128 v[188:191], v163 offset:18432
	ds_read_b128 v[192:195], v163 offset:19456
	ds_read_b128 v[196:199], v163 offset:20480
	ds_read_b128 v[200:203], v163 offset:21504
	ds_read_b128 v[204:207], v163 offset:22528
	ds_read_b128 v[208:211], v163 offset:23552
	s_add_i32 s48, s48, s51
	v_lshl_add_u64 v[212:213], s[18:19], 0, v[0:1]
	s_mov_b32 m0, s48
	s_nop 0
	global_load_lds_dwordx4 v[212:213], off
	s_add_i32 m0, s48, 0x2000
	s_add_u32 s48, s18, 0x20000
	v_lshl_add_u64 v[214:215], s[18:19], 0, v[142:143]
	s_addc_u32 s49, s19, 0
	s_add_i32 s50, s50, s51
	global_load_lds_dwordx4 v[214:215], off
	v_lshl_add_u64 v[216:217], s[48:49], 0, v[0:1]
	s_mov_b32 m0, s50
	v_lshl_add_u64 v[218:219], s[24:25], 0, v[140:141]
	global_load_lds_dwordx4 v[216:217], off
	v_lshl_add_u64 v[216:217], s[48:49], 0, v[142:143]
	s_add_i32 m0, s50, 0x2000
	s_nop 0
	global_load_lds_dwordx4 v[216:217], off
	v_lshl_add_u64 v[216:217], s[24:25], 0, v[138:139]
	s_mov_b32 m0, s15
	s_nop 0
	global_load_lds_dwordx4 v[216:217], off
	s_mov_b32 m0, s28
	s_nop 0
	global_load_lds_dwordx4 v[218:219], off
	s_waitcnt vmcnt(8)
	s_waitcnt lgkmcnt(0)
	s_setprio 1
	s_barrier
; #define PG8_STAGE(bufoff, gbase, voff) do { _Pragma("unroll") for (int _i = 0; _i < 2; ++_i) \
;         __builtin_amdgcn_global_load_lds((const unsigned*)((const char*)(gbase) + (voff)[_i]), (LAS unsigned*)(lds + (bufoff) + ldsw + _i * 8192), 16, 0, 0); } while (0)
; #define PG8_LDA(dst, b, h) do { _Pragma("unroll") for (int m = 0; m < 4; ++m) _Pragma("unroll") for (int k = 0; k < 2; ++k) dst[m][k] = *(const LAS bf16x8*)(lds + PG8_SA(b, h) + aoff + m * 2048 + k * 1024); } while (0)
; #define PG8_LDB(dst, b, h) do { _Pragma("unroll") for (int n = 0; n < 2; ++n) _Pragma("unroll") for (int k = 0; k < 2; ++k) dst[n][k] = *(const LAS bf16x8*)(lds + PG8_SB(b, h) + boff + n * 2048 + k * 1024); } while (0)
; #define PG8_MMA(ai, bj, At, Bt) do { __builtin_amdgcn_s_setprio(1); _Pragma("unroll") for (int m = 0; m < 4; ++m) _Pragma("unroll") for (int n = 0; n < 2; ++n) _Pragma("unroll") for (int k = 0; k < 2; ++k) \
;         acc[ai][bj][m][n] = __builtin_amdgcn_mfma_f32_16x16x32_bf16(Bt[n][k], At[m][k], acc[ai][bj][m][n], 0, 0, 0); __builtin_amdgcn_s_setprio(0); } while (0)
; #define PG8_WAIT_V(n) asm volatile("s_waitcnt vmcnt(" #n ")" ::: "memory")
; #define PG8_WAIT_L(n) asm volatile("s_waitcnt lgkmcnt(" #n ")" ::: "memory")
; #define PG8_BAR __builtin_amdgcn_s_barrier()
; #define PG8_SCHED __builtin_amdgcn_sched_barrier(0)
; template <class Epi, class Sched, int LDA, int LDB, bool ALIGN_EPI = true>
; __device__ __forceinline__ void gemm_phase(LAS unsigned char* lds, const Gemm g, const Sched& S, const Epi& E, int wave) {
;     ...
;             PG8_WAIT_V(8); PG8_WAIT_L(0); PG8_BAR; PG8_MMA(1, 0, At, B0); PG8_MMA(1, 1, At, B1); PG8_BAR; PG8_SCHED;
;             PG8_LDB(B0, 1, 0); PG8_LDB(B1, 1, 1); PG8_SCHED; PG8_LDA(At, 1, 0); PG8_STAGE(PG8_SA(0, 1), a2 + hstepA, voffA);
;             PG8_WAIT_V(8); PG8_WAIT_L(0); PG8_BAR; PG8_MMA(0, 0, At, B0); PG8_MMA(0, 1, At, B1); PG8_BAR; PG8_SCHED;
	v_mfma_f32_16x16x32_bf16 v[62:65], v[130:133], v[180:183], v[62:65]
	v_mfma_f32_16x16x32_bf16 v[58:61], v[148:151], v[180:183], v[58:61]
	v_mfma_f32_16x16x32_bf16 v[46:49], v[130:133], v[188:191], v[46:49]
	v_mfma_f32_16x16x32_bf16 v[42:45], v[148:151], v[188:191], v[42:45]
	v_mfma_f32_16x16x32_bf16 v[30:33], v[130:133], v[196:199], v[30:33]
	v_mfma_f32_16x16x32_bf16 v[26:29], v[148:151], v[196:199], v[26:29]
	v_mfma_f32_16x16x32_bf16 v[14:17], v[130:133], v[204:207], v[14:17]
	v_mfma_f32_16x16x32_bf16 v[10:13], v[148:151], v[204:207], v[10:13]
	v_mfma_f32_16x16x32_bf16 v[62:65], v[134:137], v[184:187], v[62:65]
	v_mfma_f32_16x16x32_bf16 v[58:61], v[152:155], v[184:187], v[58:61]
	v_mfma_f32_16x16x32_bf16 v[46:49], v[134:137], v[192:195], v[46:49]
	v_mfma_f32_16x16x32_bf16 v[42:45], v[152:155], v[192:195], v[42:45]
	v_mfma_f32_16x16x32_bf16 v[30:33], v[134:137], v[200:203], v[30:33]
	v_mfma_f32_16x16x32_bf16 v[26:29], v[152:155], v[200:203], v[26:29]
	v_mfma_f32_16x16x32_bf16 v[14:17], v[134:137], v[208:211], v[14:17]
	v_mfma_f32_16x16x32_bf16 v[10:13], v[152:155], v[208:211], v[10:13]
	v_mfma_f32_16x16x32_bf16 v[54:57], v[156:159], v[180:183], v[54:57]
	v_mfma_f32_16x16x32_bf16 v[50:53], v[168:171], v[180:183], v[50:53]
	v_mfma_f32_16x16x32_bf16 v[38:41], v[156:159], v[188:191], v[38:41]
	v_mfma_f32_16x16x32_bf16 v[34:37], v[168:171], v[188:191], v[34:37]
	v_mfma_f32_16x16x32_bf16 v[22:25], v[156:159], v[196:199], v[22:25]
	v_mfma_f32_16x16x32_bf16 v[18:21], v[168:171], v[196:199], v[18:21]
	v_mfma_f32_16x16x32_bf16 v[6:9], v[156:159], v[204:207], v[6:9]
	v_mfma_f32_16x16x32_bf16 v[2:5], v[168:171], v[204:207], v[2:5]
	v_mfma_f32_16x16x32_bf16 v[54:57], v[164:167], v[184:187], v[54:57]
	v_mfma_f32_16x16x32_bf16 v[50:53], v[172:175], v[184:187], v[50:53]
	v_mfma_f32_16x16x32_bf16 v[38:41], v[164:167], v[192:195], v[38:41]
	v_mfma_f32_16x16x32_bf16 v[34:37], v[172:175], v[192:195], v[34:37]
	v_mfma_f32_16x16x32_bf16 v[22:25], v[164:167], v[200:203], v[22:25]
	v_mfma_f32_16x16x32_bf16 v[18:21], v[172:175], v[200:203], v[18:21]
	v_mfma_f32_16x16x32_bf16 v[6:9], v[164:167], v[208:211], v[6:9]
	v_mfma_f32_16x16x32_bf16 v[2:5], v[172:175], v[208:211], v[2:5]
	s_barrier
	s_setprio 0
	ds_read_b128 v[180:183], v163 offset:32768
	ds_read_b128 v[184:187], v163 offset:33792
	ds_read_b128 v[188:191], v163 offset:34816
	ds_read_b128 v[192:195], v163 offset:35840
	ds_read_b128 v[196:199], v163 offset:36864
	ds_read_b128 v[200:203], v163 offset:37888
	ds_read_b128 v[204:207], v163 offset:38912
	ds_read_b128 v[208:211], v163 offset:39936
	s_add_i32 s48, 0, 0x18000
	s_add_i32 s49, 0, 0x1c000
	v_add_u32_e32 v152, s48, v161
	v_add_u32_e32 v172, s49, v161
	ds_read_b128 v[130:133], v152
	ds_read_b128 v[134:137], v152 offset:1024
	ds_read_b128 v[148:151], v152 offset:2048
	ds_read_b128 v[152:155], v152 offset:3072
	ds_read_b128 v[156:159], v172
	ds_read_b128 v[164:167], v172 offset:1024
	ds_read_b128 v[168:171], v172 offset:2048
	ds_read_b128 v[172:175], v172 offset:3072
	s_add_u32 s24, s24, 0x20000
	s_addc_u32 s25, s25, 0
	s_mov_b32 m0, s29
	v_lshl_add_u64 v[220:221], s[24:25], 0, v[138:139]
	global_load_lds_dwordx4 v[220:221], off
	v_lshl_add_u64 v[220:221], s[24:25], 0, v[140:141]
	s_mov_b32 m0, s34
	s_nop 0
	global_load_lds_dwordx4 v[220:221], off
	s_waitcnt vmcnt(8)
	s_waitcnt lgkmcnt(0)
	s_setprio 1
	s_barrier
	v_mfma_f32_16x16x32_bf16 v[126:129], v[130:133], v[180:183], v[126:129]
	v_mfma_f32_16x16x32_bf16 v[122:125], v[148:151], v[180:183], v[122:125]
	v_mfma_f32_16x16x32_bf16 v[110:113], v[130:133], v[188:191], v[110:113]
	v_mfma_f32_16x16x32_bf16 v[106:109], v[148:151], v[188:191], v[106:109]
	v_mfma_f32_16x16x32_bf16 v[94:97], v[130:133], v[196:199], v[94:97]
	v_mfma_f32_16x16x32_bf16 v[90:93], v[148:151], v[196:199], v[90:93]
	v_mfma_f32_16x16x32_bf16 v[78:81], v[130:133], v[204:207], v[78:81]
	v_mfma_f32_16x16x32_bf16 v[74:77], v[148:151], v[204:207], v[74:77]
	v_mfma_f32_16x16x32_bf16 v[126:129], v[134:137], v[184:187], v[126:129]
	v_mfma_f32_16x16x32_bf16 v[122:125], v[152:155], v[184:187], v[122:125]
	v_mfma_f32_16x16x32_bf16 v[110:113], v[134:137], v[192:195], v[110:113]
	v_mfma_f32_16x16x32_bf16 v[106:109], v[152:155], v[192:195], v[106:109]
	v_mfma_f32_16x16x32_bf16 v[94:97], v[134:137], v[200:203], v[94:97]
	v_mfma_f32_16x16x32_bf16 v[90:93], v[152:155], v[200:203], v[90:93]
	v_mfma_f32_16x16x32_bf16 v[78:81], v[134:137], v[208:211], v[78:81]
	v_mfma_f32_16x16x32_bf16 v[74:77], v[152:155], v[208:211], v[74:77]
	v_mfma_f32_16x16x32_bf16 v[118:121], v[156:159], v[180:183], v[118:121]
	v_mfma_f32_16x16x32_bf16 v[114:117], v[168:171], v[180:183], v[114:117]
	v_mfma_f32_16x16x32_bf16 v[102:105], v[156:159], v[188:191], v[102:105]
	v_mfma_f32_16x16x32_bf16 v[98:101], v[168:171], v[188:191], v[98:101]
	v_mfma_f32_16x16x32_bf16 v[86:89], v[156:159], v[196:199], v[86:89]
	v_mfma_f32_16x16x32_bf16 v[82:85], v[168:171], v[196:199], v[82:85]
	v_mfma_f32_16x16x32_bf16 v[70:73], v[156:159], v[204:207], v[70:73]
	v_mfma_f32_16x16x32_bf16 v[66:69], v[168:171], v[204:207], v[66:69]
	v_mfma_f32_16x16x32_bf16 v[118:121], v[164:167], v[184:187], v[118:121]
	v_mfma_f32_16x16x32_bf16 v[114:117], v[172:175], v[184:187], v[114:117]
	v_mfma_f32_16x16x32_bf16 v[102:105], v[164:167], v[192:195], v[102:105]
	v_mfma_f32_16x16x32_bf16 v[98:101], v[172:175], v[192:195], v[98:101]
	v_mfma_f32_16x16x32_bf16 v[86:89], v[164:167], v[200:203], v[86:89]
	v_mfma_f32_16x16x32_bf16 v[82:85], v[172:175], v[200:203], v[82:85]
	v_mfma_f32_16x16x32_bf16 v[70:73], v[164:167], v[208:211], v[70:73]
	v_mfma_f32_16x16x32_bf16 v[66:69], v[172:175], v[208:211], v[66:69]
	s_barrier
; #define PG8_STAGE(bufoff, gbase, voff) do { _Pragma("unroll") for (int _i = 0; _i < 2; ++_i) \
;         __builtin_amdgcn_global_load_lds((const unsigned*)((const char*)(gbase) + (voff)[_i]), (LAS unsigned*)(lds + (bufoff) + ldsw + _i * 8192), 16, 0, 0); } while (0)
; #define PG8_LDA(dst, b, h) do { _Pragma("unroll") for (int m = 0; m < 4; ++m) _Pragma("unroll") for (int k = 0; k < 2; ++k) dst[m][k] = *(const LAS bf16x8*)(lds + PG8_SA(b, h) + aoff + m * 2048 + k * 1024); } while (0)
; #define PG8_MMA(ai, bj, At, Bt) do { __builtin_amdgcn_s_setprio(1); _Pragma("unroll") for (int m = 0; m < 4; ++m) _Pragma("unroll") for (int n = 0; n < 2; ++n) _Pragma("unroll") for (int k = 0; k < 2; ++k) \
;         acc[ai][bj][m][n] = __builtin_amdgcn_mfma_f32_16x16x32_bf16(Bt[n][k], At[m][k], acc[ai][bj][m][n], 0, 0, 0); __builtin_amdgcn_s_setprio(0); } while (0)
; #define PG8_WAIT_V(n) asm volatile("s_waitcnt vmcnt(" #n ")" ::: "memory")
; #define PG8_WAIT_L(n) asm volatile("s_waitcnt lgkmcnt(" #n ")" ::: "memory")
; #define PG8_BAR __builtin_amdgcn_s_barrier()
; #define PG8_SCHED __builtin_amdgcn_sched_barrier(0)
; template <class Epi, class Sched, int LDA, int LDB, bool ALIGN_EPI = true>
; __device__ __forceinline__ void gemm_phase(LAS unsigned char* lds, const Gemm g, const Sched& S, const Epi& E, int wave) {
;     ...
;             PG8_LDA(At, 1, 1); PG8_STAGE(PG8_SB(1, 0), b3, voffB); PG8_STAGE(PG8_SB(1, 1), b3 + hstepB, voffB); PG8_STAGE(PG8_SA(1, 0), a3, voffA);
;             PG8_WAIT_V(8); PG8_WAIT_L(0); PG8_BAR; PG8_MMA(1, 0, At, B0); PG8_MMA(1, 1, At, B1); PG8_BAR; PG8_SCHED;
;         }
	s_setprio 0
	ds_read_b128 v[180:183], v163 offset:49152
	ds_read_b128 v[184:187], v163 offset:50176
	ds_read_b128 v[188:191], v163 offset:51200
	ds_read_b128 v[192:195], v163 offset:52224
	ds_read_b128 v[196:199], v163 offset:53248
	ds_read_b128 v[200:203], v163 offset:54272
	ds_read_b128 v[204:207], v163 offset:55296
	ds_read_b128 v[208:211], v163 offset:56320
	s_add_i32 s24, s48, s51
	v_lshl_add_u64 v[212:213], v[212:213], 0, s[52:53]
	s_mov_b32 m0, s24
	s_nop 0
	global_load_lds_dwordx4 v[212:213], off
	s_add_i32 m0, s24, 0x2000
	s_add_u32 s18, s18, 0x20080
	v_lshl_add_u64 v[212:213], v[214:215], 0, s[52:53]
	s_addc_u32 s19, s19, 0
	s_add_i32 s24, s49, s51
	global_load_lds_dwordx4 v[212:213], off
	v_lshl_add_u64 v[212:213], s[18:19], 0, v[0:1]
	s_mov_b32 m0, s24
	s_nop 0
	global_load_lds_dwordx4 v[212:213], off
	v_lshl_add_u64 v[212:213], s[18:19], 0, v[142:143]
	s_add_i32 m0, s24, 0x2000
	s_nop 0
	global_load_lds_dwordx4 v[212:213], off
	v_lshl_add_u64 v[212:213], v[216:217], 0, s[52:53]
	s_mov_b32 m0, s35
	s_nop 0
	global_load_lds_dwordx4 v[212:213], off
	v_lshl_add_u64 v[212:213], v[218:219], 0, s[52:53]
	s_mov_b32 m0, s36
	s_nop 0
	global_load_lds_dwordx4 v[212:213], off
	s_waitcnt vmcnt(8)
	s_waitcnt lgkmcnt(0)
	s_setprio 1
	s_barrier
	v_mfma_f32_16x16x32_bf16 v[62:65], v[130:133], v[180:183], v[62:65]
	v_mfma_f32_16x16x32_bf16 v[58:61], v[148:151], v[180:183], v[58:61]
	v_mfma_f32_16x16x32_bf16 v[46:49], v[130:133], v[188:191], v[46:49]
	v_mfma_f32_16x16x32_bf16 v[42:45], v[148:151], v[188:191], v[42:45]
	v_mfma_f32_16x16x32_bf16 v[30:33], v[130:133], v[196:199], v[30:33]
	v_mfma_f32_16x16x32_bf16 v[26:29], v[148:151], v[196:199], v[26:29]
	v_mfma_f32_16x16x32_bf16 v[14:17], v[130:133], v[204:207], v[14:17]
	v_mfma_f32_16x16x32_bf16 v[10:13], v[148:151], v[204:207], v[10:13]
	v_mfma_f32_16x16x32_bf16 v[62:65], v[134:137], v[184:187], v[62:65]
	v_mfma_f32_16x16x32_bf16 v[58:61], v[152:155], v[184:187], v[58:61]
	v_mfma_f32_16x16x32_bf16 v[46:49], v[134:137], v[192:195], v[46:49]
	v_mfma_f32_16x16x32_bf16 v[42:45], v[152:155], v[192:195], v[42:45]
	v_mfma_f32_16x16x32_bf16 v[30:33], v[134:137], v[200:203], v[30:33]
	v_mfma_f32_16x16x32_bf16 v[26:29], v[152:155], v[200:203], v[26:29]
	v_mfma_f32_16x16x32_bf16 v[14:17], v[134:137], v[208:211], v[14:17]
	v_mfma_f32_16x16x32_bf16 v[10:13], v[152:155], v[208:211], v[10:13]
	v_mfma_f32_16x16x32_bf16 v[54:57], v[156:159], v[180:183], v[54:57]
	v_mfma_f32_16x16x32_bf16 v[50:53], v[168:171], v[180:183], v[50:53]
	v_mfma_f32_16x16x32_bf16 v[38:41], v[156:159], v[188:191], v[38:41]
	v_mfma_f32_16x16x32_bf16 v[34:37], v[168:171], v[188:191], v[34:37]
	v_mfma_f32_16x16x32_bf16 v[22:25], v[156:159], v[196:199], v[22:25]
	v_mfma_f32_16x16x32_bf16 v[18:21], v[168:171], v[196:199], v[18:21]
	v_mfma_f32_16x16x32_bf16 v[6:9], v[156:159], v[204:207], v[6:9]
	v_mfma_f32_16x16x32_bf16 v[2:5], v[168:171], v[204:207], v[2:5]
	v_mfma_f32_16x16x32_bf16 v[54:57], v[164:167], v[184:187], v[54:57]
	v_mfma_f32_16x16x32_bf16 v[50:53], v[172:175], v[184:187], v[50:53]
	v_mfma_f32_16x16x32_bf16 v[38:41], v[164:167], v[192:195], v[38:41]
	v_mfma_f32_16x16x32_bf16 v[34:37], v[172:175], v[192:195], v[34:37]
	v_mfma_f32_16x16x32_bf16 v[22:25], v[164:167], v[200:203], v[22:25]
	v_mfma_f32_16x16x32_bf16 v[18:21], v[172:175], v[200:203], v[18:21]
	v_mfma_f32_16x16x32_bf16 v[6:9], v[164:167], v[208:211], v[6:9]
	v_mfma_f32_16x16x32_bf16 v[2:5], v[172:175], v[208:211], v[2:5]
	s_barrier
	s_setprio 0
	s_add_i32 s47, s47, 2
	s_add_u32 s16, s16, 0x100
	s_addc_u32 s17, s17, 0
	s_add_u32 s45, s45, 0x100
	s_addc_u32 s46, s46, 0
	s_cmp_gt_u32 s47, 5
	s_cbranch_scc0 .LBB0_2649
	v_readlane_b32 s16, v252, 14
	v_readlane_b32 s17, v252, 15
	s_and_b64 vcc, exec, s[16:17]
	s_cbranch_vccz .LBB0_2652
	s_barrier

; #define PG8_STAGE(bufoff, gbase, voff) do { _Pragma("unroll") for (int _i = 0; _i < 2; ++_i) \
;         __builtin_amdgcn_global_load_lds((const unsigned*)((const char*)(gbase) + (voff)[_i]), (LAS unsigned*)(lds + (bufoff) + ldsw + _i * 8192), 16, 0, 0); } while (0)
; #define PG8_LDA(dst, b, h) do { _Pragma("unroll") for (int m = 0; m < 4; ++m) _Pragma("unroll") for (int k = 0; k < 2; ++k) dst[m][k] = *(const LAS bf16x8*)(lds + PG8_SA(b, h) + aoff + m * 2048 + k * 1024); } while (0)
; #define PG8_LDB(dst, b, h) do { _Pragma("unroll") for (int n = 0; n < 2; ++n) _Pragma("unroll") for (int k = 0; k < 2; ++k) dst[n][k] = *(const LAS bf16x8*)(lds + PG8_SB(b, h) + boff + n * 2048 + k * 1024); } while (0)
; #define PG8_MMA(ai, bj, At, Bt) do { __builtin_amdgcn_s_setprio(1); _Pragma("unroll") for (int m = 0; m < 4; ++m) _Pragma("unroll") for (int n = 0; n < 2; ++n) _Pragma("unroll") for (int k = 0; k < 2; ++k) \
;         acc[ai][bj][m][n] = __builtin_amdgcn_mfma_f32_16x16x32_bf16(Bt[n][k], At[m][k], acc[ai][bj][m][n], 0, 0, 0); __builtin_amdgcn_s_setprio(0); } while (0)
; #define PG8_WAIT_V(n) asm volatile("s_waitcnt vmcnt(" #n ")" ::: "memory")
; #define PG8_WAIT_L(n) asm volatile("s_waitcnt lgkmcnt(" #n ")" ::: "memory")
; #define PG8_BAR __builtin_amdgcn_s_barrier()
; #define PG8_SCHED __builtin_amdgcn_sched_barrier(0)
; template <class Epi, class Sched, int LDA, int LDB, bool ALIGN_EPI = true>
; __device__ __forceinline__ void gemm_phase(LAS unsigned char* lds, const Gemm g, const Sched& S, const Epi& E, int wave) {
;     ...
;             PG8_LDB(B0, 0, 0); PG8_LDB(B1, 0, 1); PG8_SCHED; PG8_LDA(At, 0, 0); PG8_STAGE(PG8_SA(1, 1), a1 + hstepA, voffA);
;             PG8_WAIT_V(8); PG8_WAIT_L(0); PG8_BAR; PG8_MMA(0, 0, At, B0); PG8_MMA(0, 1, At, B1); PG8_BAR; PG8_SCHED;
;             PG8_LDA(At, 0, 1); PG8_STAGE(PG8_SB(0, 0), b2, voffB); PG8_STAGE(PG8_SB(0, 1), b2 + hstepB, voffB); PG8_STAGE(PG8_SA(0, 0), a2, voffA);
;             PG8_WAIT_V(8); PG8_WAIT_L(0); PG8_BAR; PG8_MMA(1, 0, At, B0); PG8_MMA(1, 1, At, B1); PG8_BAR; PG8_SCHED;
.LBB0_4715:
	ds_read_b128 v[184:187], v155
	ds_read_b128 v[188:191], v155 offset:1024
	ds_read_b128 v[192:195], v155 offset:2048
	ds_read_b128 v[196:199], v155 offset:3072
	ds_read_b128 v[200:203], v155 offset:4096
	ds_read_b128 v[204:207], v155 offset:5120
	ds_read_b128 v[208:211], v155 offset:6144
	ds_read_b128 v[212:215], v155 offset:7168
	s_add_i32 s49, s24, 2
	s_add_u32 s25, s18, 0xfff80080
	s_addc_u32 s28, s19, -1
	s_add_i32 s50, 0, 0x10000
	s_cmp_eq_u32 s17, s24
	s_cselect_b32 s29, s1, s28
	s_cselect_b32 s28, s7, s25
	v_add_u32_e32 v0, s50, v153
	s_cselect_b32 s25, s3, s45
	s_cselect_b32 s24, s15, s44
	s_add_i32 s52, 0, 0x14000
	ds_read_b128 v[144:147], v0
	ds_read_b128 v[148:151], v0 offset:1024
	ds_read_b128 v[156:159], v0 offset:2048
	ds_read_b128 v[160:163], v0 offset:3072
	v_add_u32_e32 v0, s52, v153
	ds_read_b128 v[164:167], v0
	ds_read_b128 v[168:171], v0 offset:1024
	ds_read_b128 v[172:175], v0 offset:2048
	ds_read_b128 v[180:183], v0 offset:3072
	v_lshl_add_u64 v[216:217], s[18:19], 0, v[140:141]
	s_add_i32 m0, s27, 0xc000
	s_nop 0
	global_load_lds_dwordx4 v[216:217], off
	v_lshl_add_u64 v[216:217], s[18:19], 0, v[142:143]
	s_add_i32 m0, s27, 0xe000
	s_nop 0
	global_load_lds_dwordx4 v[216:217], off
	s_waitcnt vmcnt(8)
	s_waitcnt lgkmcnt(0)
	s_setprio 1
	s_barrier
	v_mfma_f32_16x16x32_bf16 v[126:129], v[144:147], v[184:187], v[126:129]
	v_mfma_f32_16x16x32_bf16 v[122:125], v[156:159], v[184:187], v[122:125]
	v_mfma_f32_16x16x32_bf16 v[110:113], v[144:147], v[192:195], v[110:113]
	v_mfma_f32_16x16x32_bf16 v[106:109], v[156:159], v[192:195], v[106:109]
	v_mfma_f32_16x16x32_bf16 v[94:97], v[144:147], v[200:203], v[94:97]
	v_mfma_f32_16x16x32_bf16 v[90:93], v[156:159], v[200:203], v[90:93]
	v_mfma_f32_16x16x32_bf16 v[78:81], v[144:147], v[208:211], v[78:81]
	v_mfma_f32_16x16x32_bf16 v[74:77], v[156:159], v[208:211], v[74:77]
	v_mfma_f32_16x16x32_bf16 v[126:129], v[148:151], v[188:191], v[126:129]
	v_mfma_f32_16x16x32_bf16 v[122:125], v[160:163], v[188:191], v[122:125]
	v_mfma_f32_16x16x32_bf16 v[110:113], v[148:151], v[196:199], v[110:113]
	v_mfma_f32_16x16x32_bf16 v[106:109], v[160:163], v[196:199], v[106:109]
	v_mfma_f32_16x16x32_bf16 v[94:97], v[148:151], v[204:207], v[94:97]
	v_mfma_f32_16x16x32_bf16 v[90:93], v[160:163], v[204:207], v[90:93]
	v_mfma_f32_16x16x32_bf16 v[78:81], v[148:151], v[212:215], v[78:81]
	v_mfma_f32_16x16x32_bf16 v[74:77], v[160:163], v[212:215], v[74:77]
	v_mfma_f32_16x16x32_bf16 v[118:121], v[164:167], v[184:187], v[118:121]
	v_mfma_f32_16x16x32_bf16 v[114:117], v[172:175], v[184:187], v[114:117]
	v_mfma_f32_16x16x32_bf16 v[102:105], v[164:167], v[192:195], v[102:105]
	v_mfma_f32_16x16x32_bf16 v[98:101], v[172:175], v[192:195], v[98:101]
	v_mfma_f32_16x16x32_bf16 v[86:89], v[164:167], v[200:203], v[86:89]
	v_mfma_f32_16x16x32_bf16 v[82:85], v[172:175], v[200:203], v[82:85]
	v_mfma_f32_16x16x32_bf16 v[70:73], v[164:167], v[208:211], v[70:73]
	v_mfma_f32_16x16x32_bf16 v[66:69], v[172:175], v[208:211], v[66:69]
	v_mfma_f32_16x16x32_bf16 v[118:121], v[168:171], v[188:191], v[118:121]
	v_mfma_f32_16x16x32_bf16 v[114:117], v[180:183], v[188:191], v[114:117]
	v_mfma_f32_16x16x32_bf16 v[102:105], v[168:171], v[196:199], v[102:105]
	v_mfma_f32_16x16x32_bf16 v[98:101], v[180:183], v[196:199], v[98:101]
	v_mfma_f32_16x16x32_bf16 v[86:89], v[168:171], v[204:207], v[86:89]
	v_mfma_f32_16x16x32_bf16 v[82:85], v[180:183], v[204:207], v[82:85]
	v_mfma_f32_16x16x32_bf16 v[70:73], v[168:171], v[212:215], v[70:73]
	v_mfma_f32_16x16x32_bf16 v[66:69], v[180:183], v[212:215], v[66:69]
	s_barrier
	s_setprio 0
	ds_read_b128 v[184:187], v155 offset:16384
	ds_read_b128 v[188:191], v155 offset:17408
	ds_read_b128 v[192:195], v155 offset:18432
	ds_read_b128 v[196:199], v155 offset:19456
	ds_read_b128 v[200:203], v155 offset:20480
	ds_read_b128 v[204:207], v155 offset:21504
	ds_read_b128 v[208:211], v155 offset:22528
	ds_read_b128 v[212:215], v155 offset:23552
	s_add_i32 s50, s50, s53
	v_lshl_add_u64 v[216:217], s[24:25], 0, v[132:133]
	s_mov_b32 m0, s50
	s_nop 0
	global_load_lds_dwordx4 v[216:217], off
	s_add_i32 m0, s50, 0x2000
	s_add_u32 s50, s24, 0x80000
	v_lshl_add_u64 v[218:219], s[24:25], 0, v[136:137]
	s_addc_u32 s51, s25, 0
	s_add_i32 s52, s52, s53
	global_load_lds_dwordx4 v[218:219], off
	v_lshl_add_u64 v[220:221], s[50:51], 0, v[132:133]
	s_mov_b32 m0, s52
	v_lshl_add_u64 v[222:223], s[28:29], 0, v[134:135]
	global_load_lds_dwordx4 v[220:221], off
	v_lshl_add_u64 v[220:221], s[50:51], 0, v[136:137]
	s_add_i32 m0, s52, 0x2000
	s_nop 0
	global_load_lds_dwordx4 v[220:221], off
	v_lshl_add_u64 v[220:221], s[28:29], 0, v[130:131]
	s_mov_b32 m0, s27
	s_nop 0
	global_load_lds_dwordx4 v[220:221], off
	s_mov_b32 m0, s34
	s_nop 0
	global_load_lds_dwordx4 v[222:223], off
	s_waitcnt vmcnt(8)
	s_waitcnt lgkmcnt(0)
	s_setprio 1
	s_barrier
; #define PG8_STAGE(bufoff, gbase, voff) do { _Pragma("unroll") for (int _i = 0; _i < 2; ++_i) \
;         __builtin_amdgcn_global_load_lds((const unsigned*)((const char*)(gbase) + (voff)[_i]), (LAS unsigned*)(lds + (bufoff) + ldsw + _i * 8192), 16, 0, 0); } while (0)
; #define PG8_LDA(dst, b, h) do { _Pragma("unroll") for (int m = 0; m < 4; ++m) _Pragma("unroll") for (int k = 0; k < 2; ++k) dst[m][k] = *(const LAS bf16x8*)(lds + PG8_SA(b, h) + aoff + m * 2048 + k * 1024); } while (0)
; #define PG8_LDB(dst, b, h) do { _Pragma("unroll") for (int n = 0; n < 2; ++n) _Pragma("unroll") for (int k = 0; k < 2; ++k) dst[n][k] = *(const LAS bf16x8*)(lds + PG8_SB(b, h) + boff + n * 2048 + k * 1024); } while (0)
; #define PG8_MMA(ai, bj, At, Bt) do { __builtin_amdgcn_s_setprio(1); _Pragma("unroll") for (int m = 0; m < 4; ++m) _Pragma("unroll") for (int n = 0; n < 2; ++n) _Pragma("unroll") for (int k = 0; k < 2; ++k) \
;         acc[ai][bj][m][n] = __builtin_amdgcn_mfma_f32_16x16x32_bf16(Bt[n][k], At[m][k], acc[ai][bj][m][n], 0, 0, 0); __builtin_amdgcn_s_setprio(0); } while (0)
; #define PG8_WAIT_V(n) asm volatile("s_waitcnt vmcnt(" #n ")" ::: "memory")
; #define PG8_WAIT_L(n) asm volatile("s_waitcnt lgkmcnt(" #n ")" ::: "memory")
; #define PG8_BAR __builtin_amdgcn_s_barrier()
; #define PG8_SCHED __builtin_amdgcn_sched_barrier(0)
; template <class Epi, class Sched, int LDA, int LDB, bool ALIGN_EPI = true>
; __device__ __forceinline__ void gemm_phase(LAS unsigned char* lds, const Gemm g, const Sched& S, const Epi& E, int wave) {
;     ...
;             PG8_WAIT_V(8); PG8_WAIT_L(0); PG8_BAR; PG8_MMA(1, 0, At, B0); PG8_MMA(1, 1, At, B1); PG8_BAR; PG8_SCHED;
;             PG8_LDB(B0, 1, 0); PG8_LDB(B1, 1, 1); PG8_SCHED; PG8_LDA(At, 1, 0); PG8_STAGE(PG8_SA(0, 1), a2 + hstepA, voffA);
;             PG8_WAIT_V(8); PG8_WAIT_L(0); PG8_BAR; PG8_MMA(0, 0, At, B0); PG8_MMA(0, 1, At, B1); PG8_BAR; PG8_SCHED;
	v_mfma_f32_16x16x32_bf16 v[62:65], v[144:147], v[184:187], v[62:65]
	v_mfma_f32_16x16x32_bf16 v[58:61], v[156:159], v[184:187], v[58:61]
	v_mfma_f32_16x16x32_bf16 v[46:49], v[144:147], v[192:195], v[46:49]
	v_mfma_f32_16x16x32_bf16 v[42:45], v[156:159], v[192:195], v[42:45]
	v_mfma_f32_16x16x32_bf16 v[30:33], v[144:147], v[200:203], v[30:33]
	v_mfma_f32_16x16x32_bf16 v[26:29], v[156:159], v[200:203], v[26:29]
	v_mfma_f32_16x16x32_bf16 v[14:17], v[144:147], v[208:211], v[14:17]
	v_mfma_f32_16x16x32_bf16 v[10:13], v[156:159], v[208:211], v[10:13]
	v_mfma_f32_16x16x32_bf16 v[62:65], v[148:151], v[188:191], v[62:65]
	v_mfma_f32_16x16x32_bf16 v[58:61], v[160:163], v[188:191], v[58:61]
	v_mfma_f32_16x16x32_bf16 v[46:49], v[148:151], v[196:199], v[46:49]
	v_mfma_f32_16x16x32_bf16 v[42:45], v[160:163], v[196:199], v[42:45]
	v_mfma_f32_16x16x32_bf16 v[30:33], v[148:151], v[204:207], v[30:33]
	v_mfma_f32_16x16x32_bf16 v[26:29], v[160:163], v[204:207], v[26:29]
	v_mfma_f32_16x16x32_bf16 v[14:17], v[148:151], v[212:215], v[14:17]
	v_mfma_f32_16x16x32_bf16 v[10:13], v[160:163], v[212:215], v[10:13]
	v_mfma_f32_16x16x32_bf16 v[54:57], v[164:167], v[184:187], v[54:57]
	v_mfma_f32_16x16x32_bf16 v[50:53], v[172:175], v[184:187], v[50:53]
	v_mfma_f32_16x16x32_bf16 v[38:41], v[164:167], v[192:195], v[38:41]
	v_mfma_f32_16x16x32_bf16 v[34:37], v[172:175], v[192:195], v[34:37]
	v_mfma_f32_16x16x32_bf16 v[22:25], v[164:167], v[200:203], v[22:25]
	v_mfma_f32_16x16x32_bf16 v[18:21], v[172:175], v[200:203], v[18:21]
	v_mfma_f32_16x16x32_bf16 v[6:9], v[164:167], v[208:211], v[6:9]
	v_mfma_f32_16x16x32_bf16 v[2:5], v[172:175], v[208:211], v[2:5]
	v_mfma_f32_16x16x32_bf16 v[54:57], v[168:171], v[188:191], v[54:57]
	v_mfma_f32_16x16x32_bf16 v[50:53], v[180:183], v[188:191], v[50:53]
	v_mfma_f32_16x16x32_bf16 v[38:41], v[168:171], v[196:199], v[38:41]
	v_mfma_f32_16x16x32_bf16 v[34:37], v[180:183], v[196:199], v[34:37]
	v_mfma_f32_16x16x32_bf16 v[22:25], v[168:171], v[204:207], v[22:25]
	v_mfma_f32_16x16x32_bf16 v[18:21], v[180:183], v[204:207], v[18:21]
	v_mfma_f32_16x16x32_bf16 v[6:9], v[168:171], v[212:215], v[6:9]
	v_mfma_f32_16x16x32_bf16 v[2:5], v[180:183], v[212:215], v[2:5]
	s_barrier
	s_setprio 0
	ds_read_b128 v[184:187], v155 offset:32768
	ds_read_b128 v[188:191], v155 offset:33792
	ds_read_b128 v[192:195], v155 offset:34816
	ds_read_b128 v[196:199], v155 offset:35840
	ds_read_b128 v[200:203], v155 offset:36864
	ds_read_b128 v[204:207], v155 offset:37888
	ds_read_b128 v[208:211], v155 offset:38912
	ds_read_b128 v[212:215], v155 offset:39936
	s_add_i32 s50, 0, 0x18000
	v_add_u32_e32 v0, s50, v153
	s_add_i32 s51, 0, 0x1c000
	ds_read_b128 v[144:147], v0
	ds_read_b128 v[148:151], v0 offset:1024
	ds_read_b128 v[156:159], v0 offset:2048
	ds_read_b128 v[160:163], v0 offset:3072
	v_add_u32_e32 v0, s51, v153
	ds_read_b128 v[164:167], v0
	ds_read_b128 v[168:171], v0 offset:1024
	ds_read_b128 v[172:175], v0 offset:2048
	ds_read_b128 v[180:183], v0 offset:3072
	s_add_u32 s28, s28, 0x80000
	s_addc_u32 s29, s29, 0
	s_mov_b32 m0, s35
	v_lshl_add_u64 v[224:225], s[28:29], 0, v[130:131]
	global_load_lds_dwordx4 v[224:225], off
	v_lshl_add_u64 v[224:225], s[28:29], 0, v[134:135]
	s_mov_b32 m0, s36
	s_nop 0
	global_load_lds_dwordx4 v[224:225], off
	s_waitcnt vmcnt(8)
	s_waitcnt lgkmcnt(0)
	s_setprio 1
	s_barrier
	v_mfma_f32_16x16x32_bf16 v[126:129], v[144:147], v[184:187], v[126:129]
	v_mfma_f32_16x16x32_bf16 v[122:125], v[156:159], v[184:187], v[122:125]
	v_mfma_f32_16x16x32_bf16 v[110:113], v[144:147], v[192:195], v[110:113]
	v_mfma_f32_16x16x32_bf16 v[106:109], v[156:159], v[192:195], v[106:109]
	v_mfma_f32_16x16x32_bf16 v[94:97], v[144:147], v[200:203], v[94:97]
	v_mfma_f32_16x16x32_bf16 v[90:93], v[156:159], v[200:203], v[90:93]
	v_mfma_f32_16x16x32_bf16 v[78:81], v[144:147], v[208:211], v[78:81]
	v_mfma_f32_16x16x32_bf16 v[74:77], v[156:159], v[208:211], v[74:77]
	v_mfma_f32_16x16x32_bf16 v[126:129], v[148:151], v[188:191], v[126:129]
	v_mfma_f32_16x16x32_bf16 v[122:125], v[160:163], v[188:191], v[122:125]
	v_mfma_f32_16x16x32_bf16 v[110:113], v[148:151], v[196:199], v[110:113]
	v_mfma_f32_16x16x32_bf16 v[106:109], v[160:163], v[196:199], v[106:109]
	v_mfma_f32_16x16x32_bf16 v[94:97], v[148:151], v[204:207], v[94:97]
	v_mfma_f32_16x16x32_bf16 v[90:93], v[160:163], v[204:207], v[90:93]
	v_mfma_f32_16x16x32_bf16 v[78:81], v[148:151], v[212:215], v[78:81]
	v_mfma_f32_16x16x32_bf16 v[74:77], v[160:163], v[212:215], v[74:77]
	v_mfma_f32_16x16x32_bf16 v[118:121], v[164:167], v[184:187], v[118:121]
	v_mfma_f32_16x16x32_bf16 v[114:117], v[172:175], v[184:187], v[114:117]
	v_mfma_f32_16x16x32_bf16 v[102:105], v[164:167], v[192:195], v[102:105]
	v_mfma_f32_16x16x32_bf16 v[98:101], v[172:175], v[192:195], v[98:101]
	v_mfma_f32_16x16x32_bf16 v[86:89], v[164:167], v[200:203], v[86:89]
	v_mfma_f32_16x16x32_bf16 v[82:85], v[172:175], v[200:203], v[82:85]
	v_mfma_f32_16x16x32_bf16 v[70:73], v[164:167], v[208:211], v[70:73]
	v_mfma_f32_16x16x32_bf16 v[66:69], v[172:175], v[208:211], v[66:69]
	v_mfma_f32_16x16x32_bf16 v[118:121], v[168:171], v[188:191], v[118:121]
	v_mfma_f32_16x16x32_bf16 v[114:117], v[180:183], v[188:191], v[114:117]
	v_mfma_f32_16x16x32_bf16 v[102:105], v[168:171], v[196:199], v[102:105]
	v_mfma_f32_16x16x32_bf16 v[98:101], v[180:183], v[196:199], v[98:101]
	v_mfma_f32_16x16x32_bf16 v[86:89], v[168:171], v[204:207], v[86:89]
	v_mfma_f32_16x16x32_bf16 v[82:85], v[180:183], v[204:207], v[82:85]
	v_mfma_f32_16x16x32_bf16 v[70:73], v[168:171], v[212:215], v[70:73]
	v_mfma_f32_16x16x32_bf16 v[66:69], v[180:183], v[212:215], v[66:69]
	s_barrier
; #define PG8_STAGE(bufoff, gbase, voff) do { _Pragma("unroll") for (int _i = 0; _i < 2; ++_i) \
;         __builtin_amdgcn_global_load_lds((const unsigned*)((const char*)(gbase) + (voff)[_i]), (LAS unsigned*)(lds + (bufoff) + ldsw + _i * 8192), 16, 0, 0); } while (0)
; #define PG8_LDA(dst, b, h) do { _Pragma("unroll") for (int m = 0; m < 4; ++m) _Pragma("unroll") for (int k = 0; k < 2; ++k) dst[m][k] = *(const LAS bf16x8*)(lds + PG8_SA(b, h) + aoff + m * 2048 + k * 1024); } while (0)
; #define PG8_MMA(ai, bj, At, Bt) do { __builtin_amdgcn_s_setprio(1); _Pragma("unroll") for (int m = 0; m < 4; ++m) _Pragma("unroll") for (int n = 0; n < 2; ++n) _Pragma("unroll") for (int k = 0; k < 2; ++k) \
;         acc[ai][bj][m][n] = __builtin_amdgcn_mfma_f32_16x16x32_bf16(Bt[n][k], At[m][k], acc[ai][bj][m][n], 0, 0, 0); __builtin_amdgcn_s_setprio(0); } while (0)
; #define PG8_WAIT_V(n) asm volatile("s_waitcnt vmcnt(" #n ")" ::: "memory")
; #define PG8_WAIT_L(n) asm volatile("s_waitcnt lgkmcnt(" #n ")" ::: "memory")
; #define PG8_BAR __builtin_amdgcn_s_barrier()
; #define PG8_SCHED __builtin_amdgcn_sched_barrier(0)
; template <class Epi, class Sched, int LDA, int LDB, bool ALIGN_EPI = true>
; __device__ __forceinline__ void gemm_phase(LAS unsigned char* lds, const Gemm g, const Sched& S, const Epi& E, int wave) {
;     ...
;             PG8_LDA(At, 1, 1); PG8_STAGE(PG8_SB(1, 0), b3, voffB); PG8_STAGE(PG8_SB(1, 1), b3 + hstepB, voffB); PG8_STAGE(PG8_SA(1, 0), a3, voffA);
;             PG8_WAIT_V(8); PG8_WAIT_L(0); PG8_BAR; PG8_MMA(1, 0, At, B0); PG8_MMA(1, 1, At, B1); PG8_BAR; PG8_SCHED;
;         }
	s_setprio 0
	ds_read_b128 v[184:187], v155 offset:49152
	ds_read_b128 v[188:191], v155 offset:50176
	ds_read_b128 v[192:195], v155 offset:51200
	ds_read_b128 v[196:199], v155 offset:52224
	ds_read_b128 v[200:203], v155 offset:53248
	ds_read_b128 v[204:207], v155 offset:54272
	ds_read_b128 v[208:211], v155 offset:55296
	ds_read_b128 v[212:215], v155 offset:56320
	s_add_i32 s28, s50, s53
	v_lshl_add_u64 v[216:217], v[216:217], 0, s[54:55]
	s_mov_b32 m0, s28
	s_nop 0
	global_load_lds_dwordx4 v[216:217], off
	s_add_i32 m0, s28, 0x2000
	s_add_u32 s24, s24, 0x80080
	v_lshl_add_u64 v[216:217], v[218:219], 0, s[54:55]
	s_addc_u32 s25, s25, 0
	s_add_i32 s28, s51, s53
	global_load_lds_dwordx4 v[216:217], off
	v_lshl_add_u64 v[216:217], s[24:25], 0, v[132:133]
	s_mov_b32 m0, s28
	s_nop 0
	global_load_lds_dwordx4 v[216:217], off
	v_lshl_add_u64 v[216:217], s[24:25], 0, v[136:137]
	s_add_i32 m0, s28, 0x2000
	s_nop 0
	global_load_lds_dwordx4 v[216:217], off
	v_lshl_add_u64 v[216:217], v[220:221], 0, s[54:55]
	s_mov_b32 m0, s37
	s_nop 0
	global_load_lds_dwordx4 v[216:217], off
	v_lshl_add_u64 v[216:217], v[222:223], 0, s[54:55]
	s_mov_b32 m0, s38
	s_nop 0
	global_load_lds_dwordx4 v[216:217], off
	s_waitcnt vmcnt(8)
	s_waitcnt lgkmcnt(0)
	s_setprio 1
	s_barrier
	v_mfma_f32_16x16x32_bf16 v[62:65], v[144:147], v[184:187], v[62:65]
	v_mfma_f32_16x16x32_bf16 v[58:61], v[156:159], v[184:187], v[58:61]
	v_mfma_f32_16x16x32_bf16 v[46:49], v[144:147], v[192:195], v[46:49]
	v_mfma_f32_16x16x32_bf16 v[42:45], v[156:159], v[192:195], v[42:45]
	v_mfma_f32_16x16x32_bf16 v[30:33], v[144:147], v[200:203], v[30:33]
	v_mfma_f32_16x16x32_bf16 v[26:29], v[156:159], v[200:203], v[26:29]
	v_mfma_f32_16x16x32_bf16 v[14:17], v[144:147], v[208:211], v[14:17]
	v_mfma_f32_16x16x32_bf16 v[10:13], v[156:159], v[208:211], v[10:13]
	v_mfma_f32_16x16x32_bf16 v[62:65], v[148:151], v[188:191], v[62:65]
	v_mfma_f32_16x16x32_bf16 v[58:61], v[160:163], v[188:191], v[58:61]
	v_mfma_f32_16x16x32_bf16 v[46:49], v[148:151], v[196:199], v[46:49]
	v_mfma_f32_16x16x32_bf16 v[42:45], v[160:163], v[196:199], v[42:45]
	v_mfma_f32_16x16x32_bf16 v[30:33], v[148:151], v[204:207], v[30:33]
	v_mfma_f32_16x16x32_bf16 v[26:29], v[160:163], v[204:207], v[26:29]
	v_mfma_f32_16x16x32_bf16 v[14:17], v[148:151], v[212:215], v[14:17]
	v_mfma_f32_16x16x32_bf16 v[10:13], v[160:163], v[212:215], v[10:13]
	v_mfma_f32_16x16x32_bf16 v[54:57], v[164:167], v[184:187], v[54:57]
	v_mfma_f32_16x16x32_bf16 v[50:53], v[172:175], v[184:187], v[50:53]
	v_mfma_f32_16x16x32_bf16 v[38:41], v[164:167], v[192:195], v[38:41]
	v_mfma_f32_16x16x32_bf16 v[34:37], v[172:175], v[192:195], v[34:37]
	v_mfma_f32_16x16x32_bf16 v[22:25], v[164:167], v[200:203], v[22:25]
	v_mfma_f32_16x16x32_bf16 v[18:21], v[172:175], v[200:203], v[18:21]
	v_mfma_f32_16x16x32_bf16 v[6:9], v[164:167], v[208:211], v[6:9]
	v_mfma_f32_16x16x32_bf16 v[2:5], v[172:175], v[208:211], v[2:5]
	v_mfma_f32_16x16x32_bf16 v[54:57], v[168:171], v[188:191], v[54:57]
	v_mfma_f32_16x16x32_bf16 v[50:53], v[180:183], v[188:191], v[50:53]
	v_mfma_f32_16x16x32_bf16 v[38:41], v[168:171], v[196:199], v[38:41]
	v_mfma_f32_16x16x32_bf16 v[34:37], v[180:183], v[196:199], v[34:37]
	v_mfma_f32_16x16x32_bf16 v[22:25], v[168:171], v[204:207], v[22:25]
	v_mfma_f32_16x16x32_bf16 v[18:21], v[180:183], v[204:207], v[18:21]
	v_mfma_f32_16x16x32_bf16 v[6:9], v[168:171], v[212:215], v[6:9]
	v_mfma_f32_16x16x32_bf16 v[2:5], v[180:183], v[212:215], v[2:5]
	s_barrier
	s_setprio 0
	s_add_u32 s18, s18, 0x100
	s_addc_u32 s19, s19, 0
	s_add_u32 s44, s44, 0x100
	s_addc_u32 s45, s45, 0
	s_cmp_ge_i32 s49, s43
	s_mov_b32 s24, s49
	s_cbranch_scc0 .LBB0_4715
	v_readlane_b32 s18, v252, 14
	v_readlane_b32 s19, v252, 15
	s_and_b64 vcc, exec, s[18:19]
	s_cbranch_vccz .LBB0_4718
	s_barrier

; #define PG8_STAGE(bufoff, gbase, voff) do { _Pragma("unroll") for (int _i = 0; _i < 2; ++_i) \
;         __builtin_amdgcn_global_load_lds((const unsigned*)((const char*)(gbase) + (voff)[_i]), (LAS unsigned*)(lds + (bufoff) + ldsw + _i * 8192), 16, 0, 0); } while (0)
; #define PG8_LDA(dst, b, h) do { _Pragma("unroll") for (int m = 0; m < 4; ++m) _Pragma("unroll") for (int k = 0; k < 2; ++k) dst[m][k] = *(const LAS bf16x8*)(lds + PG8_SA(b, h) + aoff + m * 2048 + k * 1024); } while (0)
; #define PG8_LDB(dst, b, h) do { _Pragma("unroll") for (int n = 0; n < 2; ++n) _Pragma("unroll") for (int k = 0; k < 2; ++k) dst[n][k] = *(const LAS bf16x8*)(lds + PG8_SB(b, h) + boff + n * 2048 + k * 1024); } while (0)
; #define PG8_MMA(ai, bj, At, Bt) do { __builtin_amdgcn_s_setprio(1); _Pragma("unroll") for (int m = 0; m < 4; ++m) _Pragma("unroll") for (int n = 0; n < 2; ++n) _Pragma("unroll") for (int k = 0; k < 2; ++k) \
;         acc[ai][bj][m][n] = __builtin_amdgcn_mfma_f32_16x16x32_bf16(Bt[n][k], At[m][k], acc[ai][bj][m][n], 0, 0, 0); __builtin_amdgcn_s_setprio(0); } while (0)
; #define PG8_WAIT_V(n) asm volatile("s_waitcnt vmcnt(" #n ")" ::: "memory")
; #define PG8_WAIT_L(n) asm volatile("s_waitcnt lgkmcnt(" #n ")" ::: "memory")
; #define PG8_BAR __builtin_amdgcn_s_barrier()
; #define PG8_SCHED __builtin_amdgcn_sched_barrier(0)
; template <class Epi, class Sched, int LDA, int LDB, bool ALIGN_EPI = true>
; __device__ __forceinline__ void gemm_phase(LAS unsigned char* lds, const Gemm g, const Sched& S, const Epi& E, int wave) {
;     ...
;             PG8_LDB(B0, 0, 0); PG8_LDB(B1, 0, 1); PG8_SCHED; PG8_LDA(At, 0, 0); PG8_STAGE(PG8_SA(1, 1), a1 + hstepA, voffA);
;             PG8_WAIT_V(8); PG8_WAIT_L(0); PG8_BAR; PG8_MMA(0, 0, At, B0); PG8_MMA(0, 1, At, B1); PG8_BAR; PG8_SCHED;
;             PG8_LDA(At, 0, 1); PG8_STAGE(PG8_SB(0, 0), b2, voffB); PG8_STAGE(PG8_SB(0, 1), b2 + hstepB, voffB); PG8_STAGE(PG8_SA(0, 0), a2, voffA);
;             PG8_WAIT_V(8); PG8_WAIT_L(0); PG8_BAR; PG8_MMA(1, 0, At, B0); PG8_MMA(1, 1, At, B1); PG8_BAR; PG8_SCHED;
.LBB0_4901:
	ds_read_b128 v[172:175], v215
	ds_read_b128 v[180:183], v215 offset:1024
	ds_read_b128 v[184:187], v215 offset:2048
	ds_read_b128 v[188:191], v215 offset:3072
	ds_read_b128 v[192:195], v215 offset:4096
	ds_read_b128 v[196:199], v215 offset:5120
	ds_read_b128 v[200:203], v215 offset:6144
	ds_read_b128 v[204:207], v215 offset:7168
	s_add_i32 s65, s36, 2
	s_add_u32 s37, s34, 0xfff80080
	s_addc_u32 s38, s35, -1
	s_add_i32 s66, 0, 0x10000
	s_cmp_eq_u32 s29, s36
	s_cselect_b32 s39, s9, s38
	s_cselect_b32 s38, s13, s37
	s_cselect_b32 s37, s11, s64
	s_cselect_b32 s36, s25, s59
	s_add_i32 s72, 0, 0x14000
	v_add_u32_e32 v70, s66, v213
	v_add_u32_e32 v168, s72, v213
	ds_read_b128 v[50:53], v70
	ds_read_b128 v[54:57], v70 offset:1024
	ds_read_b128 v[66:69], v70 offset:2048
	ds_read_b128 v[70:73], v70 offset:3072
	ds_read_b128 v[156:159], v168
	ds_read_b128 v[160:163], v168 offset:1024
	ds_read_b128 v[164:167], v168 offset:2048
	ds_read_b128 v[168:171], v168 offset:3072
	v_lshl_add_u64 v[208:209], s[34:35], 0, v[152:153]
	s_add_i32 m0, s27, 0xc000
	s_nop 0
	global_load_lds_dwordx4 v[208:209], off
	v_lshl_add_u64 v[208:209], s[34:35], 0, v[154:155]
	s_add_i32 m0, s27, 0xe000
	s_nop 0
	global_load_lds_dwordx4 v[208:209], off
	s_waitcnt vmcnt(8)
	s_waitcnt lgkmcnt(0)
	s_setprio 1
	s_barrier
	v_mfma_f32_16x16x32_bf16 v[142:145], v[50:53], v[172:175], v[142:145]
	v_mfma_f32_16x16x32_bf16 v[138:141], v[66:69], v[172:175], v[138:141]
	v_mfma_f32_16x16x32_bf16 v[126:129], v[50:53], v[184:187], v[126:129]
	v_mfma_f32_16x16x32_bf16 v[122:125], v[66:69], v[184:187], v[122:125]
	v_mfma_f32_16x16x32_bf16 v[110:113], v[50:53], v[192:195], v[110:113]
	v_mfma_f32_16x16x32_bf16 v[106:109], v[66:69], v[192:195], v[106:109]
	v_mfma_f32_16x16x32_bf16 v[94:97], v[50:53], v[200:203], v[94:97]
	v_mfma_f32_16x16x32_bf16 v[90:93], v[66:69], v[200:203], v[90:93]
	v_mfma_f32_16x16x32_bf16 v[142:145], v[54:57], v[180:183], v[142:145]
	v_mfma_f32_16x16x32_bf16 v[138:141], v[70:73], v[180:183], v[138:141]
	v_mfma_f32_16x16x32_bf16 v[126:129], v[54:57], v[188:191], v[126:129]
	v_mfma_f32_16x16x32_bf16 v[122:125], v[70:73], v[188:191], v[122:125]
	v_mfma_f32_16x16x32_bf16 v[110:113], v[54:57], v[196:199], v[110:113]
	v_mfma_f32_16x16x32_bf16 v[106:109], v[70:73], v[196:199], v[106:109]
	v_mfma_f32_16x16x32_bf16 v[94:97], v[54:57], v[204:207], v[94:97]
	v_mfma_f32_16x16x32_bf16 v[90:93], v[70:73], v[204:207], v[90:93]
	v_mfma_f32_16x16x32_bf16 v[134:137], v[156:159], v[172:175], v[134:137]
	v_mfma_f32_16x16x32_bf16 v[130:133], v[164:167], v[172:175], v[130:133]
	v_mfma_f32_16x16x32_bf16 v[118:121], v[156:159], v[184:187], v[118:121]
	v_mfma_f32_16x16x32_bf16 v[114:117], v[164:167], v[184:187], v[114:117]
	v_mfma_f32_16x16x32_bf16 v[102:105], v[156:159], v[192:195], v[102:105]
	v_mfma_f32_16x16x32_bf16 v[98:101], v[164:167], v[192:195], v[98:101]
	v_mfma_f32_16x16x32_bf16 v[86:89], v[156:159], v[200:203], v[86:89]
	v_mfma_f32_16x16x32_bf16 v[82:85], v[164:167], v[200:203], v[82:85]
	v_mfma_f32_16x16x32_bf16 v[134:137], v[160:163], v[180:183], v[134:137]
	v_mfma_f32_16x16x32_bf16 v[130:133], v[168:171], v[180:183], v[130:133]
	v_mfma_f32_16x16x32_bf16 v[118:121], v[160:163], v[188:191], v[118:121]
	v_mfma_f32_16x16x32_bf16 v[114:117], v[168:171], v[188:191], v[114:117]
	v_mfma_f32_16x16x32_bf16 v[102:105], v[160:163], v[196:199], v[102:105]
	v_mfma_f32_16x16x32_bf16 v[98:101], v[168:171], v[196:199], v[98:101]
	v_mfma_f32_16x16x32_bf16 v[86:89], v[160:163], v[204:207], v[86:89]
	v_mfma_f32_16x16x32_bf16 v[82:85], v[168:171], v[204:207], v[82:85]
	s_barrier
	s_setprio 0
	ds_read_b128 v[172:175], v215 offset:16384
	ds_read_b128 v[180:183], v215 offset:17408
	ds_read_b128 v[184:187], v215 offset:18432
	ds_read_b128 v[188:191], v215 offset:19456
	ds_read_b128 v[192:195], v215 offset:20480
	ds_read_b128 v[196:199], v215 offset:21504
	ds_read_b128 v[200:203], v215 offset:22528
	ds_read_b128 v[204:207], v215 offset:23552
	s_add_i32 s66, s66, s60
	v_lshl_add_u64 v[208:209], s[36:37], 0, v[0:1]
	s_mov_b32 m0, s66
	s_nop 0
	global_load_lds_dwordx4 v[208:209], off
	s_add_i32 m0, s66, 0x2000
	s_add_u32 s66, s36, 0x80000
	v_lshl_add_u64 v[210:211], s[36:37], 0, v[150:151]
	s_addc_u32 s67, s37, 0
	s_add_i32 s72, s72, s60
	global_load_lds_dwordx4 v[210:211], off
	v_lshl_add_u64 v[216:217], s[66:67], 0, v[0:1]
	s_mov_b32 m0, s72
	v_lshl_add_u64 v[218:219], s[38:39], 0, v[148:149]
	global_load_lds_dwordx4 v[216:217], off
	v_lshl_add_u64 v[216:217], s[66:67], 0, v[150:151]
	s_add_i32 m0, s72, 0x2000
	s_nop 0
	global_load_lds_dwordx4 v[216:217], off
	v_lshl_add_u64 v[216:217], s[38:39], 0, v[146:147]
	s_mov_b32 m0, s27
	s_nop 0
	global_load_lds_dwordx4 v[216:217], off
	s_mov_b32 m0, s44
	s_nop 0
	global_load_lds_dwordx4 v[218:219], off
	s_waitcnt vmcnt(8)
	s_waitcnt lgkmcnt(0)
	s_setprio 1
	s_barrier
; #define PG8_STAGE(bufoff, gbase, voff) do { _Pragma("unroll") for (int _i = 0; _i < 2; ++_i) \
;         __builtin_amdgcn_global_load_lds((const unsigned*)((const char*)(gbase) + (voff)[_i]), (LAS unsigned*)(lds + (bufoff) + ldsw + _i * 8192), 16, 0, 0); } while (0)
; #define PG8_LDA(dst, b, h) do { _Pragma("unroll") for (int m = 0; m < 4; ++m) _Pragma("unroll") for (int k = 0; k < 2; ++k) dst[m][k] = *(const LAS bf16x8*)(lds + PG8_SA(b, h) + aoff + m * 2048 + k * 1024); } while (0)
; #define PG8_LDB(dst, b, h) do { _Pragma("unroll") for (int n = 0; n < 2; ++n) _Pragma("unroll") for (int k = 0; k < 2; ++k) dst[n][k] = *(const LAS bf16x8*)(lds + PG8_SB(b, h) + boff + n * 2048 + k * 1024); } while (0)
; #define PG8_MMA(ai, bj, At, Bt) do { __builtin_amdgcn_s_setprio(1); _Pragma("unroll") for (int m = 0; m < 4; ++m) _Pragma("unroll") for (int n = 0; n < 2; ++n) _Pragma("unroll") for (int k = 0; k < 2; ++k) \
;         acc[ai][bj][m][n] = __builtin_amdgcn_mfma_f32_16x16x32_bf16(Bt[n][k], At[m][k], acc[ai][bj][m][n], 0, 0, 0); __builtin_amdgcn_s_setprio(0); } while (0)
; #define PG8_WAIT_V(n) asm volatile("s_waitcnt vmcnt(" #n ")" ::: "memory")
; #define PG8_WAIT_L(n) asm volatile("s_waitcnt lgkmcnt(" #n ")" ::: "memory")
; #define PG8_BAR __builtin_amdgcn_s_barrier()
; #define PG8_SCHED __builtin_amdgcn_sched_barrier(0)
; template <class Epi, class Sched, int LDA, int LDB, bool ALIGN_EPI = true>
; __device__ __forceinline__ void gemm_phase(LAS unsigned char* lds, const Gemm g, const Sched& S, const Epi& E, int wave) {
;     ...
;             PG8_WAIT_V(8); PG8_WAIT_L(0); PG8_BAR; PG8_MMA(1, 0, At, B0); PG8_MMA(1, 1, At, B1); PG8_BAR; PG8_SCHED;
;             PG8_LDB(B0, 1, 0); PG8_LDB(B1, 1, 1); PG8_SCHED; PG8_LDA(At, 1, 0); PG8_STAGE(PG8_SA(0, 1), a2 + hstepA, voffA);
;             PG8_WAIT_V(8); PG8_WAIT_L(0); PG8_BAR; PG8_MMA(0, 0, At, B0); PG8_MMA(0, 1, At, B1); PG8_BAR; PG8_SCHED;
	v_mfma_f32_16x16x32_bf16 v[78:81], v[50:53], v[172:175], v[78:81]
	v_mfma_f32_16x16x32_bf16 v[74:77], v[66:69], v[172:175], v[74:77]
	v_mfma_f32_16x16x32_bf16 v[46:49], v[50:53], v[184:187], v[46:49]
	v_mfma_f32_16x16x32_bf16 v[42:45], v[66:69], v[184:187], v[42:45]
	v_mfma_f32_16x16x32_bf16 v[30:33], v[50:53], v[192:195], v[30:33]
	v_mfma_f32_16x16x32_bf16 v[26:29], v[66:69], v[192:195], v[26:29]
	v_mfma_f32_16x16x32_bf16 v[14:17], v[50:53], v[200:203], v[14:17]
	v_mfma_f32_16x16x32_bf16 v[10:13], v[66:69], v[200:203], v[10:13]
	v_mfma_f32_16x16x32_bf16 v[78:81], v[54:57], v[180:183], v[78:81]
	v_mfma_f32_16x16x32_bf16 v[74:77], v[70:73], v[180:183], v[74:77]
	v_mfma_f32_16x16x32_bf16 v[46:49], v[54:57], v[188:191], v[46:49]
	v_mfma_f32_16x16x32_bf16 v[42:45], v[70:73], v[188:191], v[42:45]
	v_mfma_f32_16x16x32_bf16 v[30:33], v[54:57], v[196:199], v[30:33]
	v_mfma_f32_16x16x32_bf16 v[26:29], v[70:73], v[196:199], v[26:29]
	v_mfma_f32_16x16x32_bf16 v[14:17], v[54:57], v[204:207], v[14:17]
	v_mfma_f32_16x16x32_bf16 v[10:13], v[70:73], v[204:207], v[10:13]
	v_mfma_f32_16x16x32_bf16 v[38:41], v[156:159], v[184:187], v[38:41]
	v_mfma_f32_16x16x32_bf16 v[34:37], v[164:167], v[184:187], v[34:37]
	v_mfma_f32_16x16x32_bf16 v[22:25], v[156:159], v[192:195], v[22:25]
	v_mfma_f32_16x16x32_bf16 v[18:21], v[164:167], v[192:195], v[18:21]
	v_mfma_f32_16x16x32_bf16 v[6:9], v[156:159], v[200:203], v[6:9]
	v_mfma_f32_16x16x32_bf16 v[2:5], v[164:167], v[200:203], v[2:5]
	v_mfma_f32_16x16x32_bf16 v[50:53], v[156:159], v[172:175], v[62:65]
	v_mfma_f32_16x16x32_bf16 v[54:57], v[164:167], v[172:175], v[58:61]
	v_mfma_f32_16x16x32_bf16 v[38:41], v[160:163], v[188:191], v[38:41]
	v_mfma_f32_16x16x32_bf16 v[34:37], v[168:171], v[188:191], v[34:37]
	v_mfma_f32_16x16x32_bf16 v[22:25], v[160:163], v[196:199], v[22:25]
	v_mfma_f32_16x16x32_bf16 v[18:21], v[168:171], v[196:199], v[18:21]
	v_mfma_f32_16x16x32_bf16 v[6:9], v[160:163], v[204:207], v[6:9]
	v_mfma_f32_16x16x32_bf16 v[2:5], v[168:171], v[204:207], v[2:5]
	v_mfma_f32_16x16x32_bf16 v[50:53], v[160:163], v[180:183], v[50:53]
	v_mfma_f32_16x16x32_bf16 v[54:57], v[168:171], v[180:183], v[54:57]
	s_barrier
	s_setprio 0
	ds_read_b128 v[172:175], v215 offset:32768
	ds_read_b128 v[180:183], v215 offset:33792
	ds_read_b128 v[184:187], v215 offset:34816
	ds_read_b128 v[188:191], v215 offset:35840
	ds_read_b128 v[192:195], v215 offset:36864
	ds_read_b128 v[196:199], v215 offset:37888
	ds_read_b128 v[200:203], v215 offset:38912
	ds_read_b128 v[204:207], v215 offset:39936
	s_add_i32 s66, 0, 0x18000
	s_add_i32 s67, 0, 0x1c000
	v_add_u32_e32 v70, s66, v213
	v_add_u32_e32 v168, s67, v213
	ds_read_b128 v[58:61], v70
	ds_read_b128 v[62:65], v70 offset:1024
	ds_read_b128 v[66:69], v70 offset:2048
	ds_read_b128 v[70:73], v70 offset:3072
	ds_read_b128 v[156:159], v168
	ds_read_b128 v[160:163], v168 offset:1024
	ds_read_b128 v[164:167], v168 offset:2048
	ds_read_b128 v[168:171], v168 offset:3072
	s_add_u32 s38, s38, 0x80000
	s_addc_u32 s39, s39, 0
	s_mov_b32 m0, s45
	v_lshl_add_u64 v[220:221], s[38:39], 0, v[146:147]
	global_load_lds_dwordx4 v[220:221], off
	v_lshl_add_u64 v[220:221], s[38:39], 0, v[148:149]
	s_mov_b32 m0, s46
	s_nop 0
	global_load_lds_dwordx4 v[220:221], off
	s_waitcnt vmcnt(8)
	s_waitcnt lgkmcnt(0)
	s_setprio 1
	s_barrier
	v_mfma_f32_16x16x32_bf16 v[142:145], v[58:61], v[172:175], v[142:145]
	v_mfma_f32_16x16x32_bf16 v[138:141], v[66:69], v[172:175], v[138:141]
	v_mfma_f32_16x16x32_bf16 v[126:129], v[58:61], v[184:187], v[126:129]
	v_mfma_f32_16x16x32_bf16 v[122:125], v[66:69], v[184:187], v[122:125]
	v_mfma_f32_16x16x32_bf16 v[110:113], v[58:61], v[192:195], v[110:113]
	v_mfma_f32_16x16x32_bf16 v[106:109], v[66:69], v[192:195], v[106:109]
	v_mfma_f32_16x16x32_bf16 v[94:97], v[58:61], v[200:203], v[94:97]
	v_mfma_f32_16x16x32_bf16 v[90:93], v[66:69], v[200:203], v[90:93]
	v_mfma_f32_16x16x32_bf16 v[142:145], v[62:65], v[180:183], v[142:145]
	v_mfma_f32_16x16x32_bf16 v[138:141], v[70:73], v[180:183], v[138:141]
	v_mfma_f32_16x16x32_bf16 v[126:129], v[62:65], v[188:191], v[126:129]
	v_mfma_f32_16x16x32_bf16 v[122:125], v[70:73], v[188:191], v[122:125]
	v_mfma_f32_16x16x32_bf16 v[110:113], v[62:65], v[196:199], v[110:113]
	v_mfma_f32_16x16x32_bf16 v[106:109], v[70:73], v[196:199], v[106:109]
	v_mfma_f32_16x16x32_bf16 v[94:97], v[62:65], v[204:207], v[94:97]
	v_mfma_f32_16x16x32_bf16 v[90:93], v[70:73], v[204:207], v[90:93]
	v_mfma_f32_16x16x32_bf16 v[134:137], v[156:159], v[172:175], v[134:137]
	v_mfma_f32_16x16x32_bf16 v[130:133], v[164:167], v[172:175], v[130:133]
	v_mfma_f32_16x16x32_bf16 v[118:121], v[156:159], v[184:187], v[118:121]
	v_mfma_f32_16x16x32_bf16 v[114:117], v[164:167], v[184:187], v[114:117]
	v_mfma_f32_16x16x32_bf16 v[102:105], v[156:159], v[192:195], v[102:105]
	v_mfma_f32_16x16x32_bf16 v[98:101], v[164:167], v[192:195], v[98:101]
	v_mfma_f32_16x16x32_bf16 v[86:89], v[156:159], v[200:203], v[86:89]
	v_mfma_f32_16x16x32_bf16 v[82:85], v[164:167], v[200:203], v[82:85]
	v_mfma_f32_16x16x32_bf16 v[134:137], v[160:163], v[180:183], v[134:137]
	v_mfma_f32_16x16x32_bf16 v[130:133], v[168:171], v[180:183], v[130:133]
	v_mfma_f32_16x16x32_bf16 v[118:121], v[160:163], v[188:191], v[118:121]
	v_mfma_f32_16x16x32_bf16 v[114:117], v[168:171], v[188:191], v[114:117]
	v_mfma_f32_16x16x32_bf16 v[102:105], v[160:163], v[196:199], v[102:105]
	v_mfma_f32_16x16x32_bf16 v[98:101], v[168:171], v[196:199], v[98:101]
	v_mfma_f32_16x16x32_bf16 v[86:89], v[160:163], v[204:207], v[86:89]
	v_mfma_f32_16x16x32_bf16 v[82:85], v[168:171], v[204:207], v[82:85]
	s_barrier
; #define PG8_STAGE(bufoff, gbase, voff) do { _Pragma("unroll") for (int _i = 0; _i < 2; ++_i) \
;         __builtin_amdgcn_global_load_lds((const unsigned*)((const char*)(gbase) + (voff)[_i]), (LAS unsigned*)(lds + (bufoff) + ldsw + _i * 8192), 16, 0, 0); } while (0)
; #define PG8_LDA(dst, b, h) do { _Pragma("unroll") for (int m = 0; m < 4; ++m) _Pragma("unroll") for (int k = 0; k < 2; ++k) dst[m][k] = *(const LAS bf16x8*)(lds + PG8_SA(b, h) + aoff + m * 2048 + k * 1024); } while (0)
; #define PG8_MMA(ai, bj, At, Bt) do { __builtin_amdgcn_s_setprio(1); _Pragma("unroll") for (int m = 0; m < 4; ++m) _Pragma("unroll") for (int n = 0; n < 2; ++n) _Pragma("unroll") for (int k = 0; k < 2; ++k) \
;         acc[ai][bj][m][n] = __builtin_amdgcn_mfma_f32_16x16x32_bf16(Bt[n][k], At[m][k], acc[ai][bj][m][n], 0, 0, 0); __builtin_amdgcn_s_setprio(0); } while (0)
; #define PG8_WAIT_V(n) asm volatile("s_waitcnt vmcnt(" #n ")" ::: "memory")
; #define PG8_WAIT_L(n) asm volatile("s_waitcnt lgkmcnt(" #n ")" ::: "memory")
; #define PG8_BAR __builtin_amdgcn_s_barrier()
; #define PG8_SCHED __builtin_amdgcn_sched_barrier(0)
; template <class Epi, class Sched, int LDA, int LDB, bool ALIGN_EPI = true>
; __device__ __forceinline__ void gemm_phase(LAS unsigned char* lds, const Gemm g, const Sched& S, const Epi& E, int wave) {
;     ...
;             PG8_LDA(At, 1, 1); PG8_STAGE(PG8_SB(1, 0), b3, voffB); PG8_STAGE(PG8_SB(1, 1), b3 + hstepB, voffB); PG8_STAGE(PG8_SA(1, 0), a3, voffA);
;             PG8_WAIT_V(8); PG8_WAIT_L(0); PG8_BAR; PG8_MMA(1, 0, At, B0); PG8_MMA(1, 1, At, B1); PG8_BAR; PG8_SCHED;
;         }
	s_setprio 0
	ds_read_b128 v[172:175], v215 offset:49152
	ds_read_b128 v[180:183], v215 offset:50176
	ds_read_b128 v[184:187], v215 offset:51200
	ds_read_b128 v[188:191], v215 offset:52224
	ds_read_b128 v[192:195], v215 offset:53248
	ds_read_b128 v[196:199], v215 offset:54272
	ds_read_b128 v[200:203], v215 offset:55296
	ds_read_b128 v[204:207], v215 offset:56320
	s_add_i32 s38, s66, s60
	v_lshl_add_u64 v[208:209], v[208:209], 0, s[70:71]
	s_mov_b32 m0, s38
	s_nop 0
	global_load_lds_dwordx4 v[208:209], off
	s_add_i32 m0, s38, 0x2000
	s_add_u32 s36, s36, 0x80080
	v_lshl_add_u64 v[208:209], v[210:211], 0, s[70:71]
	s_addc_u32 s37, s37, 0
	s_add_i32 s38, s67, s60
	global_load_lds_dwordx4 v[208:209], off
	v_lshl_add_u64 v[208:209], s[36:37], 0, v[0:1]
	s_mov_b32 m0, s38
	s_nop 0
	global_load_lds_dwordx4 v[208:209], off
	v_lshl_add_u64 v[208:209], s[36:37], 0, v[150:151]
	s_add_i32 m0, s38, 0x2000
	s_nop 0
	global_load_lds_dwordx4 v[208:209], off
	v_lshl_add_u64 v[208:209], v[216:217], 0, s[70:71]
	s_mov_b32 m0, s51
	s_nop 0
	global_load_lds_dwordx4 v[208:209], off
	v_lshl_add_u64 v[208:209], v[218:219], 0, s[70:71]
	s_mov_b32 m0, s52
	s_nop 0
	global_load_lds_dwordx4 v[208:209], off
	s_waitcnt vmcnt(8)
	s_waitcnt lgkmcnt(0)
	s_setprio 1
	s_barrier
	v_mfma_f32_16x16x32_bf16 v[78:81], v[58:61], v[172:175], v[78:81]
	v_mfma_f32_16x16x32_bf16 v[74:77], v[66:69], v[172:175], v[74:77]
	v_mfma_f32_16x16x32_bf16 v[46:49], v[58:61], v[184:187], v[46:49]
	v_mfma_f32_16x16x32_bf16 v[42:45], v[66:69], v[184:187], v[42:45]
	v_mfma_f32_16x16x32_bf16 v[30:33], v[58:61], v[192:195], v[30:33]
	v_mfma_f32_16x16x32_bf16 v[26:29], v[66:69], v[192:195], v[26:29]
	v_mfma_f32_16x16x32_bf16 v[14:17], v[58:61], v[200:203], v[14:17]
	v_mfma_f32_16x16x32_bf16 v[10:13], v[66:69], v[200:203], v[10:13]
	v_mfma_f32_16x16x32_bf16 v[78:81], v[62:65], v[180:183], v[78:81]
	v_mfma_f32_16x16x32_bf16 v[74:77], v[70:73], v[180:183], v[74:77]
	v_mfma_f32_16x16x32_bf16 v[46:49], v[62:65], v[188:191], v[46:49]
	v_mfma_f32_16x16x32_bf16 v[42:45], v[70:73], v[188:191], v[42:45]
	v_mfma_f32_16x16x32_bf16 v[30:33], v[62:65], v[196:199], v[30:33]
	v_mfma_f32_16x16x32_bf16 v[26:29], v[70:73], v[196:199], v[26:29]
	v_mfma_f32_16x16x32_bf16 v[14:17], v[62:65], v[204:207], v[14:17]
	v_mfma_f32_16x16x32_bf16 v[10:13], v[70:73], v[204:207], v[10:13]
	v_mfma_f32_16x16x32_bf16 v[50:53], v[156:159], v[172:175], v[50:53]
	v_mfma_f32_16x16x32_bf16 v[62:65], v[160:163], v[180:183], v[50:53]
	v_mfma_f32_16x16x32_bf16 v[50:53], v[164:167], v[172:175], v[54:57]
	v_mfma_f32_16x16x32_bf16 v[38:41], v[156:159], v[184:187], v[38:41]
	v_mfma_f32_16x16x32_bf16 v[34:37], v[164:167], v[184:187], v[34:37]
	v_mfma_f32_16x16x32_bf16 v[22:25], v[156:159], v[192:195], v[22:25]
	v_mfma_f32_16x16x32_bf16 v[18:21], v[164:167], v[192:195], v[18:21]
	v_mfma_f32_16x16x32_bf16 v[6:9], v[156:159], v[200:203], v[6:9]
	v_mfma_f32_16x16x32_bf16 v[2:5], v[164:167], v[200:203], v[2:5]
	v_mfma_f32_16x16x32_bf16 v[58:61], v[168:171], v[180:183], v[50:53]
	v_mfma_f32_16x16x32_bf16 v[38:41], v[160:163], v[188:191], v[38:41]
	v_mfma_f32_16x16x32_bf16 v[34:37], v[168:171], v[188:191], v[34:37]
	v_mfma_f32_16x16x32_bf16 v[22:25], v[160:163], v[196:199], v[22:25]
	v_mfma_f32_16x16x32_bf16 v[18:21], v[168:171], v[196:199], v[18:21]
	v_mfma_f32_16x16x32_bf16 v[6:9], v[160:163], v[204:207], v[6:9]
	v_mfma_f32_16x16x32_bf16 v[2:5], v[168:171], v[204:207], v[2:5]
	s_barrier
	s_setprio 0
	s_add_u32 s34, s34, 0x100
	s_addc_u32 s35, s35, 0
	s_add_u32 s59, s59, 0x100
	s_addc_u32 s64, s64, 0
	s_cmp_ge_i32 s65, s43
	s_mov_b32 s36, s65
	s_cbranch_scc0 .LBB0_4901
	v_readlane_b32 s34, v252, 14
	v_readlane_b32 s35, v252, 15
	s_and_b64 vcc, exec, s[34:35]
	s_cbranch_vccz .LBB0_4904
	s_barrier
